# back-edge rotation (asm guide 7.11) on the 9 GEMM main loops: head SALU/address block computed before the loop-back barrier
# speedup vs baseline: 1.0376x; 1.0002x over previous
; template <class Epi, class Ord>
; __device__ __forceinline__ void gemm_phase(LAS unsigned char* lds, const Gemm g, const Ord& S, const Epi& E) {
;     ...
;         for (int t = 0; t < nt; t += 2) {
;             const bool last = (t == nt - 2);
;             const char* a1 = cA + (size_t)(t + 1) * kstep;
;             const char* a2 = last ? nA : cA + (size_t)(t + 2) * kstep; const char* b2 = last ? nB : cB + (size_t)(t + 2) * kstep;
;             const char* a3 = a2 + kstep; const char* b3 = b2 + kstep;
;     ...
; #pragma unroll
;         for (int a = 0; a < 2; ++a)
; #pragma unroll
;             for (int b = 0; b < 2; ++b)
; #pragma unroll
;                 for (int m = 0; m < 4; ++m)
; #pragma unroll
;                     for (int n = 0; n < 2; ++n) acc[a][b][m][n] = (f32x4){0.f, 0.f, 0.f, 0.f};
.LBB0_165:
	v_mov_b32_e32 v123, 0
	v_mov_b32_e32 v122, 0
	s_andn2_b64 vcc, exec, s[18:19]
	v_pk_mov_b32 v[120:121], v[122:123], v[122:123]
	v_pk_mov_b32 v[126:127], v[122:123], v[122:123]
	v_pk_mov_b32 v[124:125], v[122:123], v[122:123]
	v_pk_mov_b32 v[110:111], v[122:123], v[122:123]
	v_pk_mov_b32 v[108:109], v[122:123], v[122:123]
	v_pk_mov_b32 v[106:107], v[122:123], v[122:123]
	v_pk_mov_b32 v[104:105], v[122:123], v[122:123]
	v_pk_mov_b32 v[94:95], v[122:123], v[122:123]
	v_pk_mov_b32 v[92:93], v[122:123], v[122:123]
	v_pk_mov_b32 v[90:91], v[122:123], v[122:123]
	v_pk_mov_b32 v[88:89], v[122:123], v[122:123]
	v_pk_mov_b32 v[78:79], v[122:123], v[122:123]
	v_pk_mov_b32 v[76:77], v[122:123], v[122:123]
	v_pk_mov_b32 v[74:75], v[122:123], v[122:123]
	v_pk_mov_b32 v[72:73], v[122:123], v[122:123]
	v_pk_mov_b32 v[118:119], v[122:123], v[122:123]
	v_pk_mov_b32 v[116:117], v[122:123], v[122:123]
	v_pk_mov_b32 v[114:115], v[122:123], v[122:123]
	v_pk_mov_b32 v[112:113], v[122:123], v[122:123]
	v_pk_mov_b32 v[102:103], v[122:123], v[122:123]
	v_pk_mov_b32 v[100:101], v[122:123], v[122:123]
	v_pk_mov_b32 v[98:99], v[122:123], v[122:123]
	v_pk_mov_b32 v[96:97], v[122:123], v[122:123]
	v_pk_mov_b32 v[86:87], v[122:123], v[122:123]
	v_pk_mov_b32 v[84:85], v[122:123], v[122:123]
	v_pk_mov_b32 v[82:83], v[122:123], v[122:123]
	v_pk_mov_b32 v[80:81], v[122:123], v[122:123]
	v_pk_mov_b32 v[70:71], v[122:123], v[122:123]
	v_pk_mov_b32 v[68:69], v[122:123], v[122:123]
	v_pk_mov_b32 v[66:67], v[122:123], v[122:123]
	v_pk_mov_b32 v[64:65], v[122:123], v[122:123]
	v_pk_mov_b32 v[62:63], v[122:123], v[122:123]
	v_pk_mov_b32 v[60:61], v[122:123], v[122:123]
	v_pk_mov_b32 v[58:59], v[122:123], v[122:123]
	v_pk_mov_b32 v[56:57], v[122:123], v[122:123]
	v_pk_mov_b32 v[46:47], v[122:123], v[122:123]
	v_pk_mov_b32 v[44:45], v[122:123], v[122:123]
	v_pk_mov_b32 v[42:43], v[122:123], v[122:123]
	v_pk_mov_b32 v[40:41], v[122:123], v[122:123]
	v_pk_mov_b32 v[30:31], v[122:123], v[122:123]
	v_pk_mov_b32 v[28:29], v[122:123], v[122:123]
	v_pk_mov_b32 v[26:27], v[122:123], v[122:123]
	v_pk_mov_b32 v[24:25], v[122:123], v[122:123]
	v_pk_mov_b32 v[14:15], v[122:123], v[122:123]
	v_pk_mov_b32 v[12:13], v[122:123], v[122:123]
	v_pk_mov_b32 v[10:11], v[122:123], v[122:123]
	v_pk_mov_b32 v[8:9], v[122:123], v[122:123]
	v_pk_mov_b32 v[54:55], v[122:123], v[122:123]
	v_pk_mov_b32 v[52:53], v[122:123], v[122:123]
	v_pk_mov_b32 v[50:51], v[122:123], v[122:123]
	v_pk_mov_b32 v[48:49], v[122:123], v[122:123]
	v_pk_mov_b32 v[38:39], v[122:123], v[122:123]
	v_pk_mov_b32 v[36:37], v[122:123], v[122:123]
	v_pk_mov_b32 v[34:35], v[122:123], v[122:123]
	v_pk_mov_b32 v[32:33], v[122:123], v[122:123]
	v_pk_mov_b32 v[22:23], v[122:123], v[122:123]
	v_pk_mov_b32 v[20:21], v[122:123], v[122:123]
	v_pk_mov_b32 v[18:19], v[122:123], v[122:123]
	v_pk_mov_b32 v[16:17], v[122:123], v[122:123]
	v_pk_mov_b32 v[6:7], v[122:123], v[122:123]
	v_pk_mov_b32 v[4:5], v[122:123], v[122:123]
	v_pk_mov_b32 v[2:3], v[122:123], v[122:123]
	v_pk_mov_b32 v[0:1], v[122:123], v[122:123]
	s_cbranch_vccnz .LBB0_154
	s_add_u32 s46, s46, 0x100
	s_addc_u32 s47, s47, 0
	s_add_u32 s52, s52, 0x100
	v_mov_b32_e32 v0, 0
	v_mov_b32_e32 v1, 0
	s_addc_u32 s53, s53, 0
	s_mov_b32 s12, 0
	v_pk_mov_b32 v[2:3], v[0:1], v[0:1]
	v_pk_mov_b32 v[4:5], v[0:1], v[0:1]
	v_pk_mov_b32 v[6:7], v[0:1], v[0:1]
	v_pk_mov_b32 v[16:17], v[0:1], v[0:1]
	v_pk_mov_b32 v[18:19], v[0:1], v[0:1]
	v_pk_mov_b32 v[20:21], v[0:1], v[0:1]
	v_pk_mov_b32 v[22:23], v[0:1], v[0:1]
	v_pk_mov_b32 v[32:33], v[0:1], v[0:1]
	v_pk_mov_b32 v[34:35], v[0:1], v[0:1]
	v_pk_mov_b32 v[36:37], v[0:1], v[0:1]
	v_pk_mov_b32 v[38:39], v[0:1], v[0:1]
	v_pk_mov_b32 v[48:49], v[0:1], v[0:1]
	v_pk_mov_b32 v[50:51], v[0:1], v[0:1]
	v_pk_mov_b32 v[52:53], v[0:1], v[0:1]
	v_pk_mov_b32 v[54:55], v[0:1], v[0:1]
	v_pk_mov_b32 v[8:9], v[0:1], v[0:1]
	v_pk_mov_b32 v[10:11], v[0:1], v[0:1]
	v_pk_mov_b32 v[12:13], v[0:1], v[0:1]
	v_pk_mov_b32 v[14:15], v[0:1], v[0:1]
	v_pk_mov_b32 v[24:25], v[0:1], v[0:1]
	v_pk_mov_b32 v[26:27], v[0:1], v[0:1]
	v_pk_mov_b32 v[28:29], v[0:1], v[0:1]
	v_pk_mov_b32 v[30:31], v[0:1], v[0:1]
	v_pk_mov_b32 v[40:41], v[0:1], v[0:1]
	v_pk_mov_b32 v[42:43], v[0:1], v[0:1]
	v_pk_mov_b32 v[44:45], v[0:1], v[0:1]
	v_pk_mov_b32 v[46:47], v[0:1], v[0:1]
	v_pk_mov_b32 v[56:57], v[0:1], v[0:1]
	v_pk_mov_b32 v[58:59], v[0:1], v[0:1]
	v_pk_mov_b32 v[60:61], v[0:1], v[0:1]
	v_pk_mov_b32 v[62:63], v[0:1], v[0:1]
	v_pk_mov_b32 v[64:65], v[0:1], v[0:1]
	v_pk_mov_b32 v[66:67], v[0:1], v[0:1]
	v_pk_mov_b32 v[68:69], v[0:1], v[0:1]
	v_pk_mov_b32 v[70:71], v[0:1], v[0:1]
	v_pk_mov_b32 v[80:81], v[0:1], v[0:1]
	v_pk_mov_b32 v[82:83], v[0:1], v[0:1]
	v_pk_mov_b32 v[84:85], v[0:1], v[0:1]
	v_pk_mov_b32 v[86:87], v[0:1], v[0:1]
	v_pk_mov_b32 v[96:97], v[0:1], v[0:1]
	v_pk_mov_b32 v[98:99], v[0:1], v[0:1]
	v_pk_mov_b32 v[100:101], v[0:1], v[0:1]
	v_pk_mov_b32 v[102:103], v[0:1], v[0:1]
	v_pk_mov_b32 v[112:113], v[0:1], v[0:1]
	v_pk_mov_b32 v[114:115], v[0:1], v[0:1]
	v_pk_mov_b32 v[116:117], v[0:1], v[0:1]
	v_pk_mov_b32 v[118:119], v[0:1], v[0:1]
	v_pk_mov_b32 v[72:73], v[0:1], v[0:1]
	v_pk_mov_b32 v[74:75], v[0:1], v[0:1]
	v_pk_mov_b32 v[76:77], v[0:1], v[0:1]
	v_pk_mov_b32 v[78:79], v[0:1], v[0:1]
	v_pk_mov_b32 v[88:89], v[0:1], v[0:1]
	v_pk_mov_b32 v[90:91], v[0:1], v[0:1]
	v_pk_mov_b32 v[92:93], v[0:1], v[0:1]
	v_pk_mov_b32 v[94:95], v[0:1], v[0:1]
	v_pk_mov_b32 v[104:105], v[0:1], v[0:1]
	v_pk_mov_b32 v[106:107], v[0:1], v[0:1]
	v_pk_mov_b32 v[108:109], v[0:1], v[0:1]
	v_pk_mov_b32 v[110:111], v[0:1], v[0:1]
	v_pk_mov_b32 v[124:125], v[0:1], v[0:1]
	v_pk_mov_b32 v[126:127], v[0:1], v[0:1]
	v_pk_mov_b32 v[120:121], v[0:1], v[0:1]
	v_pk_mov_b32 v[122:123], v[0:1], v[0:1]
	s_add_i32 s79, s12, 2
	s_cmp_eq_u32 s73, s12
	s_cselect_b32 s22, s0, s52
	s_cselect_b32 s23, s1, s53
	s_cselect_b32 s20, s44, s46
	s_cselect_b32 s21, s45, s47
	s_add_u32 s12, s22, 0x80
	s_addc_u32 s13, s23, 0
	s_add_i32 s80, 0, 0x10000
	v_add_u32_e32 v135, s80, v133
; #define PG8_STAGE(bufoff, gbase, voff) do { const char* _gb = (const char*)(gbase); asm volatile("" : "+s"(_gb)); _Pragma("unroll") for (int _i = 0; _i < 2; ++_i) { unsigned _vo = (voff)[_i]; asm volatile("" : "+v"(_vo)); \
;         __builtin_amdgcn_global_load_lds((const GAS unsigned*)(_gb + _vo), (LAS unsigned*)(lds + (bufoff) + ldsw + _i * 8192), 16, 0, 0); } } while (0)
; #define PG8_LDA(dst, b, h) do { _Pragma("unroll") for (int m = 0; m < 4; ++m) _Pragma("unroll") for (int k = 0; k < 2; ++k) dst[m][k] = *(const LAS bf16x8*)(lds + PG8_SA(b, h) + aoff + m * 2048 + k * 1024); } while (0)
; #define PG8_LDB(dst, b, h) do { _Pragma("unroll") for (int n = 0; n < 2; ++n) _Pragma("unroll") for (int k = 0; k < 2; ++k) dst[n][k] = *(const LAS bf16x8*)(lds + PG8_SB(b, h) + boff + n * 2048 + k * 1024); } while (0)
; #define PG8_MMA(ai, bj, At, Bt) do { __builtin_amdgcn_s_setprio(1); _Pragma("unroll") for (int m = 0; m < 4; ++m) _Pragma("unroll") for (int n = 0; n < 2; ++n) _Pragma("unroll") for (int k = 0; k < 2; ++k) \
;         acc[ai][bj][m][n] = __builtin_amdgcn_mfma_f32_16x16x32_bf16(Bt[n][k], At[m][k], acc[ai][bj][m][n], 0, 0, 0); __builtin_amdgcn_s_setprio(0); } while (0)
; #define PG8_WAIT_L(n) asm volatile("s_waitcnt lgkmcnt(" #n ")" ::: "memory")
; #define PG8_BAR __builtin_amdgcn_s_barrier()
; #define PG8_SCHED __builtin_amdgcn_sched_barrier(0)
; template <class Epi, class Ord>
; __device__ __forceinline__ void gemm_phase(LAS unsigned char* lds, const Gemm g, const Ord& S, const Epi& E) {
;     ...
;             PG8_LDB(B0, 0, 0); PG8_SCHED; PG8_LDA(At, 0, 0); PG8_STAGE(PG8_SA(1, 1), a1 + hstep, voffA);
;             PG8_WAIT_L(8); PG8_BAR; PG8_WAIT_L(0); PG8_MMA(0, 0, At, B0); PG8_BAR; PG8_SCHED;
;             PG8_LDB(B1, 0, 1); PG8_STAGE(PG8_SB(0, 0), b2, voffB);
;             PG8_BAR; PG8_WAIT_L(0); PG8_MMA(0, 1, At, B1); PG8_BAR;
;             PG8_LDA(At, 0, 1); PG8_STAGE(PG8_SA(0, 0), a2, voffA);
;             PG8_BAR; PG8_WAIT_L(0); PG8_MMA(1, 0, At, B0); PG8_BAR; PG8_SCHED;
.LBB0_167:
	ds_read_b128 v[136:139], v135
	ds_read_b128 v[140:143], v135 offset:1024
	ds_read_b128 v[144:147], v135 offset:2048
	ds_read_b128 v[148:151], v135 offset:3072
	s_add_u32 s24, s52, s10
	s_addc_u32 s25, s53, s11
	s_add_u32 s24, s24, 0xffffff80
	s_addc_u32 s25, s25, -1
	v_mov_b32_e32 v135, v128
	ds_read_b128 v[152:155], v134
	ds_read_b128 v[156:159], v134 offset:1024
	ds_read_b128 v[192:195], v134 offset:2048
	ds_read_b128 v[196:199], v134 offset:3072
	ds_read_b128 v[200:203], v134 offset:4096
	ds_read_b128 v[204:207], v134 offset:5120
	ds_read_b128 v[212:215], v134 offset:6144
	ds_read_b128 v[216:219], v134 offset:7168
	s_add_i32 m0, s65, 0xc000
	s_nop 0
	global_load_lds_dwordx4 v135, s[24:25]
	v_mov_b32_e32 v135, v130
	s_add_i32 m0, s65, 0xe000
	s_nop 0
	global_load_lds_dwordx4 v135, s[24:25]
	s_waitcnt lgkmcnt(8)
	s_barrier
	s_waitcnt lgkmcnt(0)
	s_setprio 1
	s_waitcnt lgkmcnt(0)
	v_mfma_f32_16x16x32_bf16 v[120:123], v[136:139], v[152:155], v[120:123]
	v_mfma_f32_16x16x32_bf16 v[124:127], v[144:147], v[152:155], v[124:127]
	v_mfma_f32_16x16x32_bf16 v[108:111], v[136:139], v[192:195], v[108:111]
	v_mfma_f32_16x16x32_bf16 v[104:107], v[144:147], v[192:195], v[104:107]
	v_mfma_f32_16x16x32_bf16 v[92:95], v[136:139], v[200:203], v[92:95]
	v_mfma_f32_16x16x32_bf16 v[88:91], v[144:147], v[200:203], v[88:91]
	v_mfma_f32_16x16x32_bf16 v[76:79], v[136:139], v[212:215], v[76:79]
	v_mfma_f32_16x16x32_bf16 v[72:75], v[144:147], v[212:215], v[72:75]
	v_mfma_f32_16x16x32_bf16 v[120:123], v[140:143], v[156:159], v[120:123]
	v_mfma_f32_16x16x32_bf16 v[124:127], v[148:151], v[156:159], v[124:127]
	v_mfma_f32_16x16x32_bf16 v[108:111], v[140:143], v[196:199], v[108:111]
	v_mfma_f32_16x16x32_bf16 v[104:107], v[148:151], v[196:199], v[104:107]
	v_mfma_f32_16x16x32_bf16 v[92:95], v[140:143], v[204:207], v[92:95]
	v_mfma_f32_16x16x32_bf16 v[88:91], v[148:151], v[204:207], v[88:91]
	v_mfma_f32_16x16x32_bf16 v[76:79], v[140:143], v[216:219], v[76:79]
	v_mfma_f32_16x16x32_bf16 v[72:75], v[148:151], v[216:219], v[72:75]
	s_setprio 0
	s_barrier
	s_add_i32 s82, 0, 0x14000
	v_add_u32_e32 v135, s82, v133
	ds_read_b128 v[220:223], v135
	ds_read_b128 v[224:227], v135 offset:1024
	ds_read_b128 v[228:231], v135 offset:2048
	ds_read_b128 v[232:235], v135 offset:3072
	s_mov_b64 s[24:25], s[20:21]
	v_mov_b32_e32 v135, v129
	s_add_i32 s80, s80, s64
	s_mov_b32 m0, s80
	s_nop 0
	global_load_lds_dwordx4 v135, s[24:25]
	v_mov_b32_e32 v135, v131
	s_add_i32 m0, s80, 0x2000
	s_nop 0
	global_load_lds_dwordx4 v135, s[24:25]
	s_barrier
	s_waitcnt lgkmcnt(0)
	s_setprio 1
	s_waitcnt lgkmcnt(0)
	v_mfma_f32_16x16x32_bf16 v[116:119], v[220:223], v[152:155], v[116:119]
	v_mfma_f32_16x16x32_bf16 v[112:115], v[228:231], v[152:155], v[112:115]
	v_mfma_f32_16x16x32_bf16 v[100:103], v[220:223], v[192:195], v[100:103]
	v_mfma_f32_16x16x32_bf16 v[96:99], v[228:231], v[192:195], v[96:99]
	v_mfma_f32_16x16x32_bf16 v[84:87], v[220:223], v[200:203], v[84:87]
	v_mfma_f32_16x16x32_bf16 v[80:83], v[228:231], v[200:203], v[80:83]
	v_mfma_f32_16x16x32_bf16 v[68:71], v[220:223], v[212:215], v[68:71]
	v_mfma_f32_16x16x32_bf16 v[64:67], v[228:231], v[212:215], v[64:67]
	v_mfma_f32_16x16x32_bf16 v[116:119], v[224:227], v[156:159], v[116:119]
	v_mfma_f32_16x16x32_bf16 v[112:115], v[232:235], v[156:159], v[112:115]
	v_mfma_f32_16x16x32_bf16 v[100:103], v[224:227], v[196:199], v[100:103]
	v_mfma_f32_16x16x32_bf16 v[96:99], v[232:235], v[196:199], v[96:99]
	v_mfma_f32_16x16x32_bf16 v[84:87], v[224:227], v[204:207], v[84:87]
	v_mfma_f32_16x16x32_bf16 v[80:83], v[232:235], v[204:207], v[80:83]
	v_mfma_f32_16x16x32_bf16 v[68:71], v[224:227], v[216:219], v[68:71]
	v_mfma_f32_16x16x32_bf16 v[64:67], v[232:235], v[216:219], v[64:67]
	s_setprio 0
	s_mov_b64 s[24:25], s[22:23]
	v_mov_b32_e32 v135, v128
	s_mov_b32 m0, s65
	s_barrier
	ds_read_b128 v[152:155], v134 offset:16384
	ds_read_b128 v[156:159], v134 offset:17408
	ds_read_b128 v[192:195], v134 offset:18432
	ds_read_b128 v[196:199], v134 offset:19456
	ds_read_b128 v[200:203], v134 offset:20480
	ds_read_b128 v[204:207], v134 offset:21504
	ds_read_b128 v[212:215], v134 offset:22528
	ds_read_b128 v[216:219], v134 offset:23552
	s_nop 0
	global_load_lds_dwordx4 v135, s[24:25]
	v_mov_b32_e32 v135, v130
	s_mov_b32 m0, s66
	s_nop 0
	global_load_lds_dwordx4 v135, s[24:25]
	s_barrier
	s_waitcnt lgkmcnt(0)
	s_setprio 1
	s_waitcnt lgkmcnt(0)
	v_mfma_f32_16x16x32_bf16 v[60:63], v[136:139], v[152:155], v[60:63]
	v_mfma_f32_16x16x32_bf16 v[56:59], v[144:147], v[152:155], v[56:59]
	v_mfma_f32_16x16x32_bf16 v[44:47], v[136:139], v[192:195], v[44:47]
	v_mfma_f32_16x16x32_bf16 v[40:43], v[144:147], v[192:195], v[40:43]
	v_mfma_f32_16x16x32_bf16 v[28:31], v[136:139], v[200:203], v[28:31]
	v_mfma_f32_16x16x32_bf16 v[24:27], v[144:147], v[200:203], v[24:27]
	v_mfma_f32_16x16x32_bf16 v[12:15], v[136:139], v[212:215], v[12:15]
	v_mfma_f32_16x16x32_bf16 v[8:11], v[144:147], v[212:215], v[8:11]
	v_mfma_f32_16x16x32_bf16 v[60:63], v[140:143], v[156:159], v[60:63]
	v_mfma_f32_16x16x32_bf16 v[56:59], v[148:151], v[156:159], v[56:59]
	v_mfma_f32_16x16x32_bf16 v[44:47], v[140:143], v[196:199], v[44:47]
	v_mfma_f32_16x16x32_bf16 v[40:43], v[148:151], v[196:199], v[40:43]
	v_mfma_f32_16x16x32_bf16 v[28:31], v[140:143], v[204:207], v[28:31]
	v_mfma_f32_16x16x32_bf16 v[24:27], v[148:151], v[204:207], v[24:27]
	v_mfma_f32_16x16x32_bf16 v[12:15], v[140:143], v[216:219], v[12:15]
	v_mfma_f32_16x16x32_bf16 v[8:11], v[148:151], v[216:219], v[8:11]
	s_setprio 0
	s_barrier
; #define PG8_STAGE(bufoff, gbase, voff) do { const char* _gb = (const char*)(gbase); asm volatile("" : "+s"(_gb)); _Pragma("unroll") for (int _i = 0; _i < 2; ++_i) { unsigned _vo = (voff)[_i]; asm volatile("" : "+v"(_vo)); \
;         __builtin_amdgcn_global_load_lds((const GAS unsigned*)(_gb + _vo), (LAS unsigned*)(lds + (bufoff) + ldsw + _i * 8192), 16, 0, 0); } } while (0)
; #define PG8_LDA(dst, b, h) do { _Pragma("unroll") for (int m = 0; m < 4; ++m) _Pragma("unroll") for (int k = 0; k < 2; ++k) dst[m][k] = *(const LAS bf16x8*)(lds + PG8_SA(b, h) + aoff + m * 2048 + k * 1024); } while (0)
; #define PG8_LDB(dst, b, h) do { _Pragma("unroll") for (int n = 0; n < 2; ++n) _Pragma("unroll") for (int k = 0; k < 2; ++k) dst[n][k] = *(const LAS bf16x8*)(lds + PG8_SB(b, h) + boff + n * 2048 + k * 1024); } while (0)
; #define PG8_MMA(ai, bj, At, Bt) do { __builtin_amdgcn_s_setprio(1); _Pragma("unroll") for (int m = 0; m < 4; ++m) _Pragma("unroll") for (int n = 0; n < 2; ++n) _Pragma("unroll") for (int k = 0; k < 2; ++k) \
;         acc[ai][bj][m][n] = __builtin_amdgcn_mfma_f32_16x16x32_bf16(Bt[n][k], At[m][k], acc[ai][bj][m][n], 0, 0, 0); __builtin_amdgcn_s_setprio(0); } while (0)
; #define PG8_WAIT_V(n) asm volatile("s_waitcnt vmcnt(" #n ")" ::: "memory")
; #define PG8_WAIT_L(n) asm volatile("s_waitcnt lgkmcnt(" #n ")" ::: "memory")
; #define PG8_BAR __builtin_amdgcn_s_barrier()
; #define PG8_SCHED __builtin_amdgcn_sched_barrier(0)
; template <class Epi, class Ord>
; __device__ __forceinline__ void gemm_phase(LAS unsigned char* lds, const Gemm g, const Ord& S, const Epi& E) {
;     ...
;             PG8_STAGE(PG8_SB(0, 1), b2 + hstep, voffB);
;             PG8_WAIT_V(6); PG8_BAR; PG8_MMA(1, 1, At, B1); PG8_BAR;
;             PG8_LDB(B0, 1, 0); PG8_SCHED; PG8_LDA(At, 1, 0); PG8_STAGE(PG8_SA(0, 1), a2 + hstep, voffA);
;             PG8_WAIT_L(8); PG8_BAR; PG8_WAIT_L(0); PG8_MMA(0, 0, At, B0); PG8_BAR; PG8_SCHED;
;             PG8_LDB(B1, 1, 1); PG8_STAGE(PG8_SB(1, 0), b3, voffB);
	s_add_u32 s24, s20, s10
	s_addc_u32 s25, s21, s11
	s_mov_b64 s[80:81], s[24:25]
	v_mov_b32_e32 v135, v129
	s_add_i32 s82, s82, s64
	s_mov_b32 m0, s82
	s_nop 0
	global_load_lds_dwordx4 v135, s[80:81]
	v_mov_b32_e32 v135, v131
	s_add_i32 m0, s82, 0x2000
	s_nop 0
	global_load_lds_dwordx4 v135, s[80:81]
	s_waitcnt vmcnt(6)
	s_barrier
	s_setprio 1
	v_mfma_f32_16x16x32_bf16 v[52:55], v[220:223], v[152:155], v[52:55]
	v_mfma_f32_16x16x32_bf16 v[48:51], v[228:231], v[152:155], v[48:51]
	v_mfma_f32_16x16x32_bf16 v[36:39], v[220:223], v[192:195], v[36:39]
	v_mfma_f32_16x16x32_bf16 v[32:35], v[228:231], v[192:195], v[32:35]
	v_mfma_f32_16x16x32_bf16 v[20:23], v[220:223], v[200:203], v[20:23]
	v_mfma_f32_16x16x32_bf16 v[16:19], v[228:231], v[200:203], v[16:19]
	v_mfma_f32_16x16x32_bf16 v[4:7], v[220:223], v[212:215], v[4:7]
	v_mfma_f32_16x16x32_bf16 v[0:3], v[228:231], v[212:215], v[0:3]
	v_mfma_f32_16x16x32_bf16 v[52:55], v[224:227], v[156:159], v[52:55]
	v_mfma_f32_16x16x32_bf16 v[48:51], v[232:235], v[156:159], v[48:51]
	v_mfma_f32_16x16x32_bf16 v[36:39], v[224:227], v[196:199], v[36:39]
	v_mfma_f32_16x16x32_bf16 v[32:35], v[232:235], v[196:199], v[32:35]
	v_mfma_f32_16x16x32_bf16 v[20:23], v[224:227], v[204:207], v[20:23]
	v_mfma_f32_16x16x32_bf16 v[16:19], v[232:235], v[204:207], v[16:19]
	v_mfma_f32_16x16x32_bf16 v[4:7], v[224:227], v[216:219], v[4:7]
	v_mfma_f32_16x16x32_bf16 v[0:3], v[232:235], v[216:219], v[0:3]
	s_setprio 0
	s_add_i32 s80, 0, 0x18000
	v_add_u32_e32 v135, s80, v133
	s_barrier
	ds_read_b128 v[136:139], v135
	ds_read_b128 v[140:143], v135 offset:1024
	ds_read_b128 v[144:147], v135 offset:2048
	ds_read_b128 v[148:151], v135 offset:3072
	s_add_u32 s22, s22, s10
	s_addc_u32 s23, s23, s11
	v_mov_b32_e32 v135, v128
	s_mov_b32 m0, s67
	ds_read_b128 v[152:155], v134 offset:32768
	ds_read_b128 v[156:159], v134 offset:33792
	ds_read_b128 v[192:195], v134 offset:34816
	ds_read_b128 v[196:199], v134 offset:35840
	ds_read_b128 v[200:203], v134 offset:36864
	ds_read_b128 v[204:207], v134 offset:37888
	ds_read_b128 v[212:215], v134 offset:38912
	ds_read_b128 v[216:219], v134 offset:39936
	s_nop 0
	global_load_lds_dwordx4 v135, s[22:23]
	v_mov_b32_e32 v135, v130
	s_mov_b32 m0, s68
	s_nop 0
	global_load_lds_dwordx4 v135, s[22:23]
	s_waitcnt lgkmcnt(8)
	s_barrier
	s_waitcnt lgkmcnt(0)
	s_setprio 1
	s_waitcnt lgkmcnt(0)
	v_mfma_f32_16x16x32_bf16 v[120:123], v[136:139], v[152:155], v[120:123]
	v_mfma_f32_16x16x32_bf16 v[124:127], v[144:147], v[152:155], v[124:127]
	v_mfma_f32_16x16x32_bf16 v[108:111], v[136:139], v[192:195], v[108:111]
	v_mfma_f32_16x16x32_bf16 v[104:107], v[144:147], v[192:195], v[104:107]
	v_mfma_f32_16x16x32_bf16 v[92:95], v[136:139], v[200:203], v[92:95]
	v_mfma_f32_16x16x32_bf16 v[88:91], v[144:147], v[200:203], v[88:91]
	v_mfma_f32_16x16x32_bf16 v[76:79], v[136:139], v[212:215], v[76:79]
	v_mfma_f32_16x16x32_bf16 v[72:75], v[144:147], v[212:215], v[72:75]
	v_mfma_f32_16x16x32_bf16 v[120:123], v[140:143], v[156:159], v[120:123]
	v_mfma_f32_16x16x32_bf16 v[124:127], v[148:151], v[156:159], v[124:127]
	v_mfma_f32_16x16x32_bf16 v[108:111], v[140:143], v[196:199], v[108:111]
	v_mfma_f32_16x16x32_bf16 v[104:107], v[148:151], v[196:199], v[104:107]
	v_mfma_f32_16x16x32_bf16 v[92:95], v[140:143], v[204:207], v[92:95]
	v_mfma_f32_16x16x32_bf16 v[88:91], v[148:151], v[204:207], v[88:91]
	v_mfma_f32_16x16x32_bf16 v[76:79], v[140:143], v[216:219], v[76:79]
	v_mfma_f32_16x16x32_bf16 v[72:75], v[148:151], v[216:219], v[72:75]
	s_setprio 0
	s_barrier
	s_add_i32 s22, 0, 0x1c000
	v_add_u32_e32 v135, s22, v133
	s_add_u32 s20, s20, 0x80
	ds_read_b128 v[220:223], v135
	ds_read_b128 v[224:227], v135 offset:1024
	ds_read_b128 v[228:231], v135 offset:2048
	ds_read_b128 v[232:235], v135 offset:3072
	s_addc_u32 s21, s21, 0
	v_mov_b32_e32 v135, v129
	s_add_i32 s23, s80, s64
	s_mov_b32 m0, s23
	s_nop 0
	global_load_lds_dwordx4 v135, s[20:21]
	v_mov_b32_e32 v135, v131
	s_add_i32 m0, s23, 0x2000
	s_nop 0
	global_load_lds_dwordx4 v135, s[20:21]
	s_barrier
; #define PG8_STAGE(bufoff, gbase, voff) do { const char* _gb = (const char*)(gbase); asm volatile("" : "+s"(_gb)); _Pragma("unroll") for (int _i = 0; _i < 2; ++_i) { unsigned _vo = (voff)[_i]; asm volatile("" : "+v"(_vo)); \
;         __builtin_amdgcn_global_load_lds((const GAS unsigned*)(_gb + _vo), (LAS unsigned*)(lds + (bufoff) + ldsw + _i * 8192), 16, 0, 0); } } while (0)
; #define PG8_LDA(dst, b, h) do { _Pragma("unroll") for (int m = 0; m < 4; ++m) _Pragma("unroll") for (int k = 0; k < 2; ++k) dst[m][k] = *(const LAS bf16x8*)(lds + PG8_SA(b, h) + aoff + m * 2048 + k * 1024); } while (0)
; #define PG8_MMA(ai, bj, At, Bt) do { __builtin_amdgcn_s_setprio(1); _Pragma("unroll") for (int m = 0; m < 4; ++m) _Pragma("unroll") for (int n = 0; n < 2; ++n) _Pragma("unroll") for (int k = 0; k < 2; ++k) \
;         acc[ai][bj][m][n] = __builtin_amdgcn_mfma_f32_16x16x32_bf16(Bt[n][k], At[m][k], acc[ai][bj][m][n], 0, 0, 0); __builtin_amdgcn_s_setprio(0); } while (0)
; #define PG8_WAIT_V(n) asm volatile("s_waitcnt vmcnt(" #n ")" ::: "memory")
; #define PG8_WAIT_L(n) asm volatile("s_waitcnt lgkmcnt(" #n ")" ::: "memory")
; #define PG8_BAR __builtin_amdgcn_s_barrier()
; #define PG8_SCHED __builtin_amdgcn_sched_barrier(0)
; template <class Epi, class Ord>
; __device__ __forceinline__ void gemm_phase(LAS unsigned char* lds, const Gemm g, const Ord& S, const Epi& E) {
;     ...
;         for (int t = 0; t < nt; t += 2) {
;             const bool last = (t == nt - 2);
;             const char* a1 = cA + (size_t)(t + 1) * kstep;
;             const char* a2 = last ? nA : cA + (size_t)(t + 2) * kstep; const char* b2 = last ? nB : cB + (size_t)(t + 2) * kstep;
;             const char* a3 = a2 + kstep; const char* b3 = b2 + kstep;
;     ...
;             PG8_BAR; PG8_WAIT_L(0); PG8_MMA(0, 1, At, B1); PG8_BAR;
;             PG8_LDA(At, 1, 1); PG8_STAGE(PG8_SA(1, 0), a3, voffA);
;             PG8_BAR; PG8_WAIT_L(0); PG8_MMA(1, 0, At, B0); PG8_BAR; PG8_SCHED;
;             PG8_STAGE(PG8_SB(1, 1), b3 + hstep, voffB);
;             PG8_WAIT_V(6); PG8_BAR; PG8_MMA(1, 1, At, B1); PG8_BAR;
	s_waitcnt lgkmcnt(0)
	s_setprio 1
	s_waitcnt lgkmcnt(0)
	v_mfma_f32_16x16x32_bf16 v[116:119], v[220:223], v[152:155], v[116:119]
	v_mfma_f32_16x16x32_bf16 v[112:115], v[228:231], v[152:155], v[112:115]
	v_mfma_f32_16x16x32_bf16 v[100:103], v[220:223], v[192:195], v[100:103]
	v_mfma_f32_16x16x32_bf16 v[96:99], v[228:231], v[192:195], v[96:99]
	v_mfma_f32_16x16x32_bf16 v[84:87], v[220:223], v[200:203], v[84:87]
	v_mfma_f32_16x16x32_bf16 v[80:83], v[228:231], v[200:203], v[80:83]
	v_mfma_f32_16x16x32_bf16 v[68:71], v[220:223], v[212:215], v[68:71]
	v_mfma_f32_16x16x32_bf16 v[64:67], v[228:231], v[212:215], v[64:67]
	v_mfma_f32_16x16x32_bf16 v[116:119], v[224:227], v[156:159], v[116:119]
	v_mfma_f32_16x16x32_bf16 v[112:115], v[232:235], v[156:159], v[112:115]
	v_mfma_f32_16x16x32_bf16 v[100:103], v[224:227], v[196:199], v[100:103]
	v_mfma_f32_16x16x32_bf16 v[96:99], v[232:235], v[196:199], v[96:99]
	v_mfma_f32_16x16x32_bf16 v[84:87], v[224:227], v[204:207], v[84:87]
	v_mfma_f32_16x16x32_bf16 v[80:83], v[232:235], v[204:207], v[80:83]
	v_mfma_f32_16x16x32_bf16 v[68:71], v[224:227], v[216:219], v[68:71]
	v_mfma_f32_16x16x32_bf16 v[64:67], v[232:235], v[216:219], v[64:67]
	s_setprio 0
	v_mov_b32_e32 v135, v128
	s_mov_b32 m0, s70
	s_barrier
	ds_read_b128 v[152:155], v134 offset:49152
	ds_read_b128 v[156:159], v134 offset:50176
	ds_read_b128 v[192:195], v134 offset:51200
	ds_read_b128 v[196:199], v134 offset:52224
	ds_read_b128 v[200:203], v134 offset:53248
	ds_read_b128 v[204:207], v134 offset:54272
	ds_read_b128 v[212:215], v134 offset:55296
	ds_read_b128 v[216:219], v134 offset:56320
	s_nop 0
	global_load_lds_dwordx4 v135, s[12:13]
	v_mov_b32_e32 v135, v130
	s_mov_b32 m0, s71
	s_nop 0
	global_load_lds_dwordx4 v135, s[12:13]
	s_barrier
	s_waitcnt lgkmcnt(0)
	s_setprio 1
	s_waitcnt lgkmcnt(0)
	v_mfma_f32_16x16x32_bf16 v[60:63], v[136:139], v[152:155], v[60:63]
	v_mfma_f32_16x16x32_bf16 v[56:59], v[144:147], v[152:155], v[56:59]
	v_mfma_f32_16x16x32_bf16 v[44:47], v[136:139], v[192:195], v[44:47]
	v_mfma_f32_16x16x32_bf16 v[40:43], v[144:147], v[192:195], v[40:43]
	v_mfma_f32_16x16x32_bf16 v[28:31], v[136:139], v[200:203], v[28:31]
	v_mfma_f32_16x16x32_bf16 v[24:27], v[144:147], v[200:203], v[24:27]
	v_mfma_f32_16x16x32_bf16 v[12:15], v[136:139], v[212:215], v[12:15]
	v_mfma_f32_16x16x32_bf16 v[8:11], v[144:147], v[212:215], v[8:11]
	v_mfma_f32_16x16x32_bf16 v[60:63], v[140:143], v[156:159], v[60:63]
	v_mfma_f32_16x16x32_bf16 v[56:59], v[148:151], v[156:159], v[56:59]
	v_mfma_f32_16x16x32_bf16 v[44:47], v[140:143], v[196:199], v[44:47]
	v_mfma_f32_16x16x32_bf16 v[40:43], v[148:151], v[196:199], v[40:43]
	v_mfma_f32_16x16x32_bf16 v[28:31], v[140:143], v[204:207], v[28:31]
	v_mfma_f32_16x16x32_bf16 v[24:27], v[148:151], v[204:207], v[24:27]
	v_mfma_f32_16x16x32_bf16 v[12:15], v[140:143], v[216:219], v[12:15]
	v_mfma_f32_16x16x32_bf16 v[8:11], v[148:151], v[216:219], v[8:11]
	s_setprio 0
	s_barrier
	s_add_u32 s12, s24, 0x80
	s_addc_u32 s13, s25, 0
	v_mov_b32_e32 v135, v129
	s_add_i32 s20, s22, s64
	s_mov_b32 m0, s20
	s_nop 0
	global_load_lds_dwordx4 v135, s[12:13]
	v_mov_b32_e32 v135, v131
	s_add_i32 m0, s20, 0x2000
	s_nop 0
	global_load_lds_dwordx4 v135, s[12:13]
	s_waitcnt vmcnt(6)
	s_barrier
	s_setprio 1
	v_mfma_f32_16x16x32_bf16 v[52:55], v[220:223], v[152:155], v[52:55]
	v_mfma_f32_16x16x32_bf16 v[48:51], v[228:231], v[152:155], v[48:51]
	v_mfma_f32_16x16x32_bf16 v[36:39], v[220:223], v[192:195], v[36:39]
	v_mfma_f32_16x16x32_bf16 v[32:35], v[228:231], v[192:195], v[32:35]
	v_mfma_f32_16x16x32_bf16 v[20:23], v[220:223], v[200:203], v[20:23]
	v_mfma_f32_16x16x32_bf16 v[16:19], v[228:231], v[200:203], v[16:19]
	v_mfma_f32_16x16x32_bf16 v[4:7], v[220:223], v[212:215], v[4:7]
	v_mfma_f32_16x16x32_bf16 v[0:3], v[228:231], v[212:215], v[0:3]
	v_mfma_f32_16x16x32_bf16 v[52:55], v[224:227], v[156:159], v[52:55]
	v_mfma_f32_16x16x32_bf16 v[48:51], v[232:235], v[156:159], v[48:51]
	v_mfma_f32_16x16x32_bf16 v[36:39], v[224:227], v[196:199], v[36:39]
	v_mfma_f32_16x16x32_bf16 v[32:35], v[232:235], v[196:199], v[32:35]
	v_mfma_f32_16x16x32_bf16 v[20:23], v[224:227], v[204:207], v[20:23]
	v_mfma_f32_16x16x32_bf16 v[16:19], v[232:235], v[204:207], v[16:19]
	v_mfma_f32_16x16x32_bf16 v[4:7], v[224:227], v[216:219], v[4:7]
	v_mfma_f32_16x16x32_bf16 v[0:3], v[232:235], v[216:219], v[0:3]
	s_setprio 0
	s_add_u32 s46, s46, 0x100
	s_addc_u32 s47, s47, 0
	s_add_u32 s52, s52, 0x100
	s_addc_u32 s53, s53, 0
	s_mov_b32 s12, s79
	s_add_i32 s79, s12, 2
	s_cmp_eq_u32 s73, s12
	s_cselect_b32 s22, s0, s52
	s_cselect_b32 s23, s1, s53
	s_cselect_b32 s20, s44, s46
	s_cselect_b32 s21, s45, s47
	s_add_u32 s12, s22, 0x80
	s_addc_u32 s13, s23, 0
	s_add_i32 s80, 0, 0x10000
	v_add_u32_e32 v135, s80, v133
	s_sub_i32 s98, s79, 2
	s_cmp_ge_i32 s98, s69
	s_barrier
	s_cbranch_scc0 .LBB0_167
	s_branch .LBB0_154

; template <class Epi, class Ord>
; __device__ __forceinline__ void gemm_phase(LAS unsigned char* lds, const Gemm g, const Ord& S, const Epi& E) {
;     ...
;         for (int t = 0; t < nt; t += 2) {
;             const bool last = (t == nt - 2);
;             const char* a1 = cA + (size_t)(t + 1) * kstep;
;             const char* a2 = last ? nA : cA + (size_t)(t + 2) * kstep; const char* b2 = last ? nB : cB + (size_t)(t + 2) * kstep;
;             const char* a3 = a2 + kstep; const char* b3 = b2 + kstep;
;     ...
; #pragma unroll
;         for (int a = 0; a < 2; ++a)
; #pragma unroll
;             for (int b = 0; b < 2; ++b)
; #pragma unroll
;                 for (int m = 0; m < 4; ++m)
; #pragma unroll
;                     for (int n = 0; n < 2; ++n) acc[a][b][m][n] = (f32x4){0.f, 0.f, 0.f, 0.f};
.LBB0_198:
	v_mov_b32_e32 v155, 0
	s_andn2_b64 vcc, exec, s[18:19]
	v_mov_b32_e32 v154, 0
	v_mov_b32_e32 v193, 0
	v_mov_b32_e32 v192, 0
	v_mov_b32_e32 v157, 0
	v_mov_b32_e32 v156, 0
	v_mov_b32_e32 v159, 0
	v_mov_b32_e32 v158, 0
	v_mov_b32_e32 v147, 0
	v_mov_b32_e32 v146, 0
	v_mov_b32_e32 v145, 0
	v_mov_b32_e32 v144, 0
	v_mov_b32_e32 v143, 0
	v_mov_b32_e32 v142, 0
	v_mov_b32_e32 v141, 0
	v_mov_b32_e32 v140, 0
	v_mov_b32_e32 v123, 0
	v_mov_b32_e32 v122, 0
	v_mov_b32_e32 v121, 0
	v_mov_b32_e32 v120, 0
	v_mov_b32_e32 v119, 0
	v_mov_b32_e32 v118, 0
	v_mov_b32_e32 v117, 0
	v_mov_b32_e32 v116, 0
	v_mov_b32_e32 v107, 0
	v_mov_b32_e32 v106, 0
	v_mov_b32_e32 v105, 0
	v_mov_b32_e32 v104, 0
	v_mov_b32_e32 v103, 0
	v_mov_b32_e32 v102, 0
	v_mov_b32_e32 v101, 0
	v_mov_b32_e32 v100, 0
	v_mov_b32_e32 v151, 0
	v_mov_b32_e32 v150, 0
	v_mov_b32_e32 v153, 0
	v_mov_b32_e32 v152, 0
	v_mov_b32_e32 v127, 0
	v_mov_b32_e32 v126, 0
	v_mov_b32_e32 v125, 0
	v_mov_b32_e32 v124, 0
	v_mov_b32_e32 v139, 0
	v_mov_b32_e32 v138, 0
	v_mov_b32_e32 v137, 0
	v_mov_b32_e32 v136, 0
	v_mov_b32_e32 v135, 0
	v_mov_b32_e32 v134, 0
	v_mov_b32_e32 v133, 0
	v_mov_b32_e32 v132, 0
	v_mov_b32_e32 v115, 0
	v_mov_b32_e32 v114, 0
	v_mov_b32_e32 v113, 0
	v_mov_b32_e32 v112, 0
	v_mov_b32_e32 v111, 0
	v_mov_b32_e32 v110, 0
	v_mov_b32_e32 v109, 0
	v_mov_b32_e32 v108, 0
	v_mov_b32_e32 v99, 0
	v_mov_b32_e32 v98, 0
	v_mov_b32_e32 v97, 0
	v_mov_b32_e32 v96, 0
	v_mov_b32_e32 v95, 0
	v_mov_b32_e32 v94, 0
	v_mov_b32_e32 v93, 0
	v_mov_b32_e32 v92, 0
	v_mov_b32_e32 v87, 0
	v_mov_b32_e32 v86, 0
	v_mov_b32_e32 v91, 0
	v_mov_b32_e32 v90, 0
	v_mov_b32_e32 v85, 0
	v_mov_b32_e32 v84, 0
	v_mov_b32_e32 v89, 0
	v_mov_b32_e32 v88, 0
	v_mov_b32_e32 v75, 0
	v_mov_b32_e32 v74, 0
	v_mov_b32_e32 v73, 0
	v_mov_b32_e32 v72, 0
	v_mov_b32_e32 v71, 0
	v_mov_b32_e32 v70, 0
	v_mov_b32_e32 v69, 0
	v_mov_b32_e32 v68, 0
	v_mov_b32_e32 v59, 0
	v_mov_b32_e32 v58, 0
	v_mov_b32_e32 v57, 0
	v_mov_b32_e32 v56, 0
	v_mov_b32_e32 v55, 0
	v_mov_b32_e32 v54, 0
	v_mov_b32_e32 v53, 0
	v_mov_b32_e32 v52, 0
	v_mov_b32_e32 v43, 0
	v_mov_b32_e32 v42, 0
	v_mov_b32_e32 v41, 0
	v_mov_b32_e32 v40, 0
	v_mov_b32_e32 v39, 0
	v_mov_b32_e32 v38, 0
	v_mov_b32_e32 v37, 0
	v_mov_b32_e32 v36, 0
	v_mov_b32_e32 v81, 0
	v_mov_b32_e32 v80, 0
	v_mov_b32_e32 v83, 0
	v_mov_b32_e32 v82, 0
	v_mov_b32_e32 v79, 0
	v_mov_b32_e32 v78, 0
	v_mov_b32_e32 v77, 0
	v_mov_b32_e32 v76, 0
	v_mov_b32_e32 v67, 0
	v_mov_b32_e32 v66, 0
	v_mov_b32_e32 v65, 0
	v_mov_b32_e32 v64, 0
	v_mov_b32_e32 v63, 0
	v_mov_b32_e32 v62, 0
	v_mov_b32_e32 v61, 0
	v_mov_b32_e32 v60, 0
	v_mov_b32_e32 v51, 0
	v_mov_b32_e32 v50, 0
	v_mov_b32_e32 v49, 0
	v_mov_b32_e32 v48, 0
	v_mov_b32_e32 v47, 0
	v_mov_b32_e32 v46, 0
	v_mov_b32_e32 v45, 0
	v_mov_b32_e32 v44, 0
	v_mov_b32_e32 v35, 0
	v_mov_b32_e32 v34, 0
	v_mov_b32_e32 v33, 0
	v_mov_b32_e32 v32, 0
	v_mov_b32_e32 v31, 0
	v_mov_b32_e32 v30, 0
	v_mov_b32_e32 v29, 0
	v_mov_b32_e32 v28, 0
	s_cbranch_vccnz .LBB0_202
	s_add_u32 s52, s52, 0x100
	s_addc_u32 s53, s53, 0
	s_add_u32 s56, s56, 0x100
	v_mov_b32_e32 v0, 0
	s_addc_u32 s57, s57, 0
	s_mov_b32 s12, 0
	s_waitcnt lgkmcnt(0)
	v_mov_b32_e32 v1, v0
	v_mov_b32_e32 v2, v0
	v_mov_b32_e32 v3, v0
	v_mov_b32_e32 v4, v0
	v_mov_b32_e32 v5, v0
	v_mov_b32_e32 v6, v0
	v_mov_b32_e32 v7, v0
	v_mov_b32_e32 v8, v0
	v_mov_b32_e32 v9, v0
	v_mov_b32_e32 v10, v0
	v_mov_b32_e32 v11, v0
	v_mov_b32_e32 v12, v0
	v_mov_b32_e32 v13, v0
	v_mov_b32_e32 v14, v0
	v_mov_b32_e32 v15, v0
	v_mov_b32_e32 v20, v0
	v_mov_b32_e32 v21, v0
	v_mov_b32_e32 v22, v0
	v_mov_b32_e32 v23, v0
	v_mov_b32_e32 v28, v0
	v_mov_b32_e32 v29, v0
	v_mov_b32_e32 v30, v0
	v_mov_b32_e32 v31, v0
	v_mov_b32_e32 v36, v0
	v_mov_b32_e32 v37, v0
	v_mov_b32_e32 v38, v0
	v_mov_b32_e32 v39, v0
	v_mov_b32_e32 v44, v0
	v_mov_b32_e32 v45, v0
	v_mov_b32_e32 v46, v0
	v_mov_b32_e32 v47, v0
	v_mov_b32_e32 v16, v0
	v_mov_b32_e32 v17, v0
	v_mov_b32_e32 v18, v0
	v_mov_b32_e32 v19, v0
	v_mov_b32_e32 v24, v0
	v_mov_b32_e32 v25, v0
	v_mov_b32_e32 v26, v0
	v_mov_b32_e32 v27, v0
	v_mov_b32_e32 v32, v0
	v_mov_b32_e32 v33, v0
	v_mov_b32_e32 v34, v0
	v_mov_b32_e32 v35, v0
	v_mov_b32_e32 v40, v0
	v_mov_b32_e32 v41, v0
	v_mov_b32_e32 v42, v0
	v_mov_b32_e32 v43, v0
	v_mov_b32_e32 v48, v0
	v_mov_b32_e32 v49, v0
	v_mov_b32_e32 v50, v0
	v_mov_b32_e32 v51, v0
	v_mov_b32_e32 v52, v0
	v_mov_b32_e32 v53, v0
	v_mov_b32_e32 v54, v0
	v_mov_b32_e32 v55, v0
	v_mov_b32_e32 v56, v0
	v_mov_b32_e32 v57, v0
	v_mov_b32_e32 v58, v0
	v_mov_b32_e32 v59, v0
	v_mov_b32_e32 v60, v0
	v_mov_b32_e32 v61, v0
	v_mov_b32_e32 v62, v0
	v_mov_b32_e32 v63, v0
	v_mov_b32_e32 v64, v0
	v_mov_b32_e32 v65, v0
	v_mov_b32_e32 v66, v0
	v_mov_b32_e32 v67, v0
	v_mov_b32_e32 v68, v0
	v_mov_b32_e32 v69, v0
	v_mov_b32_e32 v70, v0
	v_mov_b32_e32 v71, v0
	v_mov_b32_e32 v72, v0
	v_mov_b32_e32 v73, v0
	v_mov_b32_e32 v74, v0
	v_mov_b32_e32 v75, v0
	v_mov_b32_e32 v76, v0
	v_mov_b32_e32 v77, v0
	v_mov_b32_e32 v78, v0
	v_mov_b32_e32 v79, v0
	v_mov_b32_e32 v88, v0
	v_mov_b32_e32 v89, v0
	v_mov_b32_e32 v90, v0
	v_mov_b32_e32 v91, v0
	v_mov_b32_e32 v92, v0
	v_mov_b32_e32 v93, v0
	v_mov_b32_e32 v94, v0
	v_mov_b32_e32 v95, v0
	v_mov_b32_e32 v104, v0
	v_mov_b32_e32 v105, v0
	v_mov_b32_e32 v106, v0
	v_mov_b32_e32 v107, v0
	v_mov_b32_e32 v108, v0
	v_mov_b32_e32 v109, v0
	v_mov_b32_e32 v110, v0
	v_mov_b32_e32 v111, v0
	v_mov_b32_e32 v80, v0
	v_mov_b32_e32 v81, v0
	v_mov_b32_e32 v82, v0
	v_mov_b32_e32 v83, v0
	v_mov_b32_e32 v84, v0
	v_mov_b32_e32 v85, v0
	v_mov_b32_e32 v86, v0
	v_mov_b32_e32 v87, v0
	v_mov_b32_e32 v96, v0
	v_mov_b32_e32 v97, v0
	v_mov_b32_e32 v98, v0
	v_mov_b32_e32 v99, v0
	v_mov_b32_e32 v100, v0
	v_mov_b32_e32 v101, v0
	v_mov_b32_e32 v102, v0
	v_mov_b32_e32 v103, v0
	v_mov_b32_e32 v112, v0
	v_mov_b32_e32 v113, v0
	v_mov_b32_e32 v114, v0
	v_mov_b32_e32 v115, v0
	v_mov_b32_e32 v116, v0
	v_mov_b32_e32 v117, v0
	v_mov_b32_e32 v118, v0
	v_mov_b32_e32 v119, v0
	v_mov_b32_e32 v120, v0
	v_mov_b32_e32 v121, v0
	v_mov_b32_e32 v122, v0
	v_mov_b32_e32 v123, v0
	v_mov_b32_e32 v124, v0
	v_mov_b32_e32 v125, v0
	v_mov_b32_e32 v126, v0
	v_mov_b32_e32 v127, v0
	s_add_i32 s94, s12, 2
	s_cmp_eq_u32 s81, s12
	s_cselect_b32 s22, s44, s56
	s_cselect_b32 s23, s45, s57
	s_cselect_b32 s20, s46, s52
	s_cselect_b32 s21, s47, s53
	s_add_u32 s12, s22, 0x80
	s_addc_u32 s13, s23, 0
	s_add_i32 s82, 0, 0x10000
	v_add_u32_e32 v144, s82, v204
; #define PG8_STAGE(bufoff, gbase, voff) do { const char* _gb = (const char*)(gbase); asm volatile("" : "+s"(_gb)); _Pragma("unroll") for (int _i = 0; _i < 2; ++_i) { unsigned _vo = (voff)[_i]; asm volatile("" : "+v"(_vo)); \
;         __builtin_amdgcn_global_load_lds((const GAS unsigned*)(_gb + _vo), (LAS unsigned*)(lds + (bufoff) + ldsw + _i * 8192), 16, 0, 0); } } while (0)
; #define PG8_LDA(dst, b, h) do { _Pragma("unroll") for (int m = 0; m < 4; ++m) _Pragma("unroll") for (int k = 0; k < 2; ++k) dst[m][k] = *(const LAS bf16x8*)(lds + PG8_SA(b, h) + aoff + m * 2048 + k * 1024); } while (0)
; #define PG8_LDB(dst, b, h) do { _Pragma("unroll") for (int n = 0; n < 2; ++n) _Pragma("unroll") for (int k = 0; k < 2; ++k) dst[n][k] = *(const LAS bf16x8*)(lds + PG8_SB(b, h) + boff + n * 2048 + k * 1024); } while (0)
; #define PG8_MMA(ai, bj, At, Bt) do { __builtin_amdgcn_s_setprio(1); _Pragma("unroll") for (int m = 0; m < 4; ++m) _Pragma("unroll") for (int n = 0; n < 2; ++n) _Pragma("unroll") for (int k = 0; k < 2; ++k) \
;         acc[ai][bj][m][n] = __builtin_amdgcn_mfma_f32_16x16x32_bf16(Bt[n][k], At[m][k], acc[ai][bj][m][n], 0, 0, 0); __builtin_amdgcn_s_setprio(0); } while (0)
; #define PG8_WAIT_L(n) asm volatile("s_waitcnt lgkmcnt(" #n ")" ::: "memory")
; #define PG8_BAR __builtin_amdgcn_s_barrier()
; #define PG8_SCHED __builtin_amdgcn_sched_barrier(0)
; template <class Epi, class Ord>
; __device__ __forceinline__ void gemm_phase(LAS unsigned char* lds, const Gemm g, const Ord& S, const Epi& E) {
;     ...
;             PG8_LDB(B0, 0, 0); PG8_SCHED; PG8_LDA(At, 0, 0); PG8_STAGE(PG8_SA(1, 1), a1 + hstep, voffA);
;             PG8_WAIT_L(8); PG8_BAR; PG8_WAIT_L(0); PG8_MMA(0, 0, At, B0); PG8_BAR; PG8_SCHED;
;             PG8_LDB(B1, 0, 1); PG8_STAGE(PG8_SB(0, 0), b2, voffB);
;             PG8_BAR; PG8_WAIT_L(0); PG8_MMA(0, 1, At, B1); PG8_BAR;
;             PG8_LDA(At, 0, 1); PG8_STAGE(PG8_SA(0, 0), a2, voffA);
;             PG8_BAR; PG8_WAIT_L(0); PG8_MMA(1, 0, At, B0); PG8_BAR; PG8_SCHED;
.LBB0_200:
	ds_read_b128 v[132:135], v144
	ds_read_b128 v[136:139], v144 offset:1024
	ds_read_b128 v[140:143], v144 offset:2048
	ds_read_b128 v[144:147], v144 offset:3072
	s_add_u32 s24, s56, s0
	s_addc_u32 s25, s57, s1
	s_add_u32 s24, s24, 0xffffff80
	s_addc_u32 s25, s25, -1
	v_mov_b32_e32 v168, v129
	ds_read_b128 v[148:151], v206
	ds_read_b128 v[152:155], v206 offset:1024
	ds_read_b128 v[156:159], v206 offset:2048
	ds_read_b128 v[192:195], v206 offset:3072
	ds_read_b128 v[196:199], v206 offset:4096
	ds_read_b128 v[212:215], v206 offset:5120
	ds_read_b128 v[216:219], v206 offset:6144
	ds_read_b128 v[220:223], v206 offset:7168
	s_add_i32 m0, s70, 0xc000
	s_nop 0
	global_load_lds_dwordx4 v168, s[24:25]
	v_mov_b32_e32 v168, v201
	s_add_i32 m0, s70, 0xe000
	s_nop 0
	global_load_lds_dwordx4 v168, s[24:25]
	s_waitcnt lgkmcnt(8)
	s_barrier
	s_waitcnt lgkmcnt(0)
	s_setprio 1
	s_waitcnt lgkmcnt(0)
	v_mfma_f32_16x16x32_bf16 v[124:127], v[132:135], v[148:151], v[124:127]
	v_mfma_f32_16x16x32_bf16 v[120:123], v[140:143], v[148:151], v[120:123]
	v_mfma_f32_16x16x32_bf16 v[116:119], v[132:135], v[156:159], v[116:119]
	v_mfma_f32_16x16x32_bf16 v[112:115], v[140:143], v[156:159], v[112:115]
	v_mfma_f32_16x16x32_bf16 v[100:103], v[132:135], v[196:199], v[100:103]
	v_mfma_f32_16x16x32_bf16 v[96:99], v[140:143], v[196:199], v[96:99]
	v_mfma_f32_16x16x32_bf16 v[84:87], v[132:135], v[216:219], v[84:87]
	v_mfma_f32_16x16x32_bf16 v[80:83], v[140:143], v[216:219], v[80:83]
	v_mfma_f32_16x16x32_bf16 v[124:127], v[136:139], v[152:155], v[124:127]
	v_mfma_f32_16x16x32_bf16 v[120:123], v[144:147], v[152:155], v[120:123]
	v_mfma_f32_16x16x32_bf16 v[116:119], v[136:139], v[192:195], v[116:119]
	v_mfma_f32_16x16x32_bf16 v[112:115], v[144:147], v[192:195], v[112:115]
	v_mfma_f32_16x16x32_bf16 v[100:103], v[136:139], v[212:215], v[100:103]
	v_mfma_f32_16x16x32_bf16 v[96:99], v[144:147], v[212:215], v[96:99]
	v_mfma_f32_16x16x32_bf16 v[84:87], v[136:139], v[220:223], v[84:87]
	v_mfma_f32_16x16x32_bf16 v[80:83], v[144:147], v[220:223], v[80:83]
	s_setprio 0
	s_barrier
	s_add_i32 s84, 0, 0x14000
	v_add_u32_e32 v168, s84, v204
	ds_read_b128 v[224:227], v168
	ds_read_b128 v[228:231], v168 offset:1024
	ds_read_b128 v[232:235], v168 offset:2048
	ds_read_b128 v[236:239], v168 offset:3072
	s_mov_b64 s[24:25], s[20:21]
	v_mov_b32_e32 v168, v200
	s_add_i32 s82, s82, s69
	s_mov_b32 m0, s82
	s_nop 0
	global_load_lds_dwordx4 v168, s[24:25]
	v_mov_b32_e32 v168, v202
	s_add_i32 m0, s82, 0x2000
	s_nop 0
	global_load_lds_dwordx4 v168, s[24:25]
	s_barrier
	s_waitcnt lgkmcnt(0)
	s_setprio 1
	s_waitcnt lgkmcnt(0)
	v_mfma_f32_16x16x32_bf16 v[108:111], v[224:227], v[148:151], v[108:111]
	v_mfma_f32_16x16x32_bf16 v[104:107], v[232:235], v[148:151], v[104:107]
	v_mfma_f32_16x16x32_bf16 v[92:95], v[224:227], v[156:159], v[92:95]
	v_mfma_f32_16x16x32_bf16 v[88:91], v[232:235], v[156:159], v[88:91]
	v_mfma_f32_16x16x32_bf16 v[76:79], v[224:227], v[196:199], v[76:79]
	v_mfma_f32_16x16x32_bf16 v[72:75], v[232:235], v[196:199], v[72:75]
	v_mfma_f32_16x16x32_bf16 v[68:71], v[224:227], v[216:219], v[68:71]
	v_mfma_f32_16x16x32_bf16 v[64:67], v[232:235], v[216:219], v[64:67]
	v_mfma_f32_16x16x32_bf16 v[108:111], v[228:231], v[152:155], v[108:111]
	v_mfma_f32_16x16x32_bf16 v[104:107], v[236:239], v[152:155], v[104:107]
	v_mfma_f32_16x16x32_bf16 v[92:95], v[228:231], v[192:195], v[92:95]
	v_mfma_f32_16x16x32_bf16 v[88:91], v[236:239], v[192:195], v[88:91]
	v_mfma_f32_16x16x32_bf16 v[76:79], v[228:231], v[212:215], v[76:79]
	v_mfma_f32_16x16x32_bf16 v[72:75], v[236:239], v[212:215], v[72:75]
	v_mfma_f32_16x16x32_bf16 v[68:71], v[228:231], v[220:223], v[68:71]
	v_mfma_f32_16x16x32_bf16 v[64:67], v[236:239], v[220:223], v[64:67]
	s_setprio 0
	s_mov_b64 s[24:25], s[22:23]
	v_mov_b32_e32 v168, v129
	s_mov_b32 m0, s70
	s_barrier
	ds_read_b128 v[148:151], v206 offset:16384
	ds_read_b128 v[152:155], v206 offset:17408
	ds_read_b128 v[156:159], v206 offset:18432
	ds_read_b128 v[192:195], v206 offset:19456
	ds_read_b128 v[196:199], v206 offset:20480
	ds_read_b128 v[212:215], v206 offset:21504
	ds_read_b128 v[216:219], v206 offset:22528
	ds_read_b128 v[220:223], v206 offset:23552
	s_nop 0
	global_load_lds_dwordx4 v168, s[24:25]
	v_mov_b32_e32 v168, v201
	s_mov_b32 m0, s71
	s_nop 0
	global_load_lds_dwordx4 v168, s[24:25]
	s_barrier
	s_waitcnt lgkmcnt(0)
	s_setprio 1
	s_waitcnt lgkmcnt(0)
	v_mfma_f32_16x16x32_bf16 v[60:63], v[132:135], v[148:151], v[60:63]
	v_mfma_f32_16x16x32_bf16 v[56:59], v[140:143], v[148:151], v[56:59]
	v_mfma_f32_16x16x32_bf16 v[52:55], v[132:135], v[156:159], v[52:55]
	v_mfma_f32_16x16x32_bf16 v[48:51], v[140:143], v[156:159], v[48:51]
	v_mfma_f32_16x16x32_bf16 v[40:43], v[132:135], v[196:199], v[40:43]
	v_mfma_f32_16x16x32_bf16 v[32:35], v[140:143], v[196:199], v[32:35]
	v_mfma_f32_16x16x32_bf16 v[24:27], v[132:135], v[216:219], v[24:27]
	v_mfma_f32_16x16x32_bf16 v[16:19], v[140:143], v[216:219], v[16:19]
	v_mfma_f32_16x16x32_bf16 v[60:63], v[136:139], v[152:155], v[60:63]
	v_mfma_f32_16x16x32_bf16 v[56:59], v[144:147], v[152:155], v[56:59]
	v_mfma_f32_16x16x32_bf16 v[52:55], v[136:139], v[192:195], v[52:55]
	v_mfma_f32_16x16x32_bf16 v[48:51], v[144:147], v[192:195], v[48:51]
	v_mfma_f32_16x16x32_bf16 v[40:43], v[136:139], v[212:215], v[40:43]
	v_mfma_f32_16x16x32_bf16 v[32:35], v[144:147], v[212:215], v[32:35]
	v_mfma_f32_16x16x32_bf16 v[24:27], v[136:139], v[220:223], v[24:27]
	v_mfma_f32_16x16x32_bf16 v[16:19], v[144:147], v[220:223], v[16:19]
	s_setprio 0
	s_barrier
; #define PG8_STAGE(bufoff, gbase, voff) do { const char* _gb = (const char*)(gbase); asm volatile("" : "+s"(_gb)); _Pragma("unroll") for (int _i = 0; _i < 2; ++_i) { unsigned _vo = (voff)[_i]; asm volatile("" : "+v"(_vo)); \
;         __builtin_amdgcn_global_load_lds((const GAS unsigned*)(_gb + _vo), (LAS unsigned*)(lds + (bufoff) + ldsw + _i * 8192), 16, 0, 0); } } while (0)
; #define PG8_LDA(dst, b, h) do { _Pragma("unroll") for (int m = 0; m < 4; ++m) _Pragma("unroll") for (int k = 0; k < 2; ++k) dst[m][k] = *(const LAS bf16x8*)(lds + PG8_SA(b, h) + aoff + m * 2048 + k * 1024); } while (0)
; #define PG8_LDB(dst, b, h) do { _Pragma("unroll") for (int n = 0; n < 2; ++n) _Pragma("unroll") for (int k = 0; k < 2; ++k) dst[n][k] = *(const LAS bf16x8*)(lds + PG8_SB(b, h) + boff + n * 2048 + k * 1024); } while (0)
; #define PG8_MMA(ai, bj, At, Bt) do { __builtin_amdgcn_s_setprio(1); _Pragma("unroll") for (int m = 0; m < 4; ++m) _Pragma("unroll") for (int n = 0; n < 2; ++n) _Pragma("unroll") for (int k = 0; k < 2; ++k) \
;         acc[ai][bj][m][n] = __builtin_amdgcn_mfma_f32_16x16x32_bf16(Bt[n][k], At[m][k], acc[ai][bj][m][n], 0, 0, 0); __builtin_amdgcn_s_setprio(0); } while (0)
; #define PG8_WAIT_V(n) asm volatile("s_waitcnt vmcnt(" #n ")" ::: "memory")
; #define PG8_WAIT_L(n) asm volatile("s_waitcnt lgkmcnt(" #n ")" ::: "memory")
; #define PG8_BAR __builtin_amdgcn_s_barrier()
; #define PG8_SCHED __builtin_amdgcn_sched_barrier(0)
; template <class Epi, class Ord>
; __device__ __forceinline__ void gemm_phase(LAS unsigned char* lds, const Gemm g, const Ord& S, const Epi& E) {
;     ...
;             PG8_STAGE(PG8_SB(0, 1), b2 + hstep, voffB);
;             PG8_WAIT_V(6); PG8_BAR; PG8_MMA(1, 1, At, B1); PG8_BAR;
;             PG8_LDB(B0, 1, 0); PG8_SCHED; PG8_LDA(At, 1, 0); PG8_STAGE(PG8_SA(0, 1), a2 + hstep, voffA);
;             PG8_WAIT_L(8); PG8_BAR; PG8_WAIT_L(0); PG8_MMA(0, 0, At, B0); PG8_BAR; PG8_SCHED;
;             PG8_LDB(B1, 1, 1); PG8_STAGE(PG8_SB(1, 0), b3, voffB);
;             PG8_BAR; PG8_WAIT_L(0); PG8_MMA(0, 1, At, B1); PG8_BAR;
;             PG8_LDA(At, 1, 1); PG8_STAGE(PG8_SA(1, 0), a3, voffA);
	s_add_u32 s24, s20, s0
	s_addc_u32 s25, s21, s1
	s_mov_b64 s[82:83], s[24:25]
	v_mov_b32_e32 v132, v200
	s_add_i32 s84, s84, s69
	s_mov_b32 m0, s84
	s_nop 0
	global_load_lds_dwordx4 v132, s[82:83]
	v_mov_b32_e32 v132, v202
	s_add_i32 m0, s84, 0x2000
	s_nop 0
	global_load_lds_dwordx4 v132, s[82:83]
	s_waitcnt vmcnt(6)
	s_barrier
	s_setprio 1
	v_mfma_f32_16x16x32_bf16 v[44:47], v[224:227], v[148:151], v[44:47]
	v_mfma_f32_16x16x32_bf16 v[36:39], v[232:235], v[148:151], v[36:39]
	v_mfma_f32_16x16x32_bf16 v[28:31], v[224:227], v[156:159], v[28:31]
	v_mfma_f32_16x16x32_bf16 v[20:23], v[232:235], v[156:159], v[20:23]
	v_mfma_f32_16x16x32_bf16 v[12:15], v[224:227], v[196:199], v[12:15]
	v_mfma_f32_16x16x32_bf16 v[8:11], v[232:235], v[196:199], v[8:11]
	v_mfma_f32_16x16x32_bf16 v[4:7], v[224:227], v[216:219], v[4:7]
	v_mfma_f32_16x16x32_bf16 v[0:3], v[232:235], v[216:219], v[0:3]
	v_mfma_f32_16x16x32_bf16 v[44:47], v[228:231], v[152:155], v[44:47]
	v_mfma_f32_16x16x32_bf16 v[36:39], v[236:239], v[152:155], v[36:39]
	v_mfma_f32_16x16x32_bf16 v[28:31], v[228:231], v[192:195], v[28:31]
	v_mfma_f32_16x16x32_bf16 v[20:23], v[236:239], v[192:195], v[20:23]
	v_mfma_f32_16x16x32_bf16 v[12:15], v[228:231], v[212:215], v[12:15]
	v_mfma_f32_16x16x32_bf16 v[8:11], v[236:239], v[212:215], v[8:11]
	v_mfma_f32_16x16x32_bf16 v[4:7], v[228:231], v[220:223], v[4:7]
	v_mfma_f32_16x16x32_bf16 v[0:3], v[236:239], v[220:223], v[0:3]
	s_setprio 0
	s_add_i32 s82, 0, 0x18000
	v_add_u32_e32 v144, s82, v204
	s_barrier
	ds_read_b128 v[132:135], v144
	ds_read_b128 v[136:139], v144 offset:1024
	ds_read_b128 v[140:143], v144 offset:2048
	ds_read_b128 v[144:147], v144 offset:3072
	s_add_u32 s22, s22, s0
	s_addc_u32 s23, s23, s1
	v_mov_b32_e32 v168, v129
	s_mov_b32 m0, s72
	ds_read_b128 v[148:151], v206 offset:32768
	ds_read_b128 v[152:155], v206 offset:33792
	ds_read_b128 v[156:159], v206 offset:34816
	ds_read_b128 v[192:195], v206 offset:35840
	ds_read_b128 v[196:199], v206 offset:36864
	ds_read_b128 v[212:215], v206 offset:37888
	ds_read_b128 v[216:219], v206 offset:38912
	ds_read_b128 v[220:223], v206 offset:39936
	s_nop 0
	global_load_lds_dwordx4 v168, s[22:23]
	v_mov_b32_e32 v168, v201
	s_mov_b32 m0, s73
	s_nop 0
	global_load_lds_dwordx4 v168, s[22:23]
	s_waitcnt lgkmcnt(8)
	s_barrier
	s_waitcnt lgkmcnt(0)
	s_setprio 1
	s_waitcnt lgkmcnt(0)
	v_mfma_f32_16x16x32_bf16 v[124:127], v[132:135], v[148:151], v[124:127]
	v_mfma_f32_16x16x32_bf16 v[120:123], v[140:143], v[148:151], v[120:123]
	v_mfma_f32_16x16x32_bf16 v[116:119], v[132:135], v[156:159], v[116:119]
	v_mfma_f32_16x16x32_bf16 v[112:115], v[140:143], v[156:159], v[112:115]
	v_mfma_f32_16x16x32_bf16 v[100:103], v[132:135], v[196:199], v[100:103]
	v_mfma_f32_16x16x32_bf16 v[96:99], v[140:143], v[196:199], v[96:99]
	v_mfma_f32_16x16x32_bf16 v[84:87], v[132:135], v[216:219], v[84:87]
	v_mfma_f32_16x16x32_bf16 v[80:83], v[140:143], v[216:219], v[80:83]
	v_mfma_f32_16x16x32_bf16 v[124:127], v[136:139], v[152:155], v[124:127]
	v_mfma_f32_16x16x32_bf16 v[120:123], v[144:147], v[152:155], v[120:123]
	v_mfma_f32_16x16x32_bf16 v[116:119], v[136:139], v[192:195], v[116:119]
	v_mfma_f32_16x16x32_bf16 v[112:115], v[144:147], v[192:195], v[112:115]
	v_mfma_f32_16x16x32_bf16 v[100:103], v[136:139], v[212:215], v[100:103]
	v_mfma_f32_16x16x32_bf16 v[96:99], v[144:147], v[212:215], v[96:99]
	v_mfma_f32_16x16x32_bf16 v[84:87], v[136:139], v[220:223], v[84:87]
	v_mfma_f32_16x16x32_bf16 v[80:83], v[144:147], v[220:223], v[80:83]
	s_setprio 0
	s_barrier
	s_add_i32 s22, 0, 0x1c000
	v_add_u32_e32 v168, s22, v204
	s_add_u32 s20, s20, 0x80
	ds_read_b128 v[224:227], v168
	ds_read_b128 v[228:231], v168 offset:1024
	ds_read_b128 v[232:235], v168 offset:2048
	ds_read_b128 v[236:239], v168 offset:3072
	s_addc_u32 s21, s21, 0
	v_mov_b32_e32 v168, v200
	s_add_i32 s23, s82, s69
	s_mov_b32 m0, s23
	s_nop 0
	global_load_lds_dwordx4 v168, s[20:21]
	v_mov_b32_e32 v168, v202
	s_add_i32 m0, s23, 0x2000
	s_nop 0
	global_load_lds_dwordx4 v168, s[20:21]
	s_barrier
	s_waitcnt lgkmcnt(0)
	s_setprio 1
	s_waitcnt lgkmcnt(0)
	v_mfma_f32_16x16x32_bf16 v[108:111], v[224:227], v[148:151], v[108:111]
	v_mfma_f32_16x16x32_bf16 v[104:107], v[232:235], v[148:151], v[104:107]
	v_mfma_f32_16x16x32_bf16 v[92:95], v[224:227], v[156:159], v[92:95]
	v_mfma_f32_16x16x32_bf16 v[88:91], v[232:235], v[156:159], v[88:91]
	v_mfma_f32_16x16x32_bf16 v[76:79], v[224:227], v[196:199], v[76:79]
	v_mfma_f32_16x16x32_bf16 v[72:75], v[232:235], v[196:199], v[72:75]
	v_mfma_f32_16x16x32_bf16 v[68:71], v[224:227], v[216:219], v[68:71]
	v_mfma_f32_16x16x32_bf16 v[64:67], v[232:235], v[216:219], v[64:67]
	v_mfma_f32_16x16x32_bf16 v[108:111], v[228:231], v[152:155], v[108:111]
	v_mfma_f32_16x16x32_bf16 v[104:107], v[236:239], v[152:155], v[104:107]
	v_mfma_f32_16x16x32_bf16 v[92:95], v[228:231], v[192:195], v[92:95]
	v_mfma_f32_16x16x32_bf16 v[88:91], v[236:239], v[192:195], v[88:91]
	v_mfma_f32_16x16x32_bf16 v[76:79], v[228:231], v[212:215], v[76:79]
	v_mfma_f32_16x16x32_bf16 v[72:75], v[236:239], v[212:215], v[72:75]
	v_mfma_f32_16x16x32_bf16 v[68:71], v[228:231], v[220:223], v[68:71]
	v_mfma_f32_16x16x32_bf16 v[64:67], v[236:239], v[220:223], v[64:67]
	s_setprio 0
	v_mov_b32_e32 v168, v129
	s_mov_b32 m0, s79
	s_barrier
	ds_read_b128 v[148:151], v206 offset:49152
	ds_read_b128 v[152:155], v206 offset:50176
	ds_read_b128 v[156:159], v206 offset:51200
	ds_read_b128 v[192:195], v206 offset:52224
	ds_read_b128 v[196:199], v206 offset:53248
	ds_read_b128 v[212:215], v206 offset:54272
	ds_read_b128 v[216:219], v206 offset:55296
	ds_read_b128 v[220:223], v206 offset:56320
	s_nop 0
	global_load_lds_dwordx4 v168, s[12:13]
	v_mov_b32_e32 v168, v201
	s_mov_b32 m0, s80
	s_nop 0
	global_load_lds_dwordx4 v168, s[12:13]
	s_barrier
; #define PG8_STAGE(bufoff, gbase, voff) do { const char* _gb = (const char*)(gbase); asm volatile("" : "+s"(_gb)); _Pragma("unroll") for (int _i = 0; _i < 2; ++_i) { unsigned _vo = (voff)[_i]; asm volatile("" : "+v"(_vo)); \
;         __builtin_amdgcn_global_load_lds((const GAS unsigned*)(_gb + _vo), (LAS unsigned*)(lds + (bufoff) + ldsw + _i * 8192), 16, 0, 0); } } while (0)
; #define PG8_MMA(ai, bj, At, Bt) do { __builtin_amdgcn_s_setprio(1); _Pragma("unroll") for (int m = 0; m < 4; ++m) _Pragma("unroll") for (int n = 0; n < 2; ++n) _Pragma("unroll") for (int k = 0; k < 2; ++k) \
;         acc[ai][bj][m][n] = __builtin_amdgcn_mfma_f32_16x16x32_bf16(Bt[n][k], At[m][k], acc[ai][bj][m][n], 0, 0, 0); __builtin_amdgcn_s_setprio(0); } while (0)
; #define PG8_WAIT_V(n) asm volatile("s_waitcnt vmcnt(" #n ")" ::: "memory")
; #define PG8_WAIT_L(n) asm volatile("s_waitcnt lgkmcnt(" #n ")" ::: "memory")
; #define PG8_BAR __builtin_amdgcn_s_barrier()
; #define PG8_SCHED __builtin_amdgcn_sched_barrier(0)
; template <class Epi, class Ord>
; __device__ __forceinline__ void gemm_phase(LAS unsigned char* lds, const Gemm g, const Ord& S, const Epi& E) {
;     ...
;             PG8_BAR; PG8_WAIT_L(0); PG8_MMA(1, 0, At, B0); PG8_BAR; PG8_SCHED;
;             PG8_STAGE(PG8_SB(1, 1), b3 + hstep, voffB);
;             PG8_WAIT_V(6); PG8_BAR; PG8_MMA(1, 1, At, B1); PG8_BAR;
;         }
;     template <int NM> __device__ __forceinline__ void round(const AccT& acc, const Unit& u, int ai, int m0, int wr, int wc, int fr, int fq) const {
;     ...
;                 if (MODE == 0) { d0 = acc[ai][bj][m][0] * alpha; d1 = acc[ai][bj][m][1] * alpha; }
	s_waitcnt lgkmcnt(0)
	s_setprio 1
	s_waitcnt lgkmcnt(0)
	v_mfma_f32_16x16x32_bf16 v[60:63], v[132:135], v[148:151], v[60:63]
	v_mfma_f32_16x16x32_bf16 v[56:59], v[140:143], v[148:151], v[56:59]
	v_mfma_f32_16x16x32_bf16 v[52:55], v[132:135], v[156:159], v[52:55]
	v_mfma_f32_16x16x32_bf16 v[48:51], v[140:143], v[156:159], v[48:51]
	v_mfma_f32_16x16x32_bf16 v[40:43], v[132:135], v[196:199], v[40:43]
	v_mfma_f32_16x16x32_bf16 v[32:35], v[140:143], v[196:199], v[32:35]
	v_mfma_f32_16x16x32_bf16 v[24:27], v[132:135], v[216:219], v[24:27]
	v_mfma_f32_16x16x32_bf16 v[16:19], v[140:143], v[216:219], v[16:19]
	v_mfma_f32_16x16x32_bf16 v[60:63], v[136:139], v[152:155], v[60:63]
	v_mfma_f32_16x16x32_bf16 v[56:59], v[144:147], v[152:155], v[56:59]
	v_mfma_f32_16x16x32_bf16 v[52:55], v[136:139], v[192:195], v[52:55]
	v_mfma_f32_16x16x32_bf16 v[48:51], v[144:147], v[192:195], v[48:51]
	v_mfma_f32_16x16x32_bf16 v[40:43], v[136:139], v[212:215], v[40:43]
	v_mfma_f32_16x16x32_bf16 v[32:35], v[144:147], v[212:215], v[32:35]
	v_mfma_f32_16x16x32_bf16 v[24:27], v[136:139], v[220:223], v[24:27]
	v_mfma_f32_16x16x32_bf16 v[16:19], v[144:147], v[220:223], v[16:19]
	s_setprio 0
	s_barrier
	s_add_u32 s12, s24, 0x80
	s_addc_u32 s13, s25, 0
	v_mov_b32_e32 v132, v200
	s_add_i32 s20, s22, s69
	s_mov_b32 m0, s20
	s_nop 0
	global_load_lds_dwordx4 v132, s[12:13]
	v_mov_b32_e32 v132, v202
	s_add_i32 m0, s20, 0x2000
	s_nop 0
	global_load_lds_dwordx4 v132, s[12:13]
	s_waitcnt vmcnt(6)
	s_barrier
	s_setprio 1
	v_mfma_f32_16x16x32_bf16 v[44:47], v[224:227], v[148:151], v[44:47]
	v_mfma_f32_16x16x32_bf16 v[36:39], v[232:235], v[148:151], v[36:39]
	v_mfma_f32_16x16x32_bf16 v[28:31], v[224:227], v[156:159], v[28:31]
	v_mfma_f32_16x16x32_bf16 v[20:23], v[232:235], v[156:159], v[20:23]
	v_mfma_f32_16x16x32_bf16 v[12:15], v[224:227], v[196:199], v[12:15]
	v_mfma_f32_16x16x32_bf16 v[8:11], v[232:235], v[196:199], v[8:11]
	v_mfma_f32_16x16x32_bf16 v[4:7], v[224:227], v[216:219], v[4:7]
	v_mfma_f32_16x16x32_bf16 v[0:3], v[232:235], v[216:219], v[0:3]
	v_mfma_f32_16x16x32_bf16 v[44:47], v[228:231], v[152:155], v[44:47]
	v_mfma_f32_16x16x32_bf16 v[36:39], v[236:239], v[152:155], v[36:39]
	v_mfma_f32_16x16x32_bf16 v[28:31], v[228:231], v[192:195], v[28:31]
	v_mfma_f32_16x16x32_bf16 v[20:23], v[236:239], v[192:195], v[20:23]
	v_mfma_f32_16x16x32_bf16 v[12:15], v[228:231], v[212:215], v[12:15]
	v_mfma_f32_16x16x32_bf16 v[8:11], v[236:239], v[212:215], v[8:11]
	v_mfma_f32_16x16x32_bf16 v[4:7], v[228:231], v[220:223], v[4:7]
	v_mfma_f32_16x16x32_bf16 v[0:3], v[236:239], v[220:223], v[0:3]
	s_setprio 0
	s_add_u32 s52, s52, 0x100
	s_addc_u32 s53, s53, 0
	s_add_u32 s56, s56, 0x100
	s_addc_u32 s57, s57, 0
	s_mov_b32 s12, s94
	s_add_i32 s94, s12, 2
	s_cmp_eq_u32 s81, s12
	s_cselect_b32 s22, s44, s56
	s_cselect_b32 s23, s45, s57
	s_cselect_b32 s20, s46, s52
	s_cselect_b32 s21, s47, s53
	s_add_u32 s12, s22, 0x80
	s_addc_u32 s13, s23, 0
	s_add_i32 s82, 0, 0x10000
	v_add_u32_e32 v144, s82, v204
	s_sub_i32 s98, s94, 2
	s_cmp_ge_i32 s98, s77
	s_barrier
	s_cbranch_scc0 .LBB0_200
	v_readlane_b32 s94, v252, 31
	v_pk_mul_f32 v[154:155], v[126:127], 0.5 op_sel_hi:[1,0]
	v_pk_mul_f32 v[192:193], v[124:125], 0.5 op_sel_hi:[1,0]
	v_pk_mul_f32 v[156:157], v[122:123], 0.5 op_sel_hi:[1,0]
	v_pk_mul_f32 v[158:159], v[120:121], 0.5 op_sel_hi:[1,0]
	v_pk_mul_f32 v[150:151], v[110:111], 0.5 op_sel_hi:[1,0]
	v_pk_mul_f32 v[152:153], v[108:109], 0.5 op_sel_hi:[1,0]
	v_pk_mul_f32 v[126:127], v[106:107], 0.5 op_sel_hi:[1,0]
	v_pk_mul_f32 v[124:125], v[104:105], 0.5 op_sel_hi:[1,0]
	v_pk_mul_f32 v[146:147], v[118:119], 0.5 op_sel_hi:[1,0]
	v_pk_mul_f32 v[144:145], v[116:117], 0.5 op_sel_hi:[1,0]
	v_pk_mul_f32 v[142:143], v[114:115], 0.5 op_sel_hi:[1,0]
	v_pk_mul_f32 v[140:141], v[112:113], 0.5 op_sel_hi:[1,0]
	v_pk_mul_f32 v[138:139], v[94:95], 0.5 op_sel_hi:[1,0]
	v_pk_mul_f32 v[136:137], v[92:93], 0.5 op_sel_hi:[1,0]
	v_pk_mul_f32 v[134:135], v[90:91], 0.5 op_sel_hi:[1,0]
	v_pk_mul_f32 v[132:133], v[88:89], 0.5 op_sel_hi:[1,0]
	v_pk_mul_f32 v[122:123], v[102:103], 0.5 op_sel_hi:[1,0]
	v_pk_mul_f32 v[120:121], v[100:101], 0.5 op_sel_hi:[1,0]
	v_pk_mul_f32 v[118:119], v[98:99], 0.5 op_sel_hi:[1,0]
	v_pk_mul_f32 v[116:117], v[96:97], 0.5 op_sel_hi:[1,0]
	v_pk_mul_f32 v[114:115], v[78:79], 0.5 op_sel_hi:[1,0]
	v_pk_mul_f32 v[112:113], v[76:77], 0.5 op_sel_hi:[1,0]
	v_pk_mul_f32 v[110:111], v[74:75], 0.5 op_sel_hi:[1,0]
	v_pk_mul_f32 v[108:109], v[72:73], 0.5 op_sel_hi:[1,0]
	v_pk_mul_f32 v[106:107], v[86:87], 0.5 op_sel_hi:[1,0]
	v_pk_mul_f32 v[104:105], v[84:85], 0.5 op_sel_hi:[1,0]
	v_pk_mul_f32 v[102:103], v[82:83], 0.5 op_sel_hi:[1,0]
	v_pk_mul_f32 v[100:101], v[80:81], 0.5 op_sel_hi:[1,0]
	v_pk_mul_f32 v[98:99], v[70:71], 0.5 op_sel_hi:[1,0]
	v_pk_mul_f32 v[96:97], v[68:69], 0.5 op_sel_hi:[1,0]
	v_pk_mul_f32 v[94:95], v[66:67], 0.5 op_sel_hi:[1,0]
	v_pk_mul_f32 v[92:93], v[64:65], 0.5 op_sel_hi:[1,0]
	v_pk_mul_f32 v[86:87], v[62:63], 0.5 op_sel_hi:[1,0]
	v_pk_mul_f32 v[90:91], v[60:61], 0.5 op_sel_hi:[1,0]
	v_pk_mul_f32 v[84:85], v[58:59], 0.5 op_sel_hi:[1,0]
	v_pk_mul_f32 v[88:89], v[56:57], 0.5 op_sel_hi:[1,0]
	v_pk_mul_f32 v[80:81], v[46:47], 0.5 op_sel_hi:[1,0]
	v_pk_mul_f32 v[82:83], v[44:45], 0.5 op_sel_hi:[1,0]
	v_pk_mul_f32 v[78:79], v[38:39], 0.5 op_sel_hi:[1,0]
	v_pk_mul_f32 v[76:77], v[36:37], 0.5 op_sel_hi:[1,0]
	v_pk_mul_f32 v[74:75], v[54:55], 0.5 op_sel_hi:[1,0]
	v_pk_mul_f32 v[72:73], v[52:53], 0.5 op_sel_hi:[1,0]
	v_pk_mul_f32 v[70:71], v[50:51], 0.5 op_sel_hi:[1,0]
	v_pk_mul_f32 v[68:69], v[48:49], 0.5 op_sel_hi:[1,0]
	v_pk_mul_f32 v[66:67], v[30:31], 0.5 op_sel_hi:[1,0]
	v_pk_mul_f32 v[64:65], v[28:29], 0.5 op_sel_hi:[1,0]
	v_pk_mul_f32 v[62:63], v[22:23], 0.5 op_sel_hi:[1,0]
	v_pk_mul_f32 v[60:61], v[20:21], 0.5 op_sel_hi:[1,0]
	v_pk_mul_f32 v[58:59], v[42:43], 0.5 op_sel_hi:[1,0]
	v_pk_mul_f32 v[56:57], v[40:41], 0.5 op_sel_hi:[1,0]
	v_pk_mul_f32 v[54:55], v[34:35], 0.5 op_sel_hi:[1,0]
	v_pk_mul_f32 v[52:53], v[32:33], 0.5 op_sel_hi:[1,0]
	v_pk_mul_f32 v[50:51], v[14:15], 0.5 op_sel_hi:[1,0]
	v_pk_mul_f32 v[48:49], v[12:13], 0.5 op_sel_hi:[1,0]
	v_pk_mul_f32 v[46:47], v[10:11], 0.5 op_sel_hi:[1,0]
	v_pk_mul_f32 v[44:45], v[8:9], 0.5 op_sel_hi:[1,0]
	v_pk_mul_f32 v[42:43], v[26:27], 0.5 op_sel_hi:[1,0]
	v_pk_mul_f32 v[40:41], v[24:25], 0.5 op_sel_hi:[1,0]
	v_pk_mul_f32 v[38:39], v[18:19], 0.5 op_sel_hi:[1,0]
	v_pk_mul_f32 v[36:37], v[16:17], 0.5 op_sel_hi:[1,0]
	v_pk_mul_f32 v[34:35], v[6:7], 0.5 op_sel_hi:[1,0]
	v_pk_mul_f32 v[32:33], v[4:5], 0.5 op_sel_hi:[1,0]
	v_pk_mul_f32 v[30:31], v[2:3], 0.5 op_sel_hi:[1,0]
	v_pk_mul_f32 v[28:29], v[0:1], 0.5 op_sel_hi:[1,0]
	v_readlane_b32 s95, v252, 32

; template <class Epi, class Ord>
; __device__ __forceinline__ void gemm_phase(LAS unsigned char* lds, const Gemm g, const Ord& S, const Epi& E) {
;     ...
;             const bool last = (t == nt - 2);
;             const char* a1 = cA + (size_t)(t + 1) * kstep;
;             const char* a2 = last ? nA : cA + (size_t)(t + 2) * kstep; const char* b2 = last ? nB : cB + (size_t)(t + 2) * kstep;
;             const char* a3 = a2 + kstep; const char* b3 = b2 + kstep;
;     ...
;         for (int a = 0; a < 2; ++a)
; #pragma unroll
;             for (int b = 0; b < 2; ++b)
; #pragma unroll
;                 for (int m = 0; m < 4; ++m)
; #pragma unroll
;                     for (int n = 0; n < 2; ++n) acc[a][b][m][n] = (f32x4){0.f, 0.f, 0.f, 0.f};
;         cur = nxt; cA = nA; cB = nB; ++ui;
.LBB0_234:
	v_mov_b32_e32 v123, 0
	v_mov_b32_e32 v122, 0
	s_andn2_b64 vcc, exec, s[18:19]
	v_pk_mov_b32 v[120:121], v[122:123], v[122:123]
	v_pk_mov_b32 v[114:115], v[122:123], v[122:123]
	v_pk_mov_b32 v[112:113], v[122:123], v[122:123]
	v_pk_mov_b32 v[106:107], v[122:123], v[122:123]
	v_pk_mov_b32 v[104:105], v[122:123], v[122:123]
	v_pk_mov_b32 v[98:99], v[122:123], v[122:123]
	v_pk_mov_b32 v[96:97], v[122:123], v[122:123]
	v_pk_mov_b32 v[90:91], v[122:123], v[122:123]
	v_pk_mov_b32 v[88:89], v[122:123], v[122:123]
	v_pk_mov_b32 v[82:83], v[122:123], v[122:123]
	v_pk_mov_b32 v[80:81], v[122:123], v[122:123]
	v_pk_mov_b32 v[74:75], v[122:123], v[122:123]
	v_pk_mov_b32 v[72:73], v[122:123], v[122:123]
	v_pk_mov_b32 v[66:67], v[122:123], v[122:123]
	v_pk_mov_b32 v[64:65], v[122:123], v[122:123]
	v_pk_mov_b32 v[126:127], v[122:123], v[122:123]
	v_pk_mov_b32 v[124:125], v[122:123], v[122:123]
	v_pk_mov_b32 v[118:119], v[122:123], v[122:123]
	v_pk_mov_b32 v[116:117], v[122:123], v[122:123]
	v_pk_mov_b32 v[110:111], v[122:123], v[122:123]
	v_pk_mov_b32 v[108:109], v[122:123], v[122:123]
	v_pk_mov_b32 v[102:103], v[122:123], v[122:123]
	v_pk_mov_b32 v[100:101], v[122:123], v[122:123]
	v_pk_mov_b32 v[94:95], v[122:123], v[122:123]
	v_pk_mov_b32 v[92:93], v[122:123], v[122:123]
	v_pk_mov_b32 v[86:87], v[122:123], v[122:123]
	v_pk_mov_b32 v[84:85], v[122:123], v[122:123]
	v_pk_mov_b32 v[78:79], v[122:123], v[122:123]
	v_pk_mov_b32 v[76:77], v[122:123], v[122:123]
	v_pk_mov_b32 v[70:71], v[122:123], v[122:123]
	v_pk_mov_b32 v[68:69], v[122:123], v[122:123]
	v_pk_mov_b32 v[58:59], v[122:123], v[122:123]
	v_pk_mov_b32 v[56:57], v[122:123], v[122:123]
	v_pk_mov_b32 v[50:51], v[122:123], v[122:123]
	v_pk_mov_b32 v[48:49], v[122:123], v[122:123]
	v_pk_mov_b32 v[42:43], v[122:123], v[122:123]
	v_pk_mov_b32 v[40:41], v[122:123], v[122:123]
	v_pk_mov_b32 v[34:35], v[122:123], v[122:123]
	v_pk_mov_b32 v[32:33], v[122:123], v[122:123]
	v_pk_mov_b32 v[26:27], v[122:123], v[122:123]
	v_pk_mov_b32 v[24:25], v[122:123], v[122:123]
	v_pk_mov_b32 v[18:19], v[122:123], v[122:123]
	v_pk_mov_b32 v[16:17], v[122:123], v[122:123]
	v_pk_mov_b32 v[10:11], v[122:123], v[122:123]
	v_pk_mov_b32 v[8:9], v[122:123], v[122:123]
	v_pk_mov_b32 v[2:3], v[122:123], v[122:123]
	v_pk_mov_b32 v[0:1], v[122:123], v[122:123]
	v_pk_mov_b32 v[62:63], v[122:123], v[122:123]
	v_pk_mov_b32 v[60:61], v[122:123], v[122:123]
	v_pk_mov_b32 v[54:55], v[122:123], v[122:123]
	v_pk_mov_b32 v[52:53], v[122:123], v[122:123]
	v_pk_mov_b32 v[46:47], v[122:123], v[122:123]
	v_pk_mov_b32 v[44:45], v[122:123], v[122:123]
	v_pk_mov_b32 v[38:39], v[122:123], v[122:123]
	v_pk_mov_b32 v[36:37], v[122:123], v[122:123]
	v_pk_mov_b32 v[30:31], v[122:123], v[122:123]
	v_pk_mov_b32 v[28:29], v[122:123], v[122:123]
	v_pk_mov_b32 v[22:23], v[122:123], v[122:123]
	v_pk_mov_b32 v[20:21], v[122:123], v[122:123]
	v_pk_mov_b32 v[14:15], v[122:123], v[122:123]
	v_pk_mov_b32 v[12:13], v[122:123], v[122:123]
	v_pk_mov_b32 v[6:7], v[122:123], v[122:123]
	v_pk_mov_b32 v[4:5], v[122:123], v[122:123]
	s_cbranch_vccnz .LBB0_227
	s_add_u32 s46, s46, 0x100
	s_addc_u32 s47, s47, 0
	s_add_u32 s52, s52, 0x100
	v_mov_b32_e32 v4, 0
	v_mov_b32_e32 v5, 0
	s_addc_u32 s53, s53, 0
	s_mov_b32 s12, 0
	v_pk_mov_b32 v[6:7], v[4:5], v[4:5]
	v_pk_mov_b32 v[12:13], v[4:5], v[4:5]
	v_pk_mov_b32 v[14:15], v[4:5], v[4:5]
	v_pk_mov_b32 v[20:21], v[4:5], v[4:5]
	v_pk_mov_b32 v[22:23], v[4:5], v[4:5]
	v_pk_mov_b32 v[28:29], v[4:5], v[4:5]
	v_pk_mov_b32 v[30:31], v[4:5], v[4:5]
	v_pk_mov_b32 v[36:37], v[4:5], v[4:5]
	v_pk_mov_b32 v[38:39], v[4:5], v[4:5]
	v_pk_mov_b32 v[44:45], v[4:5], v[4:5]
	v_pk_mov_b32 v[46:47], v[4:5], v[4:5]
	v_pk_mov_b32 v[52:53], v[4:5], v[4:5]
	v_pk_mov_b32 v[54:55], v[4:5], v[4:5]
	v_pk_mov_b32 v[60:61], v[4:5], v[4:5]
	v_pk_mov_b32 v[62:63], v[4:5], v[4:5]
	v_pk_mov_b32 v[0:1], v[4:5], v[4:5]
	v_pk_mov_b32 v[2:3], v[4:5], v[4:5]
	v_pk_mov_b32 v[8:9], v[4:5], v[4:5]
	v_pk_mov_b32 v[10:11], v[4:5], v[4:5]
	v_pk_mov_b32 v[16:17], v[4:5], v[4:5]
	v_pk_mov_b32 v[18:19], v[4:5], v[4:5]
	v_pk_mov_b32 v[24:25], v[4:5], v[4:5]
	v_pk_mov_b32 v[26:27], v[4:5], v[4:5]
	v_pk_mov_b32 v[32:33], v[4:5], v[4:5]
	v_pk_mov_b32 v[34:35], v[4:5], v[4:5]
	v_pk_mov_b32 v[40:41], v[4:5], v[4:5]
	v_pk_mov_b32 v[42:43], v[4:5], v[4:5]
	v_pk_mov_b32 v[48:49], v[4:5], v[4:5]
	v_pk_mov_b32 v[50:51], v[4:5], v[4:5]
	v_pk_mov_b32 v[56:57], v[4:5], v[4:5]
	v_pk_mov_b32 v[58:59], v[4:5], v[4:5]
	v_pk_mov_b32 v[68:69], v[4:5], v[4:5]
	v_pk_mov_b32 v[70:71], v[4:5], v[4:5]
	v_pk_mov_b32 v[76:77], v[4:5], v[4:5]
	v_pk_mov_b32 v[78:79], v[4:5], v[4:5]
	v_pk_mov_b32 v[84:85], v[4:5], v[4:5]
	v_pk_mov_b32 v[86:87], v[4:5], v[4:5]
	v_pk_mov_b32 v[92:93], v[4:5], v[4:5]
	v_pk_mov_b32 v[94:95], v[4:5], v[4:5]
	v_pk_mov_b32 v[100:101], v[4:5], v[4:5]
	v_pk_mov_b32 v[102:103], v[4:5], v[4:5]
	v_pk_mov_b32 v[108:109], v[4:5], v[4:5]
	v_pk_mov_b32 v[110:111], v[4:5], v[4:5]
	v_pk_mov_b32 v[116:117], v[4:5], v[4:5]
	v_pk_mov_b32 v[118:119], v[4:5], v[4:5]
	v_pk_mov_b32 v[124:125], v[4:5], v[4:5]
	v_pk_mov_b32 v[126:127], v[4:5], v[4:5]
	v_pk_mov_b32 v[64:65], v[4:5], v[4:5]
	v_pk_mov_b32 v[66:67], v[4:5], v[4:5]
	v_pk_mov_b32 v[72:73], v[4:5], v[4:5]
	v_pk_mov_b32 v[74:75], v[4:5], v[4:5]
	v_pk_mov_b32 v[80:81], v[4:5], v[4:5]
	v_pk_mov_b32 v[82:83], v[4:5], v[4:5]
	v_pk_mov_b32 v[88:89], v[4:5], v[4:5]
	v_pk_mov_b32 v[90:91], v[4:5], v[4:5]
	v_pk_mov_b32 v[96:97], v[4:5], v[4:5]
	v_pk_mov_b32 v[98:99], v[4:5], v[4:5]
	v_pk_mov_b32 v[104:105], v[4:5], v[4:5]
	v_pk_mov_b32 v[106:107], v[4:5], v[4:5]
	v_pk_mov_b32 v[112:113], v[4:5], v[4:5]
	v_pk_mov_b32 v[114:115], v[4:5], v[4:5]
	v_pk_mov_b32 v[120:121], v[4:5], v[4:5]
	v_pk_mov_b32 v[122:123], v[4:5], v[4:5]
	s_add_i32 s80, s12, 2
	s_cmp_eq_u32 s73, s12
	s_cselect_b32 s22, s0, s52
	s_cselect_b32 s23, s1, s53
	s_cselect_b32 s20, s44, s46
	s_cselect_b32 s21, s45, s47
	s_add_u32 s12, s22, 0x80
	s_addc_u32 s13, s23, 0
	s_add_i32 s81, 0, 0x10000
	v_add_u32_e32 v152, s81, v133
; #define PG8_STAGE(bufoff, gbase, voff) do { const char* _gb = (const char*)(gbase); asm volatile("" : "+s"(_gb)); _Pragma("unroll") for (int _i = 0; _i < 2; ++_i) { unsigned _vo = (voff)[_i]; asm volatile("" : "+v"(_vo)); \
;         __builtin_amdgcn_global_load_lds((const GAS unsigned*)(_gb + _vo), (LAS unsigned*)(lds + (bufoff) + ldsw + _i * 8192), 16, 0, 0); } } while (0)
; #define PG8_LDA(dst, b, h) do { _Pragma("unroll") for (int m = 0; m < 4; ++m) _Pragma("unroll") for (int k = 0; k < 2; ++k) dst[m][k] = *(const LAS bf16x8*)(lds + PG8_SA(b, h) + aoff + m * 2048 + k * 1024); } while (0)
; #define PG8_LDB(dst, b, h) do { _Pragma("unroll") for (int n = 0; n < 2; ++n) _Pragma("unroll") for (int k = 0; k < 2; ++k) dst[n][k] = *(const LAS bf16x8*)(lds + PG8_SB(b, h) + boff + n * 2048 + k * 1024); } while (0)
; #define PG8_MMA(ai, bj, At, Bt) do { __builtin_amdgcn_s_setprio(1); _Pragma("unroll") for (int m = 0; m < 4; ++m) _Pragma("unroll") for (int n = 0; n < 2; ++n) _Pragma("unroll") for (int k = 0; k < 2; ++k) \
;         acc[ai][bj][m][n] = __builtin_amdgcn_mfma_f32_16x16x32_bf16(Bt[n][k], At[m][k], acc[ai][bj][m][n], 0, 0, 0); __builtin_amdgcn_s_setprio(0); } while (0)
; #define PG8_WAIT_L(n) asm volatile("s_waitcnt lgkmcnt(" #n ")" ::: "memory")
; #define PG8_BAR __builtin_amdgcn_s_barrier()
; #define PG8_SCHED __builtin_amdgcn_sched_barrier(0)
; template <class Epi, class Ord>
; __device__ __forceinline__ void gemm_phase(LAS unsigned char* lds, const Gemm g, const Ord& S, const Epi& E) {
;     ...
;             PG8_LDB(B0, 0, 0); PG8_SCHED; PG8_LDA(At, 0, 0); PG8_STAGE(PG8_SA(1, 1), a1 + hstep, voffA);
;             PG8_WAIT_L(8); PG8_BAR; PG8_WAIT_L(0); PG8_MMA(0, 0, At, B0); PG8_BAR; PG8_SCHED;
;             PG8_LDB(B1, 0, 1); PG8_STAGE(PG8_SB(0, 0), b2, voffB);
;             PG8_BAR; PG8_WAIT_L(0); PG8_MMA(0, 1, At, B1); PG8_BAR;
;             PG8_LDA(At, 0, 1); PG8_STAGE(PG8_SA(0, 0), a2, voffA);
;             PG8_BAR; PG8_WAIT_L(0); PG8_MMA(1, 0, At, B0); PG8_BAR; PG8_SCHED;
.LBB0_236:
	ds_read_b128 v[140:143], v152
	ds_read_b128 v[144:147], v152 offset:1024
	ds_read_b128 v[148:151], v152 offset:2048
	ds_read_b128 v[152:155], v152 offset:3072
	s_add_u32 s24, s52, s10
	s_addc_u32 s25, s53, s11
	s_add_u32 s24, s24, 0xffffff80
	s_addc_u32 s25, s25, -1
	v_mov_b32_e32 v168, v128
	ds_read_b128 v[156:159], v139
	ds_read_b128 v[192:195], v139 offset:1024
	ds_read_b128 v[196:199], v139 offset:2048
	ds_read_b128 v[200:203], v139 offset:3072
	ds_read_b128 v[204:207], v139 offset:4096
	ds_read_b128 v[212:215], v139 offset:5120
	ds_read_b128 v[216:219], v139 offset:6144
	ds_read_b128 v[220:223], v139 offset:7168
	s_add_i32 m0, s64, 0xc000
	s_nop 0
	global_load_lds_dwordx4 v168, s[24:25]
	v_mov_b32_e32 v168, v130
	s_add_i32 m0, s64, 0xe000
	s_nop 0
	global_load_lds_dwordx4 v168, s[24:25]
	s_waitcnt lgkmcnt(8)
	s_barrier
	s_waitcnt lgkmcnt(0)
	s_setprio 1
	s_waitcnt lgkmcnt(0)
	v_mfma_f32_16x16x32_bf16 v[120:123], v[140:143], v[156:159], v[120:123]
	v_mfma_f32_16x16x32_bf16 v[112:115], v[148:151], v[156:159], v[112:115]
	v_mfma_f32_16x16x32_bf16 v[104:107], v[140:143], v[196:199], v[104:107]
	v_mfma_f32_16x16x32_bf16 v[96:99], v[148:151], v[196:199], v[96:99]
	v_mfma_f32_16x16x32_bf16 v[88:91], v[140:143], v[204:207], v[88:91]
	v_mfma_f32_16x16x32_bf16 v[80:83], v[148:151], v[204:207], v[80:83]
	v_mfma_f32_16x16x32_bf16 v[72:75], v[140:143], v[216:219], v[72:75]
	v_mfma_f32_16x16x32_bf16 v[64:67], v[148:151], v[216:219], v[64:67]
	v_mfma_f32_16x16x32_bf16 v[120:123], v[144:147], v[192:195], v[120:123]
	v_mfma_f32_16x16x32_bf16 v[112:115], v[152:155], v[192:195], v[112:115]
	v_mfma_f32_16x16x32_bf16 v[104:107], v[144:147], v[200:203], v[104:107]
	v_mfma_f32_16x16x32_bf16 v[96:99], v[152:155], v[200:203], v[96:99]
	v_mfma_f32_16x16x32_bf16 v[88:91], v[144:147], v[212:215], v[88:91]
	v_mfma_f32_16x16x32_bf16 v[80:83], v[152:155], v[212:215], v[80:83]
	v_mfma_f32_16x16x32_bf16 v[72:75], v[144:147], v[220:223], v[72:75]
	v_mfma_f32_16x16x32_bf16 v[64:67], v[152:155], v[220:223], v[64:67]
	s_setprio 0
	s_barrier
	s_add_i32 s84, 0, 0x14000
	v_add_u32_e32 v168, s84, v133
	ds_read_b128 v[224:227], v168
	ds_read_b128 v[228:231], v168 offset:1024
	ds_read_b128 v[232:235], v168 offset:2048
	ds_read_b128 v[236:239], v168 offset:3072
	s_mov_b64 s[24:25], s[20:21]
	v_mov_b32_e32 v168, v129
	s_add_i32 s81, s81, s57
	s_mov_b32 m0, s81
	s_nop 0
	global_load_lds_dwordx4 v168, s[24:25]
	v_mov_b32_e32 v168, v131
	s_add_i32 m0, s81, 0x2000
	s_nop 0
	global_load_lds_dwordx4 v168, s[24:25]
	s_barrier
	s_waitcnt lgkmcnt(0)
	s_setprio 1
	s_waitcnt lgkmcnt(0)
	v_mfma_f32_16x16x32_bf16 v[124:127], v[224:227], v[156:159], v[124:127]
	v_mfma_f32_16x16x32_bf16 v[116:119], v[232:235], v[156:159], v[116:119]
	v_mfma_f32_16x16x32_bf16 v[108:111], v[224:227], v[196:199], v[108:111]
	v_mfma_f32_16x16x32_bf16 v[100:103], v[232:235], v[196:199], v[100:103]
	v_mfma_f32_16x16x32_bf16 v[92:95], v[224:227], v[204:207], v[92:95]
	v_mfma_f32_16x16x32_bf16 v[84:87], v[232:235], v[204:207], v[84:87]
	v_mfma_f32_16x16x32_bf16 v[76:79], v[224:227], v[216:219], v[76:79]
	v_mfma_f32_16x16x32_bf16 v[68:71], v[232:235], v[216:219], v[68:71]
	v_mfma_f32_16x16x32_bf16 v[124:127], v[228:231], v[192:195], v[124:127]
	v_mfma_f32_16x16x32_bf16 v[116:119], v[236:239], v[192:195], v[116:119]
	v_mfma_f32_16x16x32_bf16 v[108:111], v[228:231], v[200:203], v[108:111]
	v_mfma_f32_16x16x32_bf16 v[100:103], v[236:239], v[200:203], v[100:103]
	v_mfma_f32_16x16x32_bf16 v[92:95], v[228:231], v[212:215], v[92:95]
	v_mfma_f32_16x16x32_bf16 v[84:87], v[236:239], v[212:215], v[84:87]
	v_mfma_f32_16x16x32_bf16 v[76:79], v[228:231], v[220:223], v[76:79]
	v_mfma_f32_16x16x32_bf16 v[68:71], v[236:239], v[220:223], v[68:71]
	s_setprio 0
	s_mov_b64 s[24:25], s[22:23]
	v_mov_b32_e32 v168, v128
	s_mov_b32 m0, s64
	s_barrier
	ds_read_b128 v[156:159], v139 offset:16384
	ds_read_b128 v[192:195], v139 offset:17408
	ds_read_b128 v[196:199], v139 offset:18432
	ds_read_b128 v[200:203], v139 offset:19456
	ds_read_b128 v[204:207], v139 offset:20480
	ds_read_b128 v[212:215], v139 offset:21504
	ds_read_b128 v[216:219], v139 offset:22528
	ds_read_b128 v[220:223], v139 offset:23552
	s_nop 0
	global_load_lds_dwordx4 v168, s[24:25]
	v_mov_b32_e32 v168, v130
	s_mov_b32 m0, s65
	s_nop 0
	global_load_lds_dwordx4 v168, s[24:25]
	s_barrier
	s_waitcnt lgkmcnt(0)
	s_setprio 1
	s_waitcnt lgkmcnt(0)
	v_mfma_f32_16x16x32_bf16 v[56:59], v[140:143], v[156:159], v[56:59]
	v_mfma_f32_16x16x32_bf16 v[48:51], v[148:151], v[156:159], v[48:51]
	v_mfma_f32_16x16x32_bf16 v[40:43], v[140:143], v[196:199], v[40:43]
	v_mfma_f32_16x16x32_bf16 v[32:35], v[148:151], v[196:199], v[32:35]
	v_mfma_f32_16x16x32_bf16 v[24:27], v[140:143], v[204:207], v[24:27]
	v_mfma_f32_16x16x32_bf16 v[16:19], v[148:151], v[204:207], v[16:19]
	v_mfma_f32_16x16x32_bf16 v[8:11], v[140:143], v[216:219], v[8:11]
	v_mfma_f32_16x16x32_bf16 v[0:3], v[148:151], v[216:219], v[0:3]
	v_mfma_f32_16x16x32_bf16 v[56:59], v[144:147], v[192:195], v[56:59]
	v_mfma_f32_16x16x32_bf16 v[48:51], v[152:155], v[192:195], v[48:51]
	v_mfma_f32_16x16x32_bf16 v[40:43], v[144:147], v[200:203], v[40:43]
	v_mfma_f32_16x16x32_bf16 v[32:35], v[152:155], v[200:203], v[32:35]
	v_mfma_f32_16x16x32_bf16 v[24:27], v[144:147], v[212:215], v[24:27]
	v_mfma_f32_16x16x32_bf16 v[16:19], v[152:155], v[212:215], v[16:19]
	v_mfma_f32_16x16x32_bf16 v[8:11], v[144:147], v[220:223], v[8:11]
	v_mfma_f32_16x16x32_bf16 v[0:3], v[152:155], v[220:223], v[0:3]
	s_setprio 0
	s_barrier
; #define PG8_STAGE(bufoff, gbase, voff) do { const char* _gb = (const char*)(gbase); asm volatile("" : "+s"(_gb)); _Pragma("unroll") for (int _i = 0; _i < 2; ++_i) { unsigned _vo = (voff)[_i]; asm volatile("" : "+v"(_vo)); \
;         __builtin_amdgcn_global_load_lds((const GAS unsigned*)(_gb + _vo), (LAS unsigned*)(lds + (bufoff) + ldsw + _i * 8192), 16, 0, 0); } } while (0)
; #define PG8_LDA(dst, b, h) do { _Pragma("unroll") for (int m = 0; m < 4; ++m) _Pragma("unroll") for (int k = 0; k < 2; ++k) dst[m][k] = *(const LAS bf16x8*)(lds + PG8_SA(b, h) + aoff + m * 2048 + k * 1024); } while (0)
; #define PG8_LDB(dst, b, h) do { _Pragma("unroll") for (int n = 0; n < 2; ++n) _Pragma("unroll") for (int k = 0; k < 2; ++k) dst[n][k] = *(const LAS bf16x8*)(lds + PG8_SB(b, h) + boff + n * 2048 + k * 1024); } while (0)
; #define PG8_MMA(ai, bj, At, Bt) do { __builtin_amdgcn_s_setprio(1); _Pragma("unroll") for (int m = 0; m < 4; ++m) _Pragma("unroll") for (int n = 0; n < 2; ++n) _Pragma("unroll") for (int k = 0; k < 2; ++k) \
;         acc[ai][bj][m][n] = __builtin_amdgcn_mfma_f32_16x16x32_bf16(Bt[n][k], At[m][k], acc[ai][bj][m][n], 0, 0, 0); __builtin_amdgcn_s_setprio(0); } while (0)
; #define PG8_WAIT_V(n) asm volatile("s_waitcnt vmcnt(" #n ")" ::: "memory")
; #define PG8_WAIT_L(n) asm volatile("s_waitcnt lgkmcnt(" #n ")" ::: "memory")
; #define PG8_BAR __builtin_amdgcn_s_barrier()
; #define PG8_SCHED __builtin_amdgcn_sched_barrier(0)
; template <class Epi, class Ord>
; __device__ __forceinline__ void gemm_phase(LAS unsigned char* lds, const Gemm g, const Ord& S, const Epi& E) {
;     ...
;             PG8_STAGE(PG8_SB(0, 1), b2 + hstep, voffB);
;             PG8_WAIT_V(6); PG8_BAR; PG8_MMA(1, 1, At, B1); PG8_BAR;
;             PG8_LDB(B0, 1, 0); PG8_SCHED; PG8_LDA(At, 1, 0); PG8_STAGE(PG8_SA(0, 1), a2 + hstep, voffA);
;             PG8_WAIT_L(8); PG8_BAR; PG8_WAIT_L(0); PG8_MMA(0, 0, At, B0); PG8_BAR; PG8_SCHED;
;             PG8_LDB(B1, 1, 1); PG8_STAGE(PG8_SB(1, 0), b3, voffB);
	s_add_u32 s24, s20, s10
	s_addc_u32 s25, s21, s11
	s_mov_b64 s[82:83], s[24:25]
	v_mov_b32_e32 v140, v129
	s_add_i32 s81, s84, s57
	s_mov_b32 m0, s81
	s_nop 0
	global_load_lds_dwordx4 v140, s[82:83]
	v_mov_b32_e32 v140, v131
	s_add_i32 m0, s81, 0x2000
	s_nop 0
	global_load_lds_dwordx4 v140, s[82:83]
	s_waitcnt vmcnt(6)
	s_barrier
	s_setprio 1
	v_mfma_f32_16x16x32_bf16 v[60:63], v[224:227], v[156:159], v[60:63]
	v_mfma_f32_16x16x32_bf16 v[52:55], v[232:235], v[156:159], v[52:55]
	v_mfma_f32_16x16x32_bf16 v[44:47], v[224:227], v[196:199], v[44:47]
	v_mfma_f32_16x16x32_bf16 v[36:39], v[232:235], v[196:199], v[36:39]
	v_mfma_f32_16x16x32_bf16 v[28:31], v[224:227], v[204:207], v[28:31]
	v_mfma_f32_16x16x32_bf16 v[20:23], v[232:235], v[204:207], v[20:23]
	v_mfma_f32_16x16x32_bf16 v[12:15], v[224:227], v[216:219], v[12:15]
	v_mfma_f32_16x16x32_bf16 v[4:7], v[232:235], v[216:219], v[4:7]
	v_mfma_f32_16x16x32_bf16 v[60:63], v[228:231], v[192:195], v[60:63]
	v_mfma_f32_16x16x32_bf16 v[52:55], v[236:239], v[192:195], v[52:55]
	v_mfma_f32_16x16x32_bf16 v[44:47], v[228:231], v[200:203], v[44:47]
	v_mfma_f32_16x16x32_bf16 v[36:39], v[236:239], v[200:203], v[36:39]
	v_mfma_f32_16x16x32_bf16 v[28:31], v[228:231], v[212:215], v[28:31]
	v_mfma_f32_16x16x32_bf16 v[20:23], v[236:239], v[212:215], v[20:23]
	v_mfma_f32_16x16x32_bf16 v[12:15], v[228:231], v[220:223], v[12:15]
	v_mfma_f32_16x16x32_bf16 v[4:7], v[236:239], v[220:223], v[4:7]
	s_setprio 0
	s_add_i32 s81, 0, 0x18000
	v_add_u32_e32 v152, s81, v133
	s_barrier
	ds_read_b128 v[140:143], v152
	ds_read_b128 v[144:147], v152 offset:1024
	ds_read_b128 v[148:151], v152 offset:2048
	ds_read_b128 v[152:155], v152 offset:3072
	s_add_u32 s22, s22, s10
	s_addc_u32 s23, s23, s11
	v_mov_b32_e32 v168, v128
	s_mov_b32 m0, s68
	ds_read_b128 v[156:159], v139 offset:32768
	ds_read_b128 v[192:195], v139 offset:33792
	ds_read_b128 v[196:199], v139 offset:34816
	ds_read_b128 v[200:203], v139 offset:35840
	ds_read_b128 v[204:207], v139 offset:36864
	ds_read_b128 v[212:215], v139 offset:37888
	ds_read_b128 v[216:219], v139 offset:38912
	ds_read_b128 v[220:223], v139 offset:39936
	s_nop 0
	global_load_lds_dwordx4 v168, s[22:23]
	v_mov_b32_e32 v168, v130
	s_mov_b32 m0, s69
	s_nop 0
	global_load_lds_dwordx4 v168, s[22:23]
	s_waitcnt lgkmcnt(8)
	s_barrier
	s_waitcnt lgkmcnt(0)
	s_setprio 1
	s_waitcnt lgkmcnt(0)
	v_mfma_f32_16x16x32_bf16 v[120:123], v[140:143], v[156:159], v[120:123]
	v_mfma_f32_16x16x32_bf16 v[112:115], v[148:151], v[156:159], v[112:115]
	v_mfma_f32_16x16x32_bf16 v[104:107], v[140:143], v[196:199], v[104:107]
	v_mfma_f32_16x16x32_bf16 v[96:99], v[148:151], v[196:199], v[96:99]
	v_mfma_f32_16x16x32_bf16 v[88:91], v[140:143], v[204:207], v[88:91]
	v_mfma_f32_16x16x32_bf16 v[80:83], v[148:151], v[204:207], v[80:83]
	v_mfma_f32_16x16x32_bf16 v[72:75], v[140:143], v[216:219], v[72:75]
	v_mfma_f32_16x16x32_bf16 v[64:67], v[148:151], v[216:219], v[64:67]
	v_mfma_f32_16x16x32_bf16 v[120:123], v[144:147], v[192:195], v[120:123]
	v_mfma_f32_16x16x32_bf16 v[112:115], v[152:155], v[192:195], v[112:115]
	v_mfma_f32_16x16x32_bf16 v[104:107], v[144:147], v[200:203], v[104:107]
	v_mfma_f32_16x16x32_bf16 v[96:99], v[152:155], v[200:203], v[96:99]
	v_mfma_f32_16x16x32_bf16 v[88:91], v[144:147], v[212:215], v[88:91]
	v_mfma_f32_16x16x32_bf16 v[80:83], v[152:155], v[212:215], v[80:83]
	v_mfma_f32_16x16x32_bf16 v[72:75], v[144:147], v[220:223], v[72:75]
	v_mfma_f32_16x16x32_bf16 v[64:67], v[152:155], v[220:223], v[64:67]
	s_setprio 0
	s_barrier
	s_add_i32 s22, 0, 0x1c000
	v_add_u32_e32 v168, s22, v133
	s_add_u32 s20, s20, 0x80
	ds_read_b128 v[224:227], v168
	ds_read_b128 v[228:231], v168 offset:1024
	ds_read_b128 v[232:235], v168 offset:2048
	ds_read_b128 v[236:239], v168 offset:3072
	s_addc_u32 s21, s21, 0
	v_mov_b32_e32 v168, v129
	s_add_i32 s23, s81, s57
	s_mov_b32 m0, s23
	s_nop 0
	global_load_lds_dwordx4 v168, s[20:21]
	v_mov_b32_e32 v168, v131
	s_add_i32 m0, s23, 0x2000
	s_nop 0
	global_load_lds_dwordx4 v168, s[20:21]
	s_barrier
; #define PG8_STAGE(bufoff, gbase, voff) do { const char* _gb = (const char*)(gbase); asm volatile("" : "+s"(_gb)); _Pragma("unroll") for (int _i = 0; _i < 2; ++_i) { unsigned _vo = (voff)[_i]; asm volatile("" : "+v"(_vo)); \
;         __builtin_amdgcn_global_load_lds((const GAS unsigned*)(_gb + _vo), (LAS unsigned*)(lds + (bufoff) + ldsw + _i * 8192), 16, 0, 0); } } while (0)
; #define PG8_LDA(dst, b, h) do { _Pragma("unroll") for (int m = 0; m < 4; ++m) _Pragma("unroll") for (int k = 0; k < 2; ++k) dst[m][k] = *(const LAS bf16x8*)(lds + PG8_SA(b, h) + aoff + m * 2048 + k * 1024); } while (0)
; #define PG8_MMA(ai, bj, At, Bt) do { __builtin_amdgcn_s_setprio(1); _Pragma("unroll") for (int m = 0; m < 4; ++m) _Pragma("unroll") for (int n = 0; n < 2; ++n) _Pragma("unroll") for (int k = 0; k < 2; ++k) \
;         acc[ai][bj][m][n] = __builtin_amdgcn_mfma_f32_16x16x32_bf16(Bt[n][k], At[m][k], acc[ai][bj][m][n], 0, 0, 0); __builtin_amdgcn_s_setprio(0); } while (0)
; #define PG8_WAIT_V(n) asm volatile("s_waitcnt vmcnt(" #n ")" ::: "memory")
; #define PG8_WAIT_L(n) asm volatile("s_waitcnt lgkmcnt(" #n ")" ::: "memory")
; #define PG8_BAR __builtin_amdgcn_s_barrier()
; #define PG8_SCHED __builtin_amdgcn_sched_barrier(0)
; template <class Epi, class Ord>
; __device__ __forceinline__ void gemm_phase(LAS unsigned char* lds, const Gemm g, const Ord& S, const Epi& E) {
;     ...
;             PG8_BAR; PG8_WAIT_L(0); PG8_MMA(0, 1, At, B1); PG8_BAR;
;             PG8_LDA(At, 1, 1); PG8_STAGE(PG8_SA(1, 0), a3, voffA);
;             PG8_BAR; PG8_WAIT_L(0); PG8_MMA(1, 0, At, B0); PG8_BAR; PG8_SCHED;
;             PG8_STAGE(PG8_SB(1, 1), b3 + hstep, voffB);
;             PG8_WAIT_V(6); PG8_BAR; PG8_MMA(1, 1, At, B1); PG8_BAR;
;         }
	s_waitcnt lgkmcnt(0)
	s_setprio 1
	s_waitcnt lgkmcnt(0)
	v_mfma_f32_16x16x32_bf16 v[124:127], v[224:227], v[156:159], v[124:127]
	v_mfma_f32_16x16x32_bf16 v[116:119], v[232:235], v[156:159], v[116:119]
	v_mfma_f32_16x16x32_bf16 v[108:111], v[224:227], v[196:199], v[108:111]
	v_mfma_f32_16x16x32_bf16 v[100:103], v[232:235], v[196:199], v[100:103]
	v_mfma_f32_16x16x32_bf16 v[92:95], v[224:227], v[204:207], v[92:95]
	v_mfma_f32_16x16x32_bf16 v[84:87], v[232:235], v[204:207], v[84:87]
	v_mfma_f32_16x16x32_bf16 v[76:79], v[224:227], v[216:219], v[76:79]
	v_mfma_f32_16x16x32_bf16 v[68:71], v[232:235], v[216:219], v[68:71]
	v_mfma_f32_16x16x32_bf16 v[124:127], v[228:231], v[192:195], v[124:127]
	v_mfma_f32_16x16x32_bf16 v[116:119], v[236:239], v[192:195], v[116:119]
	v_mfma_f32_16x16x32_bf16 v[108:111], v[228:231], v[200:203], v[108:111]
	v_mfma_f32_16x16x32_bf16 v[100:103], v[236:239], v[200:203], v[100:103]
	v_mfma_f32_16x16x32_bf16 v[92:95], v[228:231], v[212:215], v[92:95]
	v_mfma_f32_16x16x32_bf16 v[84:87], v[236:239], v[212:215], v[84:87]
	v_mfma_f32_16x16x32_bf16 v[76:79], v[228:231], v[220:223], v[76:79]
	v_mfma_f32_16x16x32_bf16 v[68:71], v[236:239], v[220:223], v[68:71]
	s_setprio 0
	v_mov_b32_e32 v168, v128
	s_mov_b32 m0, s71
	s_barrier
	ds_read_b128 v[156:159], v139 offset:49152
	ds_read_b128 v[192:195], v139 offset:50176
	ds_read_b128 v[196:199], v139 offset:51200
	ds_read_b128 v[200:203], v139 offset:52224
	ds_read_b128 v[204:207], v139 offset:53248
	ds_read_b128 v[212:215], v139 offset:54272
	ds_read_b128 v[216:219], v139 offset:55296
	ds_read_b128 v[220:223], v139 offset:56320
	s_nop 0
	global_load_lds_dwordx4 v168, s[12:13]
	v_mov_b32_e32 v168, v130
	s_mov_b32 m0, s72
	s_nop 0
	global_load_lds_dwordx4 v168, s[12:13]
	s_barrier
	s_waitcnt lgkmcnt(0)
	s_setprio 1
	s_waitcnt lgkmcnt(0)
	v_mfma_f32_16x16x32_bf16 v[56:59], v[140:143], v[156:159], v[56:59]
	v_mfma_f32_16x16x32_bf16 v[48:51], v[148:151], v[156:159], v[48:51]
	v_mfma_f32_16x16x32_bf16 v[40:43], v[140:143], v[196:199], v[40:43]
	v_mfma_f32_16x16x32_bf16 v[32:35], v[148:151], v[196:199], v[32:35]
	v_mfma_f32_16x16x32_bf16 v[24:27], v[140:143], v[204:207], v[24:27]
	v_mfma_f32_16x16x32_bf16 v[16:19], v[148:151], v[204:207], v[16:19]
	v_mfma_f32_16x16x32_bf16 v[8:11], v[140:143], v[216:219], v[8:11]
	v_mfma_f32_16x16x32_bf16 v[0:3], v[148:151], v[216:219], v[0:3]
	v_mfma_f32_16x16x32_bf16 v[56:59], v[144:147], v[192:195], v[56:59]
	v_mfma_f32_16x16x32_bf16 v[48:51], v[152:155], v[192:195], v[48:51]
	v_mfma_f32_16x16x32_bf16 v[40:43], v[144:147], v[200:203], v[40:43]
	v_mfma_f32_16x16x32_bf16 v[32:35], v[152:155], v[200:203], v[32:35]
	v_mfma_f32_16x16x32_bf16 v[24:27], v[144:147], v[212:215], v[24:27]
	v_mfma_f32_16x16x32_bf16 v[16:19], v[152:155], v[212:215], v[16:19]
	v_mfma_f32_16x16x32_bf16 v[8:11], v[144:147], v[220:223], v[8:11]
	v_mfma_f32_16x16x32_bf16 v[0:3], v[152:155], v[220:223], v[0:3]
	s_setprio 0
	s_barrier
	s_add_u32 s12, s24, 0x80
	s_addc_u32 s13, s25, 0
	v_mov_b32_e32 v140, v129
	s_add_i32 s20, s22, s57
	s_mov_b32 m0, s20
	s_nop 0
	global_load_lds_dwordx4 v140, s[12:13]
	v_mov_b32_e32 v140, v131
	s_add_i32 m0, s20, 0x2000
	s_nop 0
	global_load_lds_dwordx4 v140, s[12:13]
	s_waitcnt vmcnt(6)
	s_barrier
	s_setprio 1
	v_mfma_f32_16x16x32_bf16 v[60:63], v[224:227], v[156:159], v[60:63]
	v_mfma_f32_16x16x32_bf16 v[52:55], v[232:235], v[156:159], v[52:55]
	v_mfma_f32_16x16x32_bf16 v[44:47], v[224:227], v[196:199], v[44:47]
	v_mfma_f32_16x16x32_bf16 v[36:39], v[232:235], v[196:199], v[36:39]
	v_mfma_f32_16x16x32_bf16 v[28:31], v[224:227], v[204:207], v[28:31]
	v_mfma_f32_16x16x32_bf16 v[20:23], v[232:235], v[204:207], v[20:23]
	v_mfma_f32_16x16x32_bf16 v[12:15], v[224:227], v[216:219], v[12:15]
	v_mfma_f32_16x16x32_bf16 v[4:7], v[232:235], v[216:219], v[4:7]
	v_mfma_f32_16x16x32_bf16 v[60:63], v[228:231], v[192:195], v[60:63]
	v_mfma_f32_16x16x32_bf16 v[52:55], v[236:239], v[192:195], v[52:55]
	v_mfma_f32_16x16x32_bf16 v[44:47], v[228:231], v[200:203], v[44:47]
	v_mfma_f32_16x16x32_bf16 v[36:39], v[236:239], v[200:203], v[36:39]
	v_mfma_f32_16x16x32_bf16 v[28:31], v[228:231], v[212:215], v[28:31]
	v_mfma_f32_16x16x32_bf16 v[20:23], v[236:239], v[212:215], v[20:23]
	v_mfma_f32_16x16x32_bf16 v[12:15], v[228:231], v[220:223], v[12:15]
	v_mfma_f32_16x16x32_bf16 v[4:7], v[236:239], v[220:223], v[4:7]
	s_setprio 0
	s_add_u32 s46, s46, 0x100
	s_addc_u32 s47, s47, 0
	s_add_u32 s52, s52, 0x100
	s_addc_u32 s53, s53, 0
	s_mov_b32 s12, s80
	s_add_i32 s80, s12, 2
	s_cmp_eq_u32 s73, s12
	s_cselect_b32 s22, s0, s52
	s_cselect_b32 s23, s1, s53
	s_cselect_b32 s20, s44, s46
	s_cselect_b32 s21, s45, s47
	s_add_u32 s12, s22, 0x80
	s_addc_u32 s13, s23, 0
	s_add_i32 s81, 0, 0x10000
	v_add_u32_e32 v152, s81, v133
	s_sub_i32 s98, s80, 2
	s_cmp_ge_i32 s98, s70
	s_barrier
	s_cbranch_scc0 .LBB0_236
	s_branch .LBB0_227

; template <class Epi, class Ord>
; __device__ __forceinline__ void gemm_phase(LAS unsigned char* lds, const Gemm g, const Ord& S, const Epi& E) {
;     ...
;             const bool last = (t == nt - 2);
;             const char* a1 = cA + (size_t)(t + 1) * kstep;
;             const char* a2 = last ? nA : cA + (size_t)(t + 2) * kstep; const char* b2 = last ? nB : cB + (size_t)(t + 2) * kstep;
;             const char* a3 = a2 + kstep; const char* b3 = b2 + kstep;
;     ...
;         for (int a = 0; a < 2; ++a)
; #pragma unroll
;             for (int b = 0; b < 2; ++b)
; #pragma unroll
;                 for (int m = 0; m < 4; ++m)
; #pragma unroll
;                     for (int n = 0; n < 2; ++n) acc[a][b][m][n] = (f32x4){0.f, 0.f, 0.f, 0.f};
;         cur = nxt; cA = nA; cB = nB; ++ui;
.LBB0_267:
	v_mov_b32_e32 v127, 0
	s_andn2_b64 vcc, exec, s[16:17]
	v_mov_b32_e32 v126, v127
	v_mov_b32_e32 v125, v127
	v_mov_b32_e32 v124, v127
	v_mov_b32_e32 v123, v127
	v_mov_b32_e32 v122, v127
	v_mov_b32_e32 v121, v127
	v_mov_b32_e32 v120, v127
	v_mov_b32_e32 v111, v127
	v_mov_b32_e32 v110, v127
	v_mov_b32_e32 v109, v127
	v_mov_b32_e32 v108, v127
	v_mov_b32_e32 v107, v127
	v_mov_b32_e32 v106, v127
	v_mov_b32_e32 v105, v127
	v_mov_b32_e32 v104, v127
	v_mov_b32_e32 v95, v127
	v_mov_b32_e32 v94, v127
	v_mov_b32_e32 v93, v127
	v_mov_b32_e32 v92, v127
	v_mov_b32_e32 v91, v127
	v_mov_b32_e32 v90, v127
	v_mov_b32_e32 v89, v127
	v_mov_b32_e32 v88, v127
	v_mov_b32_e32 v79, v127
	v_mov_b32_e32 v78, v127
	v_mov_b32_e32 v77, v127
	v_mov_b32_e32 v76, v127
	v_mov_b32_e32 v75, v127
	v_mov_b32_e32 v74, v127
	v_mov_b32_e32 v73, v127
	v_mov_b32_e32 v72, v127
	v_mov_b32_e32 v119, v127
	v_mov_b32_e32 v118, v127
	v_mov_b32_e32 v117, v127
	v_mov_b32_e32 v116, v127
	v_mov_b32_e32 v115, v127
	v_mov_b32_e32 v114, v127
	v_mov_b32_e32 v113, v127
	v_mov_b32_e32 v112, v127
	v_mov_b32_e32 v103, v127
	v_mov_b32_e32 v102, v127
	v_mov_b32_e32 v101, v127
	v_mov_b32_e32 v100, v127
	v_mov_b32_e32 v99, v127
	v_mov_b32_e32 v98, v127
	v_mov_b32_e32 v97, v127
	v_mov_b32_e32 v96, v127
	v_mov_b32_e32 v87, v127
	v_mov_b32_e32 v86, v127
	v_mov_b32_e32 v85, v127
	v_mov_b32_e32 v84, v127
	v_mov_b32_e32 v83, v127
	v_mov_b32_e32 v82, v127
	v_mov_b32_e32 v81, v127
	v_mov_b32_e32 v80, v127
	v_mov_b32_e32 v71, v127
	v_mov_b32_e32 v70, v127
	v_mov_b32_e32 v69, v127
	v_mov_b32_e32 v68, v127
	v_mov_b32_e32 v67, v127
	v_mov_b32_e32 v66, v127
	v_mov_b32_e32 v65, v127
	v_mov_b32_e32 v64, v127
	v_mov_b32_e32 v63, v127
	v_mov_b32_e32 v62, v127
	v_mov_b32_e32 v61, v127
	v_mov_b32_e32 v60, v127
	v_mov_b32_e32 v59, v127
	v_mov_b32_e32 v58, v127
	v_mov_b32_e32 v57, v127
	v_mov_b32_e32 v56, v127
	v_mov_b32_e32 v47, v127
	v_mov_b32_e32 v46, v127
	v_mov_b32_e32 v45, v127
	v_mov_b32_e32 v44, v127
	v_mov_b32_e32 v43, v127
	v_mov_b32_e32 v42, v127
	v_mov_b32_e32 v41, v127
	v_mov_b32_e32 v40, v127
	v_mov_b32_e32 v31, v127
	v_mov_b32_e32 v30, v127
	v_mov_b32_e32 v29, v127
	v_mov_b32_e32 v28, v127
	v_mov_b32_e32 v27, v127
	v_mov_b32_e32 v26, v127
	v_mov_b32_e32 v25, v127
	v_mov_b32_e32 v24, v127
	v_mov_b32_e32 v15, v127
	v_mov_b32_e32 v14, v127
	v_mov_b32_e32 v13, v127
	v_mov_b32_e32 v12, v127
	v_mov_b32_e32 v11, v127
	v_mov_b32_e32 v10, v127
	v_mov_b32_e32 v9, v127
	v_mov_b32_e32 v8, v127
	v_mov_b32_e32 v55, v127
	v_mov_b32_e32 v54, v127
	v_mov_b32_e32 v53, v127
	v_mov_b32_e32 v52, v127
	v_mov_b32_e32 v51, v127
	v_mov_b32_e32 v50, v127
	v_mov_b32_e32 v49, v127
	v_mov_b32_e32 v48, v127
	v_mov_b32_e32 v39, v127
	v_mov_b32_e32 v38, v127
	v_mov_b32_e32 v37, v127
	v_mov_b32_e32 v36, v127
	v_mov_b32_e32 v35, v127
	v_mov_b32_e32 v34, v127
	v_mov_b32_e32 v33, v127
	v_mov_b32_e32 v32, v127
	v_mov_b32_e32 v23, v127
	v_mov_b32_e32 v22, v127
	v_mov_b32_e32 v21, v127
	v_mov_b32_e32 v20, v127
	v_mov_b32_e32 v19, v127
	v_mov_b32_e32 v18, v127
	v_mov_b32_e32 v17, v127
	v_mov_b32_e32 v16, v127
	v_mov_b32_e32 v7, v127
	v_mov_b32_e32 v6, v127
	v_mov_b32_e32 v5, v127
	v_mov_b32_e32 v4, v127
	v_mov_b32_e32 v3, v127
	v_mov_b32_e32 v2, v127
	s_waitcnt lgkmcnt(0)
	v_mov_b32_e32 v1, v127
	v_mov_b32_e32 v0, v127
	s_cbranch_vccnz .LBB0_270
	s_add_u32 s52, s52, 0x100
	s_addc_u32 s53, s53, 0
	s_add_u32 s56, s56, 0x100
	v_mov_b32_e32 v0, 0
	v_mov_b32_e32 v1, 0
	s_addc_u32 s57, s57, 0
	s_mov_b32 s12, 0
	v_pk_mov_b32 v[2:3], v[0:1], v[0:1]
	v_pk_mov_b32 v[4:5], v[0:1], v[0:1]
	v_pk_mov_b32 v[6:7], v[0:1], v[0:1]
	v_pk_mov_b32 v[16:17], v[0:1], v[0:1]
	v_pk_mov_b32 v[18:19], v[0:1], v[0:1]
	v_pk_mov_b32 v[20:21], v[0:1], v[0:1]
	v_pk_mov_b32 v[22:23], v[0:1], v[0:1]
	v_pk_mov_b32 v[32:33], v[0:1], v[0:1]
	v_pk_mov_b32 v[34:35], v[0:1], v[0:1]
	v_pk_mov_b32 v[36:37], v[0:1], v[0:1]
	v_pk_mov_b32 v[38:39], v[0:1], v[0:1]
	v_pk_mov_b32 v[48:49], v[0:1], v[0:1]
	v_pk_mov_b32 v[50:51], v[0:1], v[0:1]
	v_pk_mov_b32 v[52:53], v[0:1], v[0:1]
	v_pk_mov_b32 v[54:55], v[0:1], v[0:1]
	v_pk_mov_b32 v[8:9], v[0:1], v[0:1]
	v_pk_mov_b32 v[10:11], v[0:1], v[0:1]
	v_pk_mov_b32 v[12:13], v[0:1], v[0:1]
	v_pk_mov_b32 v[14:15], v[0:1], v[0:1]
	v_pk_mov_b32 v[24:25], v[0:1], v[0:1]
	v_pk_mov_b32 v[26:27], v[0:1], v[0:1]
	v_pk_mov_b32 v[28:29], v[0:1], v[0:1]
	v_pk_mov_b32 v[30:31], v[0:1], v[0:1]
	v_pk_mov_b32 v[40:41], v[0:1], v[0:1]
	v_pk_mov_b32 v[42:43], v[0:1], v[0:1]
	v_pk_mov_b32 v[44:45], v[0:1], v[0:1]
	v_pk_mov_b32 v[46:47], v[0:1], v[0:1]
	v_pk_mov_b32 v[56:57], v[0:1], v[0:1]
	v_pk_mov_b32 v[58:59], v[0:1], v[0:1]
	v_pk_mov_b32 v[60:61], v[0:1], v[0:1]
	v_pk_mov_b32 v[62:63], v[0:1], v[0:1]
	v_pk_mov_b32 v[64:65], v[0:1], v[0:1]
	v_pk_mov_b32 v[66:67], v[0:1], v[0:1]
	v_pk_mov_b32 v[68:69], v[0:1], v[0:1]
	v_pk_mov_b32 v[70:71], v[0:1], v[0:1]
	v_pk_mov_b32 v[80:81], v[0:1], v[0:1]
	v_pk_mov_b32 v[82:83], v[0:1], v[0:1]
	v_pk_mov_b32 v[84:85], v[0:1], v[0:1]
	v_pk_mov_b32 v[86:87], v[0:1], v[0:1]
	v_pk_mov_b32 v[96:97], v[0:1], v[0:1]
	v_pk_mov_b32 v[98:99], v[0:1], v[0:1]
	v_pk_mov_b32 v[100:101], v[0:1], v[0:1]
	v_pk_mov_b32 v[102:103], v[0:1], v[0:1]
	v_pk_mov_b32 v[112:113], v[0:1], v[0:1]
	v_pk_mov_b32 v[114:115], v[0:1], v[0:1]
	v_pk_mov_b32 v[116:117], v[0:1], v[0:1]
	v_pk_mov_b32 v[118:119], v[0:1], v[0:1]
	v_pk_mov_b32 v[72:73], v[0:1], v[0:1]
	v_pk_mov_b32 v[74:75], v[0:1], v[0:1]
	v_pk_mov_b32 v[76:77], v[0:1], v[0:1]
	v_pk_mov_b32 v[78:79], v[0:1], v[0:1]
	v_pk_mov_b32 v[88:89], v[0:1], v[0:1]
	v_pk_mov_b32 v[90:91], v[0:1], v[0:1]
	v_pk_mov_b32 v[92:93], v[0:1], v[0:1]
	v_pk_mov_b32 v[94:95], v[0:1], v[0:1]
	v_pk_mov_b32 v[104:105], v[0:1], v[0:1]
	v_pk_mov_b32 v[106:107], v[0:1], v[0:1]
	v_pk_mov_b32 v[108:109], v[0:1], v[0:1]
	v_pk_mov_b32 v[110:111], v[0:1], v[0:1]
	v_pk_mov_b32 v[120:121], v[0:1], v[0:1]
	v_pk_mov_b32 v[122:123], v[0:1], v[0:1]
	v_pk_mov_b32 v[124:125], v[0:1], v[0:1]
	v_pk_mov_b32 v[126:127], v[0:1], v[0:1]
	s_add_i32 s95, s12, 2
	s_cmp_eq_u32 s81, s12
	s_cselect_b32 s22, s44, s56
	s_cselect_b32 s23, s45, s57
	s_cselect_b32 s20, s46, s52
	s_cselect_b32 s21, s47, s53
	s_add_u32 s12, s22, 0x80
	s_addc_u32 s13, s23, 0
	s_add_i32 s82, 0, 0x10000
	v_add_u32_e32 v140, s82, v204
; #define PG8_STAGE(bufoff, gbase, voff) do { const char* _gb = (const char*)(gbase); asm volatile("" : "+s"(_gb)); _Pragma("unroll") for (int _i = 0; _i < 2; ++_i) { unsigned _vo = (voff)[_i]; asm volatile("" : "+v"(_vo)); \
;         __builtin_amdgcn_global_load_lds((const GAS unsigned*)(_gb + _vo), (LAS unsigned*)(lds + (bufoff) + ldsw + _i * 8192), 16, 0, 0); } } while (0)
; #define PG8_LDA(dst, b, h) do { _Pragma("unroll") for (int m = 0; m < 4; ++m) _Pragma("unroll") for (int k = 0; k < 2; ++k) dst[m][k] = *(const LAS bf16x8*)(lds + PG8_SA(b, h) + aoff + m * 2048 + k * 1024); } while (0)
; #define PG8_LDB(dst, b, h) do { _Pragma("unroll") for (int n = 0; n < 2; ++n) _Pragma("unroll") for (int k = 0; k < 2; ++k) dst[n][k] = *(const LAS bf16x8*)(lds + PG8_SB(b, h) + boff + n * 2048 + k * 1024); } while (0)
; #define PG8_MMA(ai, bj, At, Bt) do { __builtin_amdgcn_s_setprio(1); _Pragma("unroll") for (int m = 0; m < 4; ++m) _Pragma("unroll") for (int n = 0; n < 2; ++n) _Pragma("unroll") for (int k = 0; k < 2; ++k) \
;         acc[ai][bj][m][n] = __builtin_amdgcn_mfma_f32_16x16x32_bf16(Bt[n][k], At[m][k], acc[ai][bj][m][n], 0, 0, 0); __builtin_amdgcn_s_setprio(0); } while (0)
; #define PG8_WAIT_L(n) asm volatile("s_waitcnt lgkmcnt(" #n ")" ::: "memory")
; #define PG8_BAR __builtin_amdgcn_s_barrier()
; #define PG8_SCHED __builtin_amdgcn_sched_barrier(0)
; template <class Epi, class Ord>
; __device__ __forceinline__ void gemm_phase(LAS unsigned char* lds, const Gemm g, const Ord& S, const Epi& E) {
;     ...
;             PG8_LDB(B0, 0, 0); PG8_SCHED; PG8_LDA(At, 0, 0); PG8_STAGE(PG8_SA(1, 1), a1 + hstep, voffA);
;             PG8_WAIT_L(8); PG8_BAR; PG8_WAIT_L(0); PG8_MMA(0, 0, At, B0); PG8_BAR; PG8_SCHED;
;             PG8_LDB(B1, 0, 1); PG8_STAGE(PG8_SB(0, 0), b2, voffB);
;             PG8_BAR; PG8_WAIT_L(0); PG8_MMA(0, 1, At, B1); PG8_BAR;
;             PG8_LDA(At, 0, 1); PG8_STAGE(PG8_SA(0, 0), a2, voffA);
;             PG8_BAR; PG8_WAIT_L(0); PG8_MMA(1, 0, At, B0); PG8_BAR; PG8_SCHED;
.LBB0_269:
	ds_read_b128 v[128:131], v140
	ds_read_b128 v[132:135], v140 offset:1024
	ds_read_b128 v[136:139], v140 offset:2048
	ds_read_b128 v[140:143], v140 offset:3072
	s_add_u32 s24, s56, s0
	s_addc_u32 s25, s57, s1
	s_add_u32 s24, s24, 0xffffff80
	s_addc_u32 s25, s25, -1
	v_mov_b32_e32 v168, v157
	ds_read_b128 v[144:147], v206
	ds_read_b128 v[148:151], v206 offset:1024
	ds_read_b128 v[152:155], v206 offset:2048
	ds_read_b128 v[192:195], v206 offset:3072
	ds_read_b128 v[196:199], v206 offset:4096
	ds_read_b128 v[212:215], v206 offset:5120
	ds_read_b128 v[216:219], v206 offset:6144
	ds_read_b128 v[220:223], v206 offset:7168
	s_add_i32 m0, s70, 0xc000
	s_nop 0
	global_load_lds_dwordx4 v168, s[24:25]
	v_mov_b32_e32 v168, v201
	s_add_i32 m0, s70, 0xe000
	s_nop 0
	global_load_lds_dwordx4 v168, s[24:25]
	s_waitcnt lgkmcnt(8)
	s_barrier
	s_waitcnt lgkmcnt(0)
	s_setprio 1
	s_waitcnt lgkmcnt(0)
	v_mfma_f32_16x16x32_bf16 v[124:127], v[128:131], v[144:147], v[124:127]
	v_mfma_f32_16x16x32_bf16 v[120:123], v[136:139], v[144:147], v[120:123]
	v_mfma_f32_16x16x32_bf16 v[108:111], v[128:131], v[152:155], v[108:111]
	v_mfma_f32_16x16x32_bf16 v[104:107], v[136:139], v[152:155], v[104:107]
	v_mfma_f32_16x16x32_bf16 v[92:95], v[128:131], v[196:199], v[92:95]
	v_mfma_f32_16x16x32_bf16 v[88:91], v[136:139], v[196:199], v[88:91]
	v_mfma_f32_16x16x32_bf16 v[76:79], v[128:131], v[216:219], v[76:79]
	v_mfma_f32_16x16x32_bf16 v[72:75], v[136:139], v[216:219], v[72:75]
	v_mfma_f32_16x16x32_bf16 v[124:127], v[132:135], v[148:151], v[124:127]
	v_mfma_f32_16x16x32_bf16 v[120:123], v[140:143], v[148:151], v[120:123]
	v_mfma_f32_16x16x32_bf16 v[108:111], v[132:135], v[192:195], v[108:111]
	v_mfma_f32_16x16x32_bf16 v[104:107], v[140:143], v[192:195], v[104:107]
	v_mfma_f32_16x16x32_bf16 v[92:95], v[132:135], v[212:215], v[92:95]
	v_mfma_f32_16x16x32_bf16 v[88:91], v[140:143], v[212:215], v[88:91]
	v_mfma_f32_16x16x32_bf16 v[76:79], v[132:135], v[220:223], v[76:79]
	v_mfma_f32_16x16x32_bf16 v[72:75], v[140:143], v[220:223], v[72:75]
	s_setprio 0
	s_barrier
	s_add_i32 s84, 0, 0x14000
	v_add_u32_e32 v168, s84, v204
	ds_read_b128 v[224:227], v168
	ds_read_b128 v[228:231], v168 offset:1024
	ds_read_b128 v[232:235], v168 offset:2048
	ds_read_b128 v[236:239], v168 offset:3072
	s_mov_b64 s[24:25], s[20:21]
	v_mov_b32_e32 v168, v200
	s_add_i32 s82, s82, s69
	s_mov_b32 m0, s82
	s_nop 0
	global_load_lds_dwordx4 v168, s[24:25]
	v_mov_b32_e32 v168, v202
	s_add_i32 m0, s82, 0x2000
	s_nop 0
	global_load_lds_dwordx4 v168, s[24:25]
	s_barrier
	s_waitcnt lgkmcnt(0)
	s_setprio 1
	s_waitcnt lgkmcnt(0)
	v_mfma_f32_16x16x32_bf16 v[116:119], v[224:227], v[144:147], v[116:119]
	v_mfma_f32_16x16x32_bf16 v[112:115], v[232:235], v[144:147], v[112:115]
	v_mfma_f32_16x16x32_bf16 v[100:103], v[224:227], v[152:155], v[100:103]
	v_mfma_f32_16x16x32_bf16 v[96:99], v[232:235], v[152:155], v[96:99]
	v_mfma_f32_16x16x32_bf16 v[84:87], v[224:227], v[196:199], v[84:87]
	v_mfma_f32_16x16x32_bf16 v[80:83], v[232:235], v[196:199], v[80:83]
	v_mfma_f32_16x16x32_bf16 v[68:71], v[224:227], v[216:219], v[68:71]
	v_mfma_f32_16x16x32_bf16 v[64:67], v[232:235], v[216:219], v[64:67]
	v_mfma_f32_16x16x32_bf16 v[116:119], v[228:231], v[148:151], v[116:119]
	v_mfma_f32_16x16x32_bf16 v[112:115], v[236:239], v[148:151], v[112:115]
	v_mfma_f32_16x16x32_bf16 v[100:103], v[228:231], v[192:195], v[100:103]
	v_mfma_f32_16x16x32_bf16 v[96:99], v[236:239], v[192:195], v[96:99]
	v_mfma_f32_16x16x32_bf16 v[84:87], v[228:231], v[212:215], v[84:87]
	v_mfma_f32_16x16x32_bf16 v[80:83], v[236:239], v[212:215], v[80:83]
	v_mfma_f32_16x16x32_bf16 v[68:71], v[228:231], v[220:223], v[68:71]
	v_mfma_f32_16x16x32_bf16 v[64:67], v[236:239], v[220:223], v[64:67]
	s_setprio 0
	s_mov_b64 s[24:25], s[22:23]
	v_mov_b32_e32 v168, v157
	s_mov_b32 m0, s70
	s_barrier
	ds_read_b128 v[144:147], v206 offset:16384
	ds_read_b128 v[148:151], v206 offset:17408
	ds_read_b128 v[152:155], v206 offset:18432
	ds_read_b128 v[192:195], v206 offset:19456
	ds_read_b128 v[196:199], v206 offset:20480
	ds_read_b128 v[212:215], v206 offset:21504
	ds_read_b128 v[216:219], v206 offset:22528
	ds_read_b128 v[220:223], v206 offset:23552
	s_nop 0
	global_load_lds_dwordx4 v168, s[24:25]
	v_mov_b32_e32 v168, v201
	s_mov_b32 m0, s71
	s_nop 0
	global_load_lds_dwordx4 v168, s[24:25]
	s_barrier
	s_waitcnt lgkmcnt(0)
	s_setprio 1
	s_waitcnt lgkmcnt(0)
	v_mfma_f32_16x16x32_bf16 v[60:63], v[128:131], v[144:147], v[60:63]
	v_mfma_f32_16x16x32_bf16 v[56:59], v[136:139], v[144:147], v[56:59]
	v_mfma_f32_16x16x32_bf16 v[44:47], v[128:131], v[152:155], v[44:47]
	v_mfma_f32_16x16x32_bf16 v[40:43], v[136:139], v[152:155], v[40:43]
	v_mfma_f32_16x16x32_bf16 v[28:31], v[128:131], v[196:199], v[28:31]
	v_mfma_f32_16x16x32_bf16 v[24:27], v[136:139], v[196:199], v[24:27]
	v_mfma_f32_16x16x32_bf16 v[12:15], v[128:131], v[216:219], v[12:15]
	v_mfma_f32_16x16x32_bf16 v[8:11], v[136:139], v[216:219], v[8:11]
	v_mfma_f32_16x16x32_bf16 v[60:63], v[132:135], v[148:151], v[60:63]
	v_mfma_f32_16x16x32_bf16 v[56:59], v[140:143], v[148:151], v[56:59]
	v_mfma_f32_16x16x32_bf16 v[44:47], v[132:135], v[192:195], v[44:47]
	v_mfma_f32_16x16x32_bf16 v[40:43], v[140:143], v[192:195], v[40:43]
	v_mfma_f32_16x16x32_bf16 v[28:31], v[132:135], v[212:215], v[28:31]
	v_mfma_f32_16x16x32_bf16 v[24:27], v[140:143], v[212:215], v[24:27]
	v_mfma_f32_16x16x32_bf16 v[12:15], v[132:135], v[220:223], v[12:15]
	v_mfma_f32_16x16x32_bf16 v[8:11], v[140:143], v[220:223], v[8:11]
	s_setprio 0
	s_barrier
; #define PG8_STAGE(bufoff, gbase, voff) do { const char* _gb = (const char*)(gbase); asm volatile("" : "+s"(_gb)); _Pragma("unroll") for (int _i = 0; _i < 2; ++_i) { unsigned _vo = (voff)[_i]; asm volatile("" : "+v"(_vo)); \
;         __builtin_amdgcn_global_load_lds((const GAS unsigned*)(_gb + _vo), (LAS unsigned*)(lds + (bufoff) + ldsw + _i * 8192), 16, 0, 0); } } while (0)
; #define PG8_LDA(dst, b, h) do { _Pragma("unroll") for (int m = 0; m < 4; ++m) _Pragma("unroll") for (int k = 0; k < 2; ++k) dst[m][k] = *(const LAS bf16x8*)(lds + PG8_SA(b, h) + aoff + m * 2048 + k * 1024); } while (0)
; #define PG8_LDB(dst, b, h) do { _Pragma("unroll") for (int n = 0; n < 2; ++n) _Pragma("unroll") for (int k = 0; k < 2; ++k) dst[n][k] = *(const LAS bf16x8*)(lds + PG8_SB(b, h) + boff + n * 2048 + k * 1024); } while (0)
; #define PG8_MMA(ai, bj, At, Bt) do { __builtin_amdgcn_s_setprio(1); _Pragma("unroll") for (int m = 0; m < 4; ++m) _Pragma("unroll") for (int n = 0; n < 2; ++n) _Pragma("unroll") for (int k = 0; k < 2; ++k) \
;         acc[ai][bj][m][n] = __builtin_amdgcn_mfma_f32_16x16x32_bf16(Bt[n][k], At[m][k], acc[ai][bj][m][n], 0, 0, 0); __builtin_amdgcn_s_setprio(0); } while (0)
; #define PG8_WAIT_V(n) asm volatile("s_waitcnt vmcnt(" #n ")" ::: "memory")
; #define PG8_WAIT_L(n) asm volatile("s_waitcnt lgkmcnt(" #n ")" ::: "memory")
; #define PG8_BAR __builtin_amdgcn_s_barrier()
; #define PG8_SCHED __builtin_amdgcn_sched_barrier(0)
; template <class Epi, class Ord>
; __device__ __forceinline__ void gemm_phase(LAS unsigned char* lds, const Gemm g, const Ord& S, const Epi& E) {
;     ...
;             PG8_STAGE(PG8_SB(0, 1), b2 + hstep, voffB);
;             PG8_WAIT_V(6); PG8_BAR; PG8_MMA(1, 1, At, B1); PG8_BAR;
;             PG8_LDB(B0, 1, 0); PG8_SCHED; PG8_LDA(At, 1, 0); PG8_STAGE(PG8_SA(0, 1), a2 + hstep, voffA);
;             PG8_WAIT_L(8); PG8_BAR; PG8_WAIT_L(0); PG8_MMA(0, 0, At, B0); PG8_BAR; PG8_SCHED;
;             PG8_LDB(B1, 1, 1); PG8_STAGE(PG8_SB(1, 0), b3, voffB);
	s_add_u32 s24, s20, s0
	s_addc_u32 s25, s21, s1
	s_mov_b64 s[82:83], s[24:25]
	v_mov_b32_e32 v128, v200
	s_add_i32 s84, s84, s69
	s_mov_b32 m0, s84
	s_nop 0
	global_load_lds_dwordx4 v128, s[82:83]
	v_mov_b32_e32 v128, v202
	s_add_i32 m0, s84, 0x2000
	s_nop 0
	global_load_lds_dwordx4 v128, s[82:83]
	s_waitcnt vmcnt(6)
	s_barrier
	s_setprio 1
	v_mfma_f32_16x16x32_bf16 v[52:55], v[224:227], v[144:147], v[52:55]
	v_mfma_f32_16x16x32_bf16 v[48:51], v[232:235], v[144:147], v[48:51]
	v_mfma_f32_16x16x32_bf16 v[36:39], v[224:227], v[152:155], v[36:39]
	v_mfma_f32_16x16x32_bf16 v[32:35], v[232:235], v[152:155], v[32:35]
	v_mfma_f32_16x16x32_bf16 v[20:23], v[224:227], v[196:199], v[20:23]
	v_mfma_f32_16x16x32_bf16 v[16:19], v[232:235], v[196:199], v[16:19]
	v_mfma_f32_16x16x32_bf16 v[4:7], v[224:227], v[216:219], v[4:7]
	v_mfma_f32_16x16x32_bf16 v[0:3], v[232:235], v[216:219], v[0:3]
	v_mfma_f32_16x16x32_bf16 v[52:55], v[228:231], v[148:151], v[52:55]
	v_mfma_f32_16x16x32_bf16 v[48:51], v[236:239], v[148:151], v[48:51]
	v_mfma_f32_16x16x32_bf16 v[36:39], v[228:231], v[192:195], v[36:39]
	v_mfma_f32_16x16x32_bf16 v[32:35], v[236:239], v[192:195], v[32:35]
	v_mfma_f32_16x16x32_bf16 v[20:23], v[228:231], v[212:215], v[20:23]
	v_mfma_f32_16x16x32_bf16 v[16:19], v[236:239], v[212:215], v[16:19]
	v_mfma_f32_16x16x32_bf16 v[4:7], v[228:231], v[220:223], v[4:7]
	v_mfma_f32_16x16x32_bf16 v[0:3], v[236:239], v[220:223], v[0:3]
	s_setprio 0
	s_add_i32 s82, 0, 0x18000
	v_add_u32_e32 v140, s82, v204
	s_barrier
	ds_read_b128 v[128:131], v140
	ds_read_b128 v[132:135], v140 offset:1024
	ds_read_b128 v[136:139], v140 offset:2048
	ds_read_b128 v[140:143], v140 offset:3072
	s_add_u32 s22, s22, s0
	s_addc_u32 s23, s23, s1
	v_mov_b32_e32 v168, v157
	s_mov_b32 m0, s72
	ds_read_b128 v[144:147], v206 offset:32768
	ds_read_b128 v[148:151], v206 offset:33792
	ds_read_b128 v[152:155], v206 offset:34816
	ds_read_b128 v[192:195], v206 offset:35840
	ds_read_b128 v[196:199], v206 offset:36864
	ds_read_b128 v[212:215], v206 offset:37888
	ds_read_b128 v[216:219], v206 offset:38912
	ds_read_b128 v[220:223], v206 offset:39936
	s_nop 0
	global_load_lds_dwordx4 v168, s[22:23]
	v_mov_b32_e32 v168, v201
	s_mov_b32 m0, s73
	s_nop 0
	global_load_lds_dwordx4 v168, s[22:23]
	s_waitcnt lgkmcnt(8)
	s_barrier
	s_waitcnt lgkmcnt(0)
	s_setprio 1
	s_waitcnt lgkmcnt(0)
	v_mfma_f32_16x16x32_bf16 v[124:127], v[128:131], v[144:147], v[124:127]
	v_mfma_f32_16x16x32_bf16 v[120:123], v[136:139], v[144:147], v[120:123]
	v_mfma_f32_16x16x32_bf16 v[108:111], v[128:131], v[152:155], v[108:111]
	v_mfma_f32_16x16x32_bf16 v[104:107], v[136:139], v[152:155], v[104:107]
	v_mfma_f32_16x16x32_bf16 v[92:95], v[128:131], v[196:199], v[92:95]
	v_mfma_f32_16x16x32_bf16 v[88:91], v[136:139], v[196:199], v[88:91]
	v_mfma_f32_16x16x32_bf16 v[76:79], v[128:131], v[216:219], v[76:79]
	v_mfma_f32_16x16x32_bf16 v[72:75], v[136:139], v[216:219], v[72:75]
	v_mfma_f32_16x16x32_bf16 v[124:127], v[132:135], v[148:151], v[124:127]
	v_mfma_f32_16x16x32_bf16 v[120:123], v[140:143], v[148:151], v[120:123]
	v_mfma_f32_16x16x32_bf16 v[108:111], v[132:135], v[192:195], v[108:111]
	v_mfma_f32_16x16x32_bf16 v[104:107], v[140:143], v[192:195], v[104:107]
	v_mfma_f32_16x16x32_bf16 v[92:95], v[132:135], v[212:215], v[92:95]
	v_mfma_f32_16x16x32_bf16 v[88:91], v[140:143], v[212:215], v[88:91]
	v_mfma_f32_16x16x32_bf16 v[76:79], v[132:135], v[220:223], v[76:79]
	v_mfma_f32_16x16x32_bf16 v[72:75], v[140:143], v[220:223], v[72:75]
	s_setprio 0
	s_barrier
	s_add_i32 s22, 0, 0x1c000
	v_add_u32_e32 v168, s22, v204
	s_add_u32 s20, s20, 0x80
	ds_read_b128 v[224:227], v168
	ds_read_b128 v[228:231], v168 offset:1024
	ds_read_b128 v[232:235], v168 offset:2048
	ds_read_b128 v[236:239], v168 offset:3072
	s_addc_u32 s21, s21, 0
	v_mov_b32_e32 v168, v200
	s_add_i32 s23, s82, s69
	s_mov_b32 m0, s23
	s_nop 0
	global_load_lds_dwordx4 v168, s[20:21]
	v_mov_b32_e32 v168, v202
	s_add_i32 m0, s23, 0x2000
	s_nop 0
	global_load_lds_dwordx4 v168, s[20:21]
	s_barrier
; #define PG8_STAGE(bufoff, gbase, voff) do { const char* _gb = (const char*)(gbase); asm volatile("" : "+s"(_gb)); _Pragma("unroll") for (int _i = 0; _i < 2; ++_i) { unsigned _vo = (voff)[_i]; asm volatile("" : "+v"(_vo)); \
;         __builtin_amdgcn_global_load_lds((const GAS unsigned*)(_gb + _vo), (LAS unsigned*)(lds + (bufoff) + ldsw + _i * 8192), 16, 0, 0); } } while (0)
; #define PG8_LDA(dst, b, h) do { _Pragma("unroll") for (int m = 0; m < 4; ++m) _Pragma("unroll") for (int k = 0; k < 2; ++k) dst[m][k] = *(const LAS bf16x8*)(lds + PG8_SA(b, h) + aoff + m * 2048 + k * 1024); } while (0)
; #define PG8_MMA(ai, bj, At, Bt) do { __builtin_amdgcn_s_setprio(1); _Pragma("unroll") for (int m = 0; m < 4; ++m) _Pragma("unroll") for (int n = 0; n < 2; ++n) _Pragma("unroll") for (int k = 0; k < 2; ++k) \
;         acc[ai][bj][m][n] = __builtin_amdgcn_mfma_f32_16x16x32_bf16(Bt[n][k], At[m][k], acc[ai][bj][m][n], 0, 0, 0); __builtin_amdgcn_s_setprio(0); } while (0)
; #define PG8_WAIT_V(n) asm volatile("s_waitcnt vmcnt(" #n ")" ::: "memory")
; #define PG8_WAIT_L(n) asm volatile("s_waitcnt lgkmcnt(" #n ")" ::: "memory")
; #define PG8_BAR __builtin_amdgcn_s_barrier()
; #define PG8_SCHED __builtin_amdgcn_sched_barrier(0)
; template <class Epi, class Ord>
; __device__ __forceinline__ void gemm_phase(LAS unsigned char* lds, const Gemm g, const Ord& S, const Epi& E) {
;     ...
;             PG8_BAR; PG8_WAIT_L(0); PG8_MMA(0, 1, At, B1); PG8_BAR;
;             PG8_LDA(At, 1, 1); PG8_STAGE(PG8_SA(1, 0), a3, voffA);
;             PG8_BAR; PG8_WAIT_L(0); PG8_MMA(1, 0, At, B0); PG8_BAR; PG8_SCHED;
;             PG8_STAGE(PG8_SB(1, 1), b3 + hstep, voffB);
;             PG8_WAIT_V(6); PG8_BAR; PG8_MMA(1, 1, At, B1); PG8_BAR;
;         }
	s_waitcnt lgkmcnt(0)
	s_setprio 1
	s_waitcnt lgkmcnt(0)
	v_mfma_f32_16x16x32_bf16 v[116:119], v[224:227], v[144:147], v[116:119]
	v_mfma_f32_16x16x32_bf16 v[112:115], v[232:235], v[144:147], v[112:115]
	v_mfma_f32_16x16x32_bf16 v[100:103], v[224:227], v[152:155], v[100:103]
	v_mfma_f32_16x16x32_bf16 v[96:99], v[232:235], v[152:155], v[96:99]
	v_mfma_f32_16x16x32_bf16 v[84:87], v[224:227], v[196:199], v[84:87]
	v_mfma_f32_16x16x32_bf16 v[80:83], v[232:235], v[196:199], v[80:83]
	v_mfma_f32_16x16x32_bf16 v[68:71], v[224:227], v[216:219], v[68:71]
	v_mfma_f32_16x16x32_bf16 v[64:67], v[232:235], v[216:219], v[64:67]
	v_mfma_f32_16x16x32_bf16 v[116:119], v[228:231], v[148:151], v[116:119]
	v_mfma_f32_16x16x32_bf16 v[112:115], v[236:239], v[148:151], v[112:115]
	v_mfma_f32_16x16x32_bf16 v[100:103], v[228:231], v[192:195], v[100:103]
	v_mfma_f32_16x16x32_bf16 v[96:99], v[236:239], v[192:195], v[96:99]
	v_mfma_f32_16x16x32_bf16 v[84:87], v[228:231], v[212:215], v[84:87]
	v_mfma_f32_16x16x32_bf16 v[80:83], v[236:239], v[212:215], v[80:83]
	v_mfma_f32_16x16x32_bf16 v[68:71], v[228:231], v[220:223], v[68:71]
	v_mfma_f32_16x16x32_bf16 v[64:67], v[236:239], v[220:223], v[64:67]
	s_setprio 0
	v_mov_b32_e32 v168, v157
	s_mov_b32 m0, s79
	s_barrier
	ds_read_b128 v[144:147], v206 offset:49152
	ds_read_b128 v[148:151], v206 offset:50176
	ds_read_b128 v[152:155], v206 offset:51200
	ds_read_b128 v[192:195], v206 offset:52224
	ds_read_b128 v[196:199], v206 offset:53248
	ds_read_b128 v[212:215], v206 offset:54272
	ds_read_b128 v[216:219], v206 offset:55296
	ds_read_b128 v[220:223], v206 offset:56320
	s_nop 0
	global_load_lds_dwordx4 v168, s[12:13]
	v_mov_b32_e32 v168, v201
	s_mov_b32 m0, s80
	s_nop 0
	global_load_lds_dwordx4 v168, s[12:13]
	s_barrier
	s_waitcnt lgkmcnt(0)
	s_setprio 1
	s_waitcnt lgkmcnt(0)
	v_mfma_f32_16x16x32_bf16 v[60:63], v[128:131], v[144:147], v[60:63]
	v_mfma_f32_16x16x32_bf16 v[56:59], v[136:139], v[144:147], v[56:59]
	v_mfma_f32_16x16x32_bf16 v[44:47], v[128:131], v[152:155], v[44:47]
	v_mfma_f32_16x16x32_bf16 v[40:43], v[136:139], v[152:155], v[40:43]
	v_mfma_f32_16x16x32_bf16 v[28:31], v[128:131], v[196:199], v[28:31]
	v_mfma_f32_16x16x32_bf16 v[24:27], v[136:139], v[196:199], v[24:27]
	v_mfma_f32_16x16x32_bf16 v[12:15], v[128:131], v[216:219], v[12:15]
	v_mfma_f32_16x16x32_bf16 v[8:11], v[136:139], v[216:219], v[8:11]
	v_mfma_f32_16x16x32_bf16 v[60:63], v[132:135], v[148:151], v[60:63]
	v_mfma_f32_16x16x32_bf16 v[56:59], v[140:143], v[148:151], v[56:59]
	v_mfma_f32_16x16x32_bf16 v[44:47], v[132:135], v[192:195], v[44:47]
	v_mfma_f32_16x16x32_bf16 v[40:43], v[140:143], v[192:195], v[40:43]
	v_mfma_f32_16x16x32_bf16 v[28:31], v[132:135], v[212:215], v[28:31]
	v_mfma_f32_16x16x32_bf16 v[24:27], v[140:143], v[212:215], v[24:27]
	v_mfma_f32_16x16x32_bf16 v[12:15], v[132:135], v[220:223], v[12:15]
	v_mfma_f32_16x16x32_bf16 v[8:11], v[140:143], v[220:223], v[8:11]
	s_setprio 0
	s_barrier
	s_add_u32 s12, s24, 0x80
	s_addc_u32 s13, s25, 0
	v_mov_b32_e32 v128, v200
	s_add_i32 s20, s22, s69
	s_mov_b32 m0, s20
	s_nop 0
	global_load_lds_dwordx4 v128, s[12:13]
	v_mov_b32_e32 v128, v202
	s_add_i32 m0, s20, 0x2000
	s_nop 0
	global_load_lds_dwordx4 v128, s[12:13]
	s_waitcnt vmcnt(6)
	s_barrier
	s_setprio 1
	v_mfma_f32_16x16x32_bf16 v[52:55], v[224:227], v[144:147], v[52:55]
	v_mfma_f32_16x16x32_bf16 v[48:51], v[232:235], v[144:147], v[48:51]
	v_mfma_f32_16x16x32_bf16 v[36:39], v[224:227], v[152:155], v[36:39]
	v_mfma_f32_16x16x32_bf16 v[32:35], v[232:235], v[152:155], v[32:35]
	v_mfma_f32_16x16x32_bf16 v[20:23], v[224:227], v[196:199], v[20:23]
	v_mfma_f32_16x16x32_bf16 v[16:19], v[232:235], v[196:199], v[16:19]
	v_mfma_f32_16x16x32_bf16 v[4:7], v[224:227], v[216:219], v[4:7]
	v_mfma_f32_16x16x32_bf16 v[0:3], v[232:235], v[216:219], v[0:3]
	v_mfma_f32_16x16x32_bf16 v[52:55], v[228:231], v[148:151], v[52:55]
	v_mfma_f32_16x16x32_bf16 v[48:51], v[236:239], v[148:151], v[48:51]
	v_mfma_f32_16x16x32_bf16 v[36:39], v[228:231], v[192:195], v[36:39]
	v_mfma_f32_16x16x32_bf16 v[32:35], v[236:239], v[192:195], v[32:35]
	v_mfma_f32_16x16x32_bf16 v[20:23], v[228:231], v[212:215], v[20:23]
	v_mfma_f32_16x16x32_bf16 v[16:19], v[236:239], v[212:215], v[16:19]
	v_mfma_f32_16x16x32_bf16 v[4:7], v[228:231], v[220:223], v[4:7]
	v_mfma_f32_16x16x32_bf16 v[0:3], v[236:239], v[220:223], v[0:3]
	s_setprio 0
	s_add_u32 s52, s52, 0x100
	s_addc_u32 s53, s53, 0
	s_add_u32 s56, s56, 0x100
	s_addc_u32 s57, s57, 0
	s_mov_b32 s12, s95
	s_add_i32 s95, s12, 2
	s_cmp_eq_u32 s81, s12
	s_cselect_b32 s22, s44, s56
	s_cselect_b32 s23, s45, s57
	s_cselect_b32 s20, s46, s52
	s_cselect_b32 s21, s47, s53
	s_add_u32 s12, s22, 0x80
	s_addc_u32 s13, s23, 0
	s_add_i32 s82, 0, 0x10000
	v_add_u32_e32 v140, s82, v204
	s_sub_i32 s98, s95, 2
	s_cmp_ge_i32 s98, s77
	s_barrier
	s_cbranch_scc0 .LBB0_269

; template <class Epi, class Ord>
; __device__ __forceinline__ void gemm_phase(LAS unsigned char* lds, const Gemm g, const Ord& S, const Epi& E) {
;     ...
;             const bool last = (t == nt - 2);
;             const char* a1 = cA + (size_t)(t + 1) * kstep;
;             const char* a2 = last ? nA : cA + (size_t)(t + 2) * kstep; const char* b2 = last ? nB : cB + (size_t)(t + 2) * kstep;
;             const char* a3 = a2 + kstep; const char* b3 = b2 + kstep;
;     ...
;         for (int a = 0; a < 2; ++a)
; #pragma unroll
;             for (int b = 0; b < 2; ++b)
; #pragma unroll
;                 for (int m = 0; m < 4; ++m)
; #pragma unroll
;                     for (int n = 0; n < 2; ++n) acc[a][b][m][n] = (f32x4){0.f, 0.f, 0.f, 0.f};
;         cur = nxt; cA = nA; cB = nB; ++ui;
.LBB0_310:
	v_mov_b32_e32 v143, 0
	s_andn2_b64 vcc, exec, s[52:53]
	v_mov_b32_e32 v142, v143
	v_mov_b32_e32 v141, v143
	v_mov_b32_e32 v140, v143
	v_mov_b32_e32 v135, v143
	v_mov_b32_e32 v134, v143
	v_mov_b32_e32 v133, v143
	v_mov_b32_e32 v132, v143
	v_mov_b32_e32 v111, v143
	v_mov_b32_e32 v110, v143
	v_mov_b32_e32 v109, v143
	v_mov_b32_e32 v108, v143
	v_mov_b32_e32 v107, v143
	v_mov_b32_e32 v106, v143
	v_mov_b32_e32 v105, v143
	v_mov_b32_e32 v104, v143
	v_mov_b32_e32 v95, v143
	v_mov_b32_e32 v94, v143
	v_mov_b32_e32 v93, v143
	v_mov_b32_e32 v92, v143
	v_mov_b32_e32 v91, v143
	v_mov_b32_e32 v90, v143
	v_mov_b32_e32 v89, v143
	v_mov_b32_e32 v88, v143
	v_mov_b32_e32 v79, v143
	v_mov_b32_e32 v78, v143
	v_mov_b32_e32 v77, v143
	v_mov_b32_e32 v76, v143
	v_mov_b32_e32 v75, v143
	v_mov_b32_e32 v74, v143
	v_mov_b32_e32 v73, v143
	v_mov_b32_e32 v72, v143
	v_mov_b32_e32 v123, v143
	v_mov_b32_e32 v122, v143
	v_mov_b32_e32 v121, v143
	v_mov_b32_e32 v120, v143
	v_mov_b32_e32 v115, v143
	v_mov_b32_e32 v114, v143
	v_mov_b32_e32 v113, v143
	v_mov_b32_e32 v112, v143
	v_mov_b32_e32 v103, v143
	v_mov_b32_e32 v102, v143
	v_mov_b32_e32 v101, v143
	v_mov_b32_e32 v100, v143
	v_mov_b32_e32 v99, v143
	v_mov_b32_e32 v98, v143
	v_mov_b32_e32 v97, v143
	v_mov_b32_e32 v96, v143
	v_mov_b32_e32 v87, v143
	v_mov_b32_e32 v86, v143
	v_mov_b32_e32 v85, v143
	v_mov_b32_e32 v84, v143
	v_mov_b32_e32 v83, v143
	v_mov_b32_e32 v82, v143
	v_mov_b32_e32 v81, v143
	v_mov_b32_e32 v80, v143
	v_mov_b32_e32 v71, v143
	v_mov_b32_e32 v70, v143
	v_mov_b32_e32 v69, v143
	v_mov_b32_e32 v68, v143
	v_mov_b32_e32 v67, v143
	v_mov_b32_e32 v66, v143
	v_mov_b32_e32 v65, v143
	v_mov_b32_e32 v64, v143
	v_mov_b32_e32 v63, v143
	v_mov_b32_e32 v62, v143
	v_mov_b32_e32 v61, v143
	v_mov_b32_e32 v60, v143
	v_mov_b32_e32 v59, v143
	v_mov_b32_e32 v58, v143
	v_mov_b32_e32 v57, v143
	v_mov_b32_e32 v56, v143
	v_mov_b32_e32 v47, v143
	v_mov_b32_e32 v46, v143
	v_mov_b32_e32 v45, v143
	v_mov_b32_e32 v44, v143
	v_mov_b32_e32 v43, v143
	v_mov_b32_e32 v42, v143
	v_mov_b32_e32 v41, v143
	v_mov_b32_e32 v40, v143
	v_mov_b32_e32 v31, v143
	v_mov_b32_e32 v30, v143
	v_mov_b32_e32 v29, v143
	v_mov_b32_e32 v28, v143
	v_mov_b32_e32 v27, v143
	v_mov_b32_e32 v26, v143
	v_mov_b32_e32 v25, v143
	v_mov_b32_e32 v24, v143
	v_mov_b32_e32 v15, v143
	v_mov_b32_e32 v14, v143
	v_mov_b32_e32 v13, v143
	v_mov_b32_e32 v12, v143
	v_mov_b32_e32 v11, v143
	v_mov_b32_e32 v10, v143
	v_mov_b32_e32 v9, v143
	v_mov_b32_e32 v8, v143
	v_mov_b32_e32 v55, v143
	v_mov_b32_e32 v54, v143
	v_mov_b32_e32 v53, v143
	v_mov_b32_e32 v52, v143
	v_mov_b32_e32 v51, v143
	v_mov_b32_e32 v50, v143
	v_mov_b32_e32 v49, v143
	v_mov_b32_e32 v48, v143
	v_mov_b32_e32 v39, v143
	v_mov_b32_e32 v38, v143
	v_mov_b32_e32 v37, v143
	v_mov_b32_e32 v36, v143
	v_mov_b32_e32 v35, v143
	v_mov_b32_e32 v34, v143
	v_mov_b32_e32 v33, v143
	v_mov_b32_e32 v32, v143
	v_mov_b32_e32 v23, v143
	v_mov_b32_e32 v22, v143
	v_mov_b32_e32 v21, v143
	v_mov_b32_e32 v20, v143
	v_mov_b32_e32 v19, v143
	v_mov_b32_e32 v18, v143
	v_mov_b32_e32 v17, v143
	v_mov_b32_e32 v16, v143
	v_mov_b32_e32 v7, v143
	v_mov_b32_e32 v6, v143
	v_mov_b32_e32 v5, v143
	v_mov_b32_e32 v4, v143
	v_mov_b32_e32 v3, v143
	v_mov_b32_e32 v2, v143
	v_mov_b32_e32 v1, v143
	v_mov_b32_e32 v0, v143
	s_cbranch_vccnz .LBB0_299
	s_add_u32 s78, s16, 0x100
	s_addc_u32 s79, s17, 0
	s_add_u32 s46, s46, 0x100
	v_mov_b32_e32 v0, 0
	s_addc_u32 s47, s47, 0
	s_mov_b32 s12, 0
	v_mov_b32_e32 v1, v0
	v_mov_b32_e32 v2, v0
	v_mov_b32_e32 v3, v0
	v_mov_b32_e32 v4, v0
	v_mov_b32_e32 v5, v0
	v_mov_b32_e32 v6, v0
	v_mov_b32_e32 v7, v0
	v_mov_b32_e32 v16, v0
	v_mov_b32_e32 v17, v0
	v_mov_b32_e32 v18, v0
	v_mov_b32_e32 v19, v0
	v_mov_b32_e32 v20, v0
	v_mov_b32_e32 v21, v0
	v_mov_b32_e32 v22, v0
	v_mov_b32_e32 v23, v0
	v_mov_b32_e32 v32, v0
	v_mov_b32_e32 v33, v0
	v_mov_b32_e32 v34, v0
	v_mov_b32_e32 v35, v0
	v_mov_b32_e32 v36, v0
	v_mov_b32_e32 v37, v0
	v_mov_b32_e32 v38, v0
	v_mov_b32_e32 v39, v0
	v_mov_b32_e32 v48, v0
	v_mov_b32_e32 v49, v0
	v_mov_b32_e32 v50, v0
	v_mov_b32_e32 v51, v0
	v_mov_b32_e32 v52, v0
	v_mov_b32_e32 v53, v0
	v_mov_b32_e32 v54, v0
	v_mov_b32_e32 v55, v0
	v_mov_b32_e32 v8, v0
	v_mov_b32_e32 v9, v0
	v_mov_b32_e32 v10, v0
	v_mov_b32_e32 v11, v0
	v_mov_b32_e32 v12, v0
	v_mov_b32_e32 v13, v0
	v_mov_b32_e32 v14, v0
	v_mov_b32_e32 v15, v0
	v_mov_b32_e32 v24, v0
	v_mov_b32_e32 v25, v0
	v_mov_b32_e32 v26, v0
	v_mov_b32_e32 v27, v0
	v_mov_b32_e32 v28, v0
	v_mov_b32_e32 v29, v0
	v_mov_b32_e32 v30, v0
	v_mov_b32_e32 v31, v0
	v_mov_b32_e32 v40, v0
	v_mov_b32_e32 v41, v0
	v_mov_b32_e32 v42, v0
	v_mov_b32_e32 v43, v0
	v_mov_b32_e32 v44, v0
	v_mov_b32_e32 v45, v0
	v_mov_b32_e32 v46, v0
	v_mov_b32_e32 v47, v0
	v_mov_b32_e32 v56, v0
	v_mov_b32_e32 v57, v0
	v_mov_b32_e32 v58, v0
	v_mov_b32_e32 v59, v0
	v_mov_b32_e32 v60, v0
	v_mov_b32_e32 v61, v0
	v_mov_b32_e32 v62, v0
	v_mov_b32_e32 v63, v0
	v_mov_b32_e32 v64, v0
	v_mov_b32_e32 v65, v0
	v_mov_b32_e32 v66, v0
	v_mov_b32_e32 v67, v0
	v_mov_b32_e32 v68, v0
	v_mov_b32_e32 v69, v0
	v_mov_b32_e32 v70, v0
	v_mov_b32_e32 v71, v0
	v_mov_b32_e32 v80, v0
	v_mov_b32_e32 v81, v0
	v_mov_b32_e32 v82, v0
	v_mov_b32_e32 v83, v0
	v_mov_b32_e32 v84, v0
	v_mov_b32_e32 v85, v0
	v_mov_b32_e32 v86, v0
	v_mov_b32_e32 v87, v0
	v_mov_b32_e32 v96, v0
	v_mov_b32_e32 v97, v0
	v_mov_b32_e32 v98, v0
	v_mov_b32_e32 v99, v0
	v_mov_b32_e32 v100, v0
	v_mov_b32_e32 v101, v0
	v_mov_b32_e32 v102, v0
	v_mov_b32_e32 v103, v0
	v_mov_b32_e32 v112, v0
	v_mov_b32_e32 v113, v0
	v_mov_b32_e32 v114, v0
	v_mov_b32_e32 v115, v0
	v_mov_b32_e32 v120, v0
	v_mov_b32_e32 v121, v0
	v_mov_b32_e32 v122, v0
	v_mov_b32_e32 v123, v0
	v_mov_b32_e32 v72, v0
	v_mov_b32_e32 v73, v0
	v_mov_b32_e32 v74, v0
	v_mov_b32_e32 v75, v0
	v_mov_b32_e32 v76, v0
	v_mov_b32_e32 v77, v0
	v_mov_b32_e32 v78, v0
	v_mov_b32_e32 v79, v0
	v_mov_b32_e32 v88, v0
	v_mov_b32_e32 v89, v0
	v_mov_b32_e32 v90, v0
	v_mov_b32_e32 v91, v0
	v_mov_b32_e32 v92, v0
	v_mov_b32_e32 v93, v0
	v_mov_b32_e32 v94, v0
	v_mov_b32_e32 v95, v0
	v_mov_b32_e32 v104, v0
	v_mov_b32_e32 v105, v0
	v_mov_b32_e32 v106, v0
	v_mov_b32_e32 v107, v0
	v_mov_b32_e32 v108, v0
	v_mov_b32_e32 v109, v0
	v_mov_b32_e32 v110, v0
	v_mov_b32_e32 v111, v0
	v_mov_b32_e32 v132, v0
	v_mov_b32_e32 v133, v0
	v_mov_b32_e32 v134, v0
	v_mov_b32_e32 v135, v0
	v_mov_b32_e32 v140, v0
	v_mov_b32_e32 v141, v0
	v_mov_b32_e32 v142, v0
	v_mov_b32_e32 v143, v0
	s_add_i32 s80, s12, 2
	s_cmp_eq_u32 s71, s12
	s_cselect_b32 s20, s0, s46
	s_cselect_b32 s21, s1, s47
	s_cselect_b32 s16, s44, s78
	s_cselect_b32 s17, s45, s79
	s_add_u32 s12, s20, 0x80
	s_addc_u32 s13, s21, 0
	s_add_i32 s81, 0, 0x10000
	v_add_u32_e32 v136, s81, v216
; #define PG8_STAGE(bufoff, gbase, voff) do { const char* _gb = (const char*)(gbase); asm volatile("" : "+s"(_gb)); _Pragma("unroll") for (int _i = 0; _i < 2; ++_i) { unsigned _vo = (voff)[_i]; asm volatile("" : "+v"(_vo)); \
;         __builtin_amdgcn_global_load_lds((const GAS unsigned*)(_gb + _vo), (LAS unsigned*)(lds + (bufoff) + ldsw + _i * 8192), 16, 0, 0); } } while (0)
; #define PG8_LDA(dst, b, h) do { _Pragma("unroll") for (int m = 0; m < 4; ++m) _Pragma("unroll") for (int k = 0; k < 2; ++k) dst[m][k] = *(const LAS bf16x8*)(lds + PG8_SA(b, h) + aoff + m * 2048 + k * 1024); } while (0)
; #define PG8_LDB(dst, b, h) do { _Pragma("unroll") for (int n = 0; n < 2; ++n) _Pragma("unroll") for (int k = 0; k < 2; ++k) dst[n][k] = *(const LAS bf16x8*)(lds + PG8_SB(b, h) + boff + n * 2048 + k * 1024); } while (0)
; #define PG8_MMA(ai, bj, At, Bt) do { __builtin_amdgcn_s_setprio(1); _Pragma("unroll") for (int m = 0; m < 4; ++m) _Pragma("unroll") for (int n = 0; n < 2; ++n) _Pragma("unroll") for (int k = 0; k < 2; ++k) \
;         acc[ai][bj][m][n] = __builtin_amdgcn_mfma_f32_16x16x32_bf16(Bt[n][k], At[m][k], acc[ai][bj][m][n], 0, 0, 0); __builtin_amdgcn_s_setprio(0); } while (0)
; #define PG8_WAIT_L(n) asm volatile("s_waitcnt lgkmcnt(" #n ")" ::: "memory")
; #define PG8_BAR __builtin_amdgcn_s_barrier()
; #define PG8_SCHED __builtin_amdgcn_sched_barrier(0)
; template <class Epi, class Ord>
; __device__ __forceinline__ void gemm_phase(LAS unsigned char* lds, const Gemm g, const Ord& S, const Epi& E) {
;     ...
;             PG8_LDB(B0, 0, 0); PG8_SCHED; PG8_LDA(At, 0, 0); PG8_STAGE(PG8_SA(1, 1), a1 + hstep, voffA);
;             PG8_WAIT_L(8); PG8_BAR; PG8_WAIT_L(0); PG8_MMA(0, 0, At, B0); PG8_BAR; PG8_SCHED;
;             PG8_LDB(B1, 0, 1); PG8_STAGE(PG8_SB(0, 0), b2, voffB);
;             PG8_BAR; PG8_WAIT_L(0); PG8_MMA(0, 1, At, B1); PG8_BAR;
;             PG8_LDA(At, 0, 1); PG8_STAGE(PG8_SA(0, 0), a2, voffA);
;             PG8_BAR; PG8_WAIT_L(0); PG8_MMA(1, 0, At, B0); PG8_BAR; PG8_SCHED;
.LBB0_312:
	ds_read_b128 v[116:119], v136
	ds_read_b128 v[124:127], v136 offset:1024
	ds_read_b128 v[128:131], v136 offset:2048
	ds_read_b128 v[136:139], v136 offset:3072
	s_add_u32 s22, s46, s10
	s_addc_u32 s23, s47, s11
	s_add_u32 s22, s22, 0xffffff80
	s_addc_u32 s23, s23, -1
	v_mov_b32_e32 v206, v211
	ds_read_b128 v[144:147], v168
	ds_read_b128 v[148:151], v168 offset:1024
	ds_read_b128 v[152:155], v168 offset:2048
	ds_read_b128 v[156:159], v168 offset:3072
	ds_read_b128 v[194:197], v168 offset:4096
	ds_read_b128 v[198:201], v168 offset:5120
	ds_read_b128 v[202:205], v168 offset:6144
	ds_read_b128 v[218:221], v168 offset:7168
	s_add_i32 m0, s57, 0xc000
	s_nop 0
	global_load_lds_dwordx4 v206, s[22:23]
	v_mov_b32_e32 v206, v213
	s_add_i32 m0, s57, 0xe000
	s_nop 0
	global_load_lds_dwordx4 v206, s[22:23]
	s_waitcnt lgkmcnt(8)
	s_barrier
	s_waitcnt lgkmcnt(0)
	s_setprio 1
	s_waitcnt lgkmcnt(0)
	v_mfma_f32_16x16x32_bf16 v[140:143], v[116:119], v[144:147], v[140:143]
	v_mfma_f32_16x16x32_bf16 v[132:135], v[128:131], v[144:147], v[132:135]
	v_mfma_f32_16x16x32_bf16 v[108:111], v[116:119], v[152:155], v[108:111]
	v_mfma_f32_16x16x32_bf16 v[104:107], v[128:131], v[152:155], v[104:107]
	v_mfma_f32_16x16x32_bf16 v[92:95], v[116:119], v[194:197], v[92:95]
	v_mfma_f32_16x16x32_bf16 v[88:91], v[128:131], v[194:197], v[88:91]
	v_mfma_f32_16x16x32_bf16 v[76:79], v[116:119], v[202:205], v[76:79]
	v_mfma_f32_16x16x32_bf16 v[72:75], v[128:131], v[202:205], v[72:75]
	v_mfma_f32_16x16x32_bf16 v[140:143], v[124:127], v[148:151], v[140:143]
	v_mfma_f32_16x16x32_bf16 v[132:135], v[136:139], v[148:151], v[132:135]
	v_mfma_f32_16x16x32_bf16 v[108:111], v[124:127], v[156:159], v[108:111]
	v_mfma_f32_16x16x32_bf16 v[104:107], v[136:139], v[156:159], v[104:107]
	v_mfma_f32_16x16x32_bf16 v[92:95], v[124:127], v[198:201], v[92:95]
	v_mfma_f32_16x16x32_bf16 v[88:91], v[136:139], v[198:201], v[88:91]
	v_mfma_f32_16x16x32_bf16 v[76:79], v[124:127], v[218:221], v[76:79]
	v_mfma_f32_16x16x32_bf16 v[72:75], v[136:139], v[218:221], v[72:75]
	s_setprio 0
	s_barrier
	s_add_i32 s84, 0, 0x14000
	v_add_u32_e32 v206, s84, v216
	ds_read_b128 v[222:225], v206
	ds_read_b128 v[226:229], v206 offset:1024
	ds_read_b128 v[230:233], v206 offset:2048
	ds_read_b128 v[234:237], v206 offset:3072
	s_mov_b64 s[22:23], s[16:17]
	v_mov_b32_e32 v206, v212
	s_add_i32 s81, s81, s56
	s_mov_b32 m0, s81
	s_nop 0
	global_load_lds_dwordx4 v206, s[22:23]
	v_mov_b32_e32 v206, v214
	s_add_i32 m0, s81, 0x2000
	s_nop 0
	global_load_lds_dwordx4 v206, s[22:23]
	s_barrier
	s_waitcnt lgkmcnt(0)
	s_setprio 1
	s_waitcnt lgkmcnt(0)
	v_mfma_f32_16x16x32_bf16 v[120:123], v[222:225], v[144:147], v[120:123]
	v_mfma_f32_16x16x32_bf16 v[112:115], v[230:233], v[144:147], v[112:115]
	v_mfma_f32_16x16x32_bf16 v[100:103], v[222:225], v[152:155], v[100:103]
	v_mfma_f32_16x16x32_bf16 v[96:99], v[230:233], v[152:155], v[96:99]
	v_mfma_f32_16x16x32_bf16 v[84:87], v[222:225], v[194:197], v[84:87]
	v_mfma_f32_16x16x32_bf16 v[80:83], v[230:233], v[194:197], v[80:83]
	v_mfma_f32_16x16x32_bf16 v[68:71], v[222:225], v[202:205], v[68:71]
	v_mfma_f32_16x16x32_bf16 v[64:67], v[230:233], v[202:205], v[64:67]
	v_mfma_f32_16x16x32_bf16 v[120:123], v[226:229], v[148:151], v[120:123]
	v_mfma_f32_16x16x32_bf16 v[112:115], v[234:237], v[148:151], v[112:115]
	v_mfma_f32_16x16x32_bf16 v[100:103], v[226:229], v[156:159], v[100:103]
	v_mfma_f32_16x16x32_bf16 v[96:99], v[234:237], v[156:159], v[96:99]
	v_mfma_f32_16x16x32_bf16 v[84:87], v[226:229], v[198:201], v[84:87]
	v_mfma_f32_16x16x32_bf16 v[80:83], v[234:237], v[198:201], v[80:83]
	v_mfma_f32_16x16x32_bf16 v[68:71], v[226:229], v[218:221], v[68:71]
	v_mfma_f32_16x16x32_bf16 v[64:67], v[234:237], v[218:221], v[64:67]
	s_setprio 0
	s_mov_b64 s[22:23], s[20:21]
	v_mov_b32_e32 v206, v211
	s_mov_b32 m0, s57
	s_barrier
	ds_read_b128 v[144:147], v168 offset:16384
	ds_read_b128 v[148:151], v168 offset:17408
	ds_read_b128 v[152:155], v168 offset:18432
	ds_read_b128 v[156:159], v168 offset:19456
	ds_read_b128 v[194:197], v168 offset:20480
	ds_read_b128 v[198:201], v168 offset:21504
	ds_read_b128 v[202:205], v168 offset:22528
	ds_read_b128 v[218:221], v168 offset:23552
	s_nop 0
	global_load_lds_dwordx4 v206, s[22:23]
	v_mov_b32_e32 v206, v213
	s_mov_b32 m0, s62
	s_nop 0
	global_load_lds_dwordx4 v206, s[22:23]
	s_barrier
	s_waitcnt lgkmcnt(0)
	s_setprio 1
	s_waitcnt lgkmcnt(0)
	v_mfma_f32_16x16x32_bf16 v[60:63], v[116:119], v[144:147], v[60:63]
	v_mfma_f32_16x16x32_bf16 v[56:59], v[128:131], v[144:147], v[56:59]
	v_mfma_f32_16x16x32_bf16 v[44:47], v[116:119], v[152:155], v[44:47]
	v_mfma_f32_16x16x32_bf16 v[40:43], v[128:131], v[152:155], v[40:43]
	v_mfma_f32_16x16x32_bf16 v[28:31], v[116:119], v[194:197], v[28:31]
	v_mfma_f32_16x16x32_bf16 v[24:27], v[128:131], v[194:197], v[24:27]
	v_mfma_f32_16x16x32_bf16 v[12:15], v[116:119], v[202:205], v[12:15]
	v_mfma_f32_16x16x32_bf16 v[8:11], v[128:131], v[202:205], v[8:11]
	v_mfma_f32_16x16x32_bf16 v[60:63], v[124:127], v[148:151], v[60:63]
	v_mfma_f32_16x16x32_bf16 v[56:59], v[136:139], v[148:151], v[56:59]
	v_mfma_f32_16x16x32_bf16 v[44:47], v[124:127], v[156:159], v[44:47]
	v_mfma_f32_16x16x32_bf16 v[40:43], v[136:139], v[156:159], v[40:43]
	v_mfma_f32_16x16x32_bf16 v[28:31], v[124:127], v[198:201], v[28:31]
	v_mfma_f32_16x16x32_bf16 v[24:27], v[136:139], v[198:201], v[24:27]
	v_mfma_f32_16x16x32_bf16 v[12:15], v[124:127], v[218:221], v[12:15]
	v_mfma_f32_16x16x32_bf16 v[8:11], v[136:139], v[218:221], v[8:11]
	s_setprio 0
	s_barrier
; #define PG8_STAGE(bufoff, gbase, voff) do { const char* _gb = (const char*)(gbase); asm volatile("" : "+s"(_gb)); _Pragma("unroll") for (int _i = 0; _i < 2; ++_i) { unsigned _vo = (voff)[_i]; asm volatile("" : "+v"(_vo)); \
;         __builtin_amdgcn_global_load_lds((const GAS unsigned*)(_gb + _vo), (LAS unsigned*)(lds + (bufoff) + ldsw + _i * 8192), 16, 0, 0); } } while (0)
; #define PG8_LDA(dst, b, h) do { _Pragma("unroll") for (int m = 0; m < 4; ++m) _Pragma("unroll") for (int k = 0; k < 2; ++k) dst[m][k] = *(const LAS bf16x8*)(lds + PG8_SA(b, h) + aoff + m * 2048 + k * 1024); } while (0)
; #define PG8_LDB(dst, b, h) do { _Pragma("unroll") for (int n = 0; n < 2; ++n) _Pragma("unroll") for (int k = 0; k < 2; ++k) dst[n][k] = *(const LAS bf16x8*)(lds + PG8_SB(b, h) + boff + n * 2048 + k * 1024); } while (0)
; #define PG8_MMA(ai, bj, At, Bt) do { __builtin_amdgcn_s_setprio(1); _Pragma("unroll") for (int m = 0; m < 4; ++m) _Pragma("unroll") for (int n = 0; n < 2; ++n) _Pragma("unroll") for (int k = 0; k < 2; ++k) \
;         acc[ai][bj][m][n] = __builtin_amdgcn_mfma_f32_16x16x32_bf16(Bt[n][k], At[m][k], acc[ai][bj][m][n], 0, 0, 0); __builtin_amdgcn_s_setprio(0); } while (0)
; #define PG8_WAIT_V(n) asm volatile("s_waitcnt vmcnt(" #n ")" ::: "memory")
; #define PG8_WAIT_L(n) asm volatile("s_waitcnt lgkmcnt(" #n ")" ::: "memory")
; #define PG8_BAR __builtin_amdgcn_s_barrier()
; #define PG8_SCHED __builtin_amdgcn_sched_barrier(0)
; template <class Epi, class Ord>
; __device__ __forceinline__ void gemm_phase(LAS unsigned char* lds, const Gemm g, const Ord& S, const Epi& E) {
;     ...
;             PG8_STAGE(PG8_SB(0, 1), b2 + hstep, voffB);
;             PG8_WAIT_V(6); PG8_BAR; PG8_MMA(1, 1, At, B1); PG8_BAR;
;             PG8_LDB(B0, 1, 0); PG8_SCHED; PG8_LDA(At, 1, 0); PG8_STAGE(PG8_SA(0, 1), a2 + hstep, voffA);
;             PG8_WAIT_L(8); PG8_BAR; PG8_WAIT_L(0); PG8_MMA(0, 0, At, B0); PG8_BAR; PG8_SCHED;
;             PG8_LDB(B1, 1, 1); PG8_STAGE(PG8_SB(1, 0), b3, voffB);
	s_add_u32 s22, s16, s10
	s_addc_u32 s23, s17, s11
	s_mov_b64 s[82:83], s[22:23]
	v_mov_b32_e32 v116, v212
	s_add_i32 s81, s84, s56
	s_mov_b32 m0, s81
	s_nop 0
	global_load_lds_dwordx4 v116, s[82:83]
	v_mov_b32_e32 v116, v214
	s_add_i32 m0, s81, 0x2000
	s_nop 0
	global_load_lds_dwordx4 v116, s[82:83]
	s_waitcnt vmcnt(6)
	s_barrier
	s_setprio 1
	v_mfma_f32_16x16x32_bf16 v[52:55], v[222:225], v[144:147], v[52:55]
	v_mfma_f32_16x16x32_bf16 v[48:51], v[230:233], v[144:147], v[48:51]
	v_mfma_f32_16x16x32_bf16 v[36:39], v[222:225], v[152:155], v[36:39]
	v_mfma_f32_16x16x32_bf16 v[32:35], v[230:233], v[152:155], v[32:35]
	v_mfma_f32_16x16x32_bf16 v[20:23], v[222:225], v[194:197], v[20:23]
	v_mfma_f32_16x16x32_bf16 v[16:19], v[230:233], v[194:197], v[16:19]
	v_mfma_f32_16x16x32_bf16 v[4:7], v[222:225], v[202:205], v[4:7]
	v_mfma_f32_16x16x32_bf16 v[0:3], v[230:233], v[202:205], v[0:3]
	v_mfma_f32_16x16x32_bf16 v[52:55], v[226:229], v[148:151], v[52:55]
	v_mfma_f32_16x16x32_bf16 v[48:51], v[234:237], v[148:151], v[48:51]
	v_mfma_f32_16x16x32_bf16 v[36:39], v[226:229], v[156:159], v[36:39]
	v_mfma_f32_16x16x32_bf16 v[32:35], v[234:237], v[156:159], v[32:35]
	v_mfma_f32_16x16x32_bf16 v[20:23], v[226:229], v[198:201], v[20:23]
	v_mfma_f32_16x16x32_bf16 v[16:19], v[234:237], v[198:201], v[16:19]
	v_mfma_f32_16x16x32_bf16 v[4:7], v[226:229], v[218:221], v[4:7]
	v_mfma_f32_16x16x32_bf16 v[0:3], v[234:237], v[218:221], v[0:3]
	s_setprio 0
	s_add_i32 s81, 0, 0x18000
	v_add_u32_e32 v136, s81, v216
	s_barrier
	ds_read_b128 v[116:119], v136
	ds_read_b128 v[124:127], v136 offset:1024
	ds_read_b128 v[128:131], v136 offset:2048
	ds_read_b128 v[136:139], v136 offset:3072
	s_add_u32 s20, s20, s10
	s_addc_u32 s21, s21, s11
	v_mov_b32_e32 v206, v211
	s_mov_b32 m0, s64
	ds_read_b128 v[144:147], v168 offset:32768
	ds_read_b128 v[148:151], v168 offset:33792
	ds_read_b128 v[152:155], v168 offset:34816
	ds_read_b128 v[156:159], v168 offset:35840
	ds_read_b128 v[194:197], v168 offset:36864
	ds_read_b128 v[198:201], v168 offset:37888
	ds_read_b128 v[202:205], v168 offset:38912
	ds_read_b128 v[218:221], v168 offset:39936
	s_nop 0
	global_load_lds_dwordx4 v206, s[20:21]
	v_mov_b32_e32 v206, v213
	s_mov_b32 m0, s65
	s_nop 0
	global_load_lds_dwordx4 v206, s[20:21]
	s_waitcnt lgkmcnt(8)
	s_barrier
	s_waitcnt lgkmcnt(0)
	s_setprio 1
	s_waitcnt lgkmcnt(0)
	v_mfma_f32_16x16x32_bf16 v[140:143], v[116:119], v[144:147], v[140:143]
	v_mfma_f32_16x16x32_bf16 v[132:135], v[128:131], v[144:147], v[132:135]
	v_mfma_f32_16x16x32_bf16 v[108:111], v[116:119], v[152:155], v[108:111]
	v_mfma_f32_16x16x32_bf16 v[104:107], v[128:131], v[152:155], v[104:107]
	v_mfma_f32_16x16x32_bf16 v[92:95], v[116:119], v[194:197], v[92:95]
	v_mfma_f32_16x16x32_bf16 v[88:91], v[128:131], v[194:197], v[88:91]
	v_mfma_f32_16x16x32_bf16 v[76:79], v[116:119], v[202:205], v[76:79]
	v_mfma_f32_16x16x32_bf16 v[72:75], v[128:131], v[202:205], v[72:75]
	v_mfma_f32_16x16x32_bf16 v[140:143], v[124:127], v[148:151], v[140:143]
	v_mfma_f32_16x16x32_bf16 v[132:135], v[136:139], v[148:151], v[132:135]
	v_mfma_f32_16x16x32_bf16 v[108:111], v[124:127], v[156:159], v[108:111]
	v_mfma_f32_16x16x32_bf16 v[104:107], v[136:139], v[156:159], v[104:107]
	v_mfma_f32_16x16x32_bf16 v[92:95], v[124:127], v[198:201], v[92:95]
	v_mfma_f32_16x16x32_bf16 v[88:91], v[136:139], v[198:201], v[88:91]
	v_mfma_f32_16x16x32_bf16 v[76:79], v[124:127], v[218:221], v[76:79]
	v_mfma_f32_16x16x32_bf16 v[72:75], v[136:139], v[218:221], v[72:75]
	s_setprio 0
	s_barrier
	s_add_i32 s20, 0, 0x1c000
	v_add_u32_e32 v206, s20, v216
	s_add_u32 s16, s16, 0x80
	ds_read_b128 v[222:225], v206
	ds_read_b128 v[226:229], v206 offset:1024
	ds_read_b128 v[230:233], v206 offset:2048
	ds_read_b128 v[234:237], v206 offset:3072
	s_addc_u32 s17, s17, 0
	v_mov_b32_e32 v206, v212
	s_add_i32 s21, s81, s56
	s_mov_b32 m0, s21
	s_nop 0
	global_load_lds_dwordx4 v206, s[16:17]
	v_mov_b32_e32 v206, v214
	s_add_i32 m0, s21, 0x2000
	s_nop 0
	global_load_lds_dwordx4 v206, s[16:17]
	s_barrier
; #define PG8_STAGE(bufoff, gbase, voff) do { const char* _gb = (const char*)(gbase); asm volatile("" : "+s"(_gb)); _Pragma("unroll") for (int _i = 0; _i < 2; ++_i) { unsigned _vo = (voff)[_i]; asm volatile("" : "+v"(_vo)); \
;         __builtin_amdgcn_global_load_lds((const GAS unsigned*)(_gb + _vo), (LAS unsigned*)(lds + (bufoff) + ldsw + _i * 8192), 16, 0, 0); } } while (0)
; #define PG8_LDA(dst, b, h) do { _Pragma("unroll") for (int m = 0; m < 4; ++m) _Pragma("unroll") for (int k = 0; k < 2; ++k) dst[m][k] = *(const LAS bf16x8*)(lds + PG8_SA(b, h) + aoff + m * 2048 + k * 1024); } while (0)
; #define PG8_MMA(ai, bj, At, Bt) do { __builtin_amdgcn_s_setprio(1); _Pragma("unroll") for (int m = 0; m < 4; ++m) _Pragma("unroll") for (int n = 0; n < 2; ++n) _Pragma("unroll") for (int k = 0; k < 2; ++k) \
;         acc[ai][bj][m][n] = __builtin_amdgcn_mfma_f32_16x16x32_bf16(Bt[n][k], At[m][k], acc[ai][bj][m][n], 0, 0, 0); __builtin_amdgcn_s_setprio(0); } while (0)
; #define PG8_WAIT_V(n) asm volatile("s_waitcnt vmcnt(" #n ")" ::: "memory")
; #define PG8_WAIT_L(n) asm volatile("s_waitcnt lgkmcnt(" #n ")" ::: "memory")
; #define PG8_BAR __builtin_amdgcn_s_barrier()
; #define PG8_SCHED __builtin_amdgcn_sched_barrier(0)
; template <class Epi, class Ord>
; __device__ __forceinline__ void gemm_phase(LAS unsigned char* lds, const Gemm g, const Ord& S, const Epi& E) {
;     ...
;             PG8_BAR; PG8_WAIT_L(0); PG8_MMA(0, 1, At, B1); PG8_BAR;
;             PG8_LDA(At, 1, 1); PG8_STAGE(PG8_SA(1, 0), a3, voffA);
;             PG8_BAR; PG8_WAIT_L(0); PG8_MMA(1, 0, At, B0); PG8_BAR; PG8_SCHED;
;             PG8_STAGE(PG8_SB(1, 1), b3 + hstep, voffB);
;             PG8_WAIT_V(6); PG8_BAR; PG8_MMA(1, 1, At, B1); PG8_BAR;
;         }
	s_waitcnt lgkmcnt(0)
	s_setprio 1
	s_waitcnt lgkmcnt(0)
	v_mfma_f32_16x16x32_bf16 v[120:123], v[222:225], v[144:147], v[120:123]
	v_mfma_f32_16x16x32_bf16 v[112:115], v[230:233], v[144:147], v[112:115]
	v_mfma_f32_16x16x32_bf16 v[100:103], v[222:225], v[152:155], v[100:103]
	v_mfma_f32_16x16x32_bf16 v[96:99], v[230:233], v[152:155], v[96:99]
	v_mfma_f32_16x16x32_bf16 v[84:87], v[222:225], v[194:197], v[84:87]
	v_mfma_f32_16x16x32_bf16 v[80:83], v[230:233], v[194:197], v[80:83]
	v_mfma_f32_16x16x32_bf16 v[68:71], v[222:225], v[202:205], v[68:71]
	v_mfma_f32_16x16x32_bf16 v[64:67], v[230:233], v[202:205], v[64:67]
	v_mfma_f32_16x16x32_bf16 v[120:123], v[226:229], v[148:151], v[120:123]
	v_mfma_f32_16x16x32_bf16 v[112:115], v[234:237], v[148:151], v[112:115]
	v_mfma_f32_16x16x32_bf16 v[100:103], v[226:229], v[156:159], v[100:103]
	v_mfma_f32_16x16x32_bf16 v[96:99], v[234:237], v[156:159], v[96:99]
	v_mfma_f32_16x16x32_bf16 v[84:87], v[226:229], v[198:201], v[84:87]
	v_mfma_f32_16x16x32_bf16 v[80:83], v[234:237], v[198:201], v[80:83]
	v_mfma_f32_16x16x32_bf16 v[68:71], v[226:229], v[218:221], v[68:71]
	v_mfma_f32_16x16x32_bf16 v[64:67], v[234:237], v[218:221], v[64:67]
	s_setprio 0
	v_mov_b32_e32 v206, v211
	s_mov_b32 m0, s69
	s_barrier
	ds_read_b128 v[144:147], v168 offset:49152
	ds_read_b128 v[148:151], v168 offset:50176
	ds_read_b128 v[152:155], v168 offset:51200
	ds_read_b128 v[156:159], v168 offset:52224
	ds_read_b128 v[194:197], v168 offset:53248
	ds_read_b128 v[198:201], v168 offset:54272
	ds_read_b128 v[202:205], v168 offset:55296
	ds_read_b128 v[218:221], v168 offset:56320
	s_nop 0
	global_load_lds_dwordx4 v206, s[12:13]
	v_mov_b32_e32 v206, v213
	s_mov_b32 m0, s70
	s_nop 0
	global_load_lds_dwordx4 v206, s[12:13]
	s_barrier
	s_waitcnt lgkmcnt(0)
	s_setprio 1
	s_waitcnt lgkmcnt(0)
	v_mfma_f32_16x16x32_bf16 v[60:63], v[116:119], v[144:147], v[60:63]
	v_mfma_f32_16x16x32_bf16 v[56:59], v[128:131], v[144:147], v[56:59]
	v_mfma_f32_16x16x32_bf16 v[44:47], v[116:119], v[152:155], v[44:47]
	v_mfma_f32_16x16x32_bf16 v[40:43], v[128:131], v[152:155], v[40:43]
	v_mfma_f32_16x16x32_bf16 v[28:31], v[116:119], v[194:197], v[28:31]
	v_mfma_f32_16x16x32_bf16 v[24:27], v[128:131], v[194:197], v[24:27]
	v_mfma_f32_16x16x32_bf16 v[12:15], v[116:119], v[202:205], v[12:15]
	v_mfma_f32_16x16x32_bf16 v[8:11], v[128:131], v[202:205], v[8:11]
	v_mfma_f32_16x16x32_bf16 v[60:63], v[124:127], v[148:151], v[60:63]
	v_mfma_f32_16x16x32_bf16 v[56:59], v[136:139], v[148:151], v[56:59]
	v_mfma_f32_16x16x32_bf16 v[44:47], v[124:127], v[156:159], v[44:47]
	v_mfma_f32_16x16x32_bf16 v[40:43], v[136:139], v[156:159], v[40:43]
	v_mfma_f32_16x16x32_bf16 v[28:31], v[124:127], v[198:201], v[28:31]
	v_mfma_f32_16x16x32_bf16 v[24:27], v[136:139], v[198:201], v[24:27]
	v_mfma_f32_16x16x32_bf16 v[12:15], v[124:127], v[218:221], v[12:15]
	v_mfma_f32_16x16x32_bf16 v[8:11], v[136:139], v[218:221], v[8:11]
	s_setprio 0
	s_barrier
	s_add_u32 s12, s22, 0x80
	s_addc_u32 s13, s23, 0
	v_mov_b32_e32 v116, v212
	s_add_i32 s16, s20, s56
	s_mov_b32 m0, s16
	s_nop 0
	global_load_lds_dwordx4 v116, s[12:13]
	v_mov_b32_e32 v116, v214
	s_add_i32 m0, s16, 0x2000
	s_nop 0
	global_load_lds_dwordx4 v116, s[12:13]
	s_waitcnt vmcnt(6)
	s_barrier
	s_setprio 1
	v_mfma_f32_16x16x32_bf16 v[52:55], v[222:225], v[144:147], v[52:55]
	v_mfma_f32_16x16x32_bf16 v[48:51], v[230:233], v[144:147], v[48:51]
	v_mfma_f32_16x16x32_bf16 v[36:39], v[222:225], v[152:155], v[36:39]
	v_mfma_f32_16x16x32_bf16 v[32:35], v[230:233], v[152:155], v[32:35]
	v_mfma_f32_16x16x32_bf16 v[20:23], v[222:225], v[194:197], v[20:23]
	v_mfma_f32_16x16x32_bf16 v[16:19], v[230:233], v[194:197], v[16:19]
	v_mfma_f32_16x16x32_bf16 v[4:7], v[222:225], v[202:205], v[4:7]
	v_mfma_f32_16x16x32_bf16 v[0:3], v[230:233], v[202:205], v[0:3]
	v_mfma_f32_16x16x32_bf16 v[52:55], v[226:229], v[148:151], v[52:55]
	v_mfma_f32_16x16x32_bf16 v[48:51], v[234:237], v[148:151], v[48:51]
	v_mfma_f32_16x16x32_bf16 v[36:39], v[226:229], v[156:159], v[36:39]
	v_mfma_f32_16x16x32_bf16 v[32:35], v[234:237], v[156:159], v[32:35]
	v_mfma_f32_16x16x32_bf16 v[20:23], v[226:229], v[198:201], v[20:23]
	v_mfma_f32_16x16x32_bf16 v[16:19], v[234:237], v[198:201], v[16:19]
	v_mfma_f32_16x16x32_bf16 v[4:7], v[226:229], v[218:221], v[4:7]
	v_mfma_f32_16x16x32_bf16 v[0:3], v[234:237], v[218:221], v[0:3]
	s_setprio 0
	s_add_u32 s78, s78, 0x100
	s_addc_u32 s79, s79, 0
	s_add_u32 s46, s46, 0x100
	s_addc_u32 s47, s47, 0
	s_mov_b32 s12, s80
	s_add_i32 s80, s12, 2
	s_cmp_eq_u32 s71, s12
	s_cselect_b32 s20, s0, s46
	s_cselect_b32 s21, s1, s47
	s_cselect_b32 s16, s44, s78
	s_cselect_b32 s17, s45, s79
	s_add_u32 s12, s20, 0x80
	s_addc_u32 s13, s21, 0
	s_add_i32 s81, 0, 0x10000
	v_add_u32_e32 v136, s81, v216
	s_sub_i32 s98, s80, 2
	s_cmp_ge_i32 s98, s68
	s_barrier
	s_cbranch_scc0 .LBB0_312
	s_branch .LBB0_299

; template <class Epi, class Ord>
; __device__ __forceinline__ void gemm_phase(LAS unsigned char* lds, const Gemm g, const Ord& S, const Epi& E) {
;     ...
;             const bool last = (t == nt - 2);
;             const char* a1 = cA + (size_t)(t + 1) * kstep;
;             const char* a2 = last ? nA : cA + (size_t)(t + 2) * kstep; const char* b2 = last ? nB : cB + (size_t)(t + 2) * kstep;
;             const char* a3 = a2 + kstep; const char* b3 = b2 + kstep;
;     ...
;         for (int a = 0; a < 2; ++a)
; #pragma unroll
;             for (int b = 0; b < 2; ++b)
; #pragma unroll
;                 for (int m = 0; m < 4; ++m)
; #pragma unroll
;                     for (int n = 0; n < 2; ++n) acc[a][b][m][n] = (f32x4){0.f, 0.f, 0.f, 0.f};
;         cur = nxt; cA = nA; cB = nB; ++ui;
.LBB0_496:
	v_mov_b32_e32 v127, 0
	v_mov_b32_e32 v126, 0
	s_andn2_b64 vcc, exec, s[16:17]
	v_pk_mov_b32 v[124:125], v[126:127], v[126:127]
	v_pk_mov_b32 v[122:123], v[126:127], v[126:127]
	v_pk_mov_b32 v[120:121], v[126:127], v[126:127]
	v_pk_mov_b32 v[110:111], v[126:127], v[126:127]
	v_pk_mov_b32 v[108:109], v[126:127], v[126:127]
	v_pk_mov_b32 v[106:107], v[126:127], v[126:127]
	v_pk_mov_b32 v[104:105], v[126:127], v[126:127]
	v_pk_mov_b32 v[94:95], v[126:127], v[126:127]
	v_pk_mov_b32 v[92:93], v[126:127], v[126:127]
	v_pk_mov_b32 v[90:91], v[126:127], v[126:127]
	v_pk_mov_b32 v[88:89], v[126:127], v[126:127]
	v_pk_mov_b32 v[78:79], v[126:127], v[126:127]
	v_pk_mov_b32 v[76:77], v[126:127], v[126:127]
	v_pk_mov_b32 v[74:75], v[126:127], v[126:127]
	v_pk_mov_b32 v[72:73], v[126:127], v[126:127]
	v_pk_mov_b32 v[118:119], v[126:127], v[126:127]
	v_pk_mov_b32 v[116:117], v[126:127], v[126:127]
	v_pk_mov_b32 v[114:115], v[126:127], v[126:127]
	v_pk_mov_b32 v[112:113], v[126:127], v[126:127]
	v_pk_mov_b32 v[102:103], v[126:127], v[126:127]
	v_pk_mov_b32 v[100:101], v[126:127], v[126:127]
	v_pk_mov_b32 v[98:99], v[126:127], v[126:127]
	v_pk_mov_b32 v[96:97], v[126:127], v[126:127]
	v_pk_mov_b32 v[86:87], v[126:127], v[126:127]
	v_pk_mov_b32 v[84:85], v[126:127], v[126:127]
	v_pk_mov_b32 v[82:83], v[126:127], v[126:127]
	v_pk_mov_b32 v[80:81], v[126:127], v[126:127]
	v_pk_mov_b32 v[70:71], v[126:127], v[126:127]
	v_pk_mov_b32 v[68:69], v[126:127], v[126:127]
	v_pk_mov_b32 v[66:67], v[126:127], v[126:127]
	v_pk_mov_b32 v[64:65], v[126:127], v[126:127]
	v_pk_mov_b32 v[62:63], v[126:127], v[126:127]
	v_pk_mov_b32 v[60:61], v[126:127], v[126:127]
	v_pk_mov_b32 v[58:59], v[126:127], v[126:127]
	v_pk_mov_b32 v[56:57], v[126:127], v[126:127]
	v_pk_mov_b32 v[46:47], v[126:127], v[126:127]
	v_pk_mov_b32 v[44:45], v[126:127], v[126:127]
	v_pk_mov_b32 v[42:43], v[126:127], v[126:127]
	v_pk_mov_b32 v[40:41], v[126:127], v[126:127]
	v_pk_mov_b32 v[30:31], v[126:127], v[126:127]
	v_pk_mov_b32 v[28:29], v[126:127], v[126:127]
	v_pk_mov_b32 v[26:27], v[126:127], v[126:127]
	v_pk_mov_b32 v[24:25], v[126:127], v[126:127]
	v_pk_mov_b32 v[14:15], v[126:127], v[126:127]
	v_pk_mov_b32 v[12:13], v[126:127], v[126:127]
	v_pk_mov_b32 v[10:11], v[126:127], v[126:127]
	v_pk_mov_b32 v[8:9], v[126:127], v[126:127]
	v_pk_mov_b32 v[54:55], v[126:127], v[126:127]
	v_pk_mov_b32 v[52:53], v[126:127], v[126:127]
	v_pk_mov_b32 v[50:51], v[126:127], v[126:127]
	v_pk_mov_b32 v[48:49], v[126:127], v[126:127]
	v_pk_mov_b32 v[38:39], v[126:127], v[126:127]
	v_pk_mov_b32 v[36:37], v[126:127], v[126:127]
	v_pk_mov_b32 v[34:35], v[126:127], v[126:127]
	v_pk_mov_b32 v[32:33], v[126:127], v[126:127]
	v_pk_mov_b32 v[22:23], v[126:127], v[126:127]
	v_pk_mov_b32 v[20:21], v[126:127], v[126:127]
	v_pk_mov_b32 v[18:19], v[126:127], v[126:127]
	v_pk_mov_b32 v[16:17], v[126:127], v[126:127]
	v_pk_mov_b32 v[6:7], v[126:127], v[126:127]
	v_pk_mov_b32 v[4:5], v[126:127], v[126:127]
	v_pk_mov_b32 v[2:3], v[126:127], v[126:127]
	v_pk_mov_b32 v[0:1], v[126:127], v[126:127]
	s_cbranch_vccnz .LBB0_484
	s_add_u32 s46, s46, 0x100
	s_addc_u32 s47, s47, 0
	s_add_u32 s48, s48, 0x100
	v_mov_b32_e32 v0, 0
	v_mov_b32_e32 v1, 0
	s_addc_u32 s49, s49, 0
	s_mov_b32 s12, 0
	v_pk_mov_b32 v[2:3], v[0:1], v[0:1]
	v_pk_mov_b32 v[4:5], v[0:1], v[0:1]
	v_pk_mov_b32 v[6:7], v[0:1], v[0:1]
	v_pk_mov_b32 v[16:17], v[0:1], v[0:1]
	v_pk_mov_b32 v[18:19], v[0:1], v[0:1]
	v_pk_mov_b32 v[20:21], v[0:1], v[0:1]
	v_pk_mov_b32 v[22:23], v[0:1], v[0:1]
	v_pk_mov_b32 v[32:33], v[0:1], v[0:1]
	v_pk_mov_b32 v[34:35], v[0:1], v[0:1]
	v_pk_mov_b32 v[36:37], v[0:1], v[0:1]
	v_pk_mov_b32 v[38:39], v[0:1], v[0:1]
	v_pk_mov_b32 v[48:49], v[0:1], v[0:1]
	v_pk_mov_b32 v[50:51], v[0:1], v[0:1]
	v_pk_mov_b32 v[52:53], v[0:1], v[0:1]
	v_pk_mov_b32 v[54:55], v[0:1], v[0:1]
	v_pk_mov_b32 v[8:9], v[0:1], v[0:1]
	v_pk_mov_b32 v[10:11], v[0:1], v[0:1]
	v_pk_mov_b32 v[12:13], v[0:1], v[0:1]
	v_pk_mov_b32 v[14:15], v[0:1], v[0:1]
	v_pk_mov_b32 v[24:25], v[0:1], v[0:1]
	v_pk_mov_b32 v[26:27], v[0:1], v[0:1]
	v_pk_mov_b32 v[28:29], v[0:1], v[0:1]
	v_pk_mov_b32 v[30:31], v[0:1], v[0:1]
	v_pk_mov_b32 v[40:41], v[0:1], v[0:1]
	v_pk_mov_b32 v[42:43], v[0:1], v[0:1]
	v_pk_mov_b32 v[44:45], v[0:1], v[0:1]
	v_pk_mov_b32 v[46:47], v[0:1], v[0:1]
	v_pk_mov_b32 v[56:57], v[0:1], v[0:1]
	v_pk_mov_b32 v[58:59], v[0:1], v[0:1]
	v_pk_mov_b32 v[60:61], v[0:1], v[0:1]
	v_pk_mov_b32 v[62:63], v[0:1], v[0:1]
	v_pk_mov_b32 v[64:65], v[0:1], v[0:1]
	v_pk_mov_b32 v[66:67], v[0:1], v[0:1]
	v_pk_mov_b32 v[68:69], v[0:1], v[0:1]
	v_pk_mov_b32 v[70:71], v[0:1], v[0:1]
	v_pk_mov_b32 v[80:81], v[0:1], v[0:1]
	v_pk_mov_b32 v[82:83], v[0:1], v[0:1]
	v_pk_mov_b32 v[84:85], v[0:1], v[0:1]
	v_pk_mov_b32 v[86:87], v[0:1], v[0:1]
	v_pk_mov_b32 v[96:97], v[0:1], v[0:1]
	v_pk_mov_b32 v[98:99], v[0:1], v[0:1]
	v_pk_mov_b32 v[100:101], v[0:1], v[0:1]
	v_pk_mov_b32 v[102:103], v[0:1], v[0:1]
	v_pk_mov_b32 v[112:113], v[0:1], v[0:1]
	v_pk_mov_b32 v[114:115], v[0:1], v[0:1]
	v_pk_mov_b32 v[116:117], v[0:1], v[0:1]
	v_pk_mov_b32 v[118:119], v[0:1], v[0:1]
	v_pk_mov_b32 v[72:73], v[0:1], v[0:1]
	v_pk_mov_b32 v[74:75], v[0:1], v[0:1]
	v_pk_mov_b32 v[76:77], v[0:1], v[0:1]
	v_pk_mov_b32 v[78:79], v[0:1], v[0:1]
	v_pk_mov_b32 v[88:89], v[0:1], v[0:1]
	v_pk_mov_b32 v[90:91], v[0:1], v[0:1]
	v_pk_mov_b32 v[92:93], v[0:1], v[0:1]
	v_pk_mov_b32 v[94:95], v[0:1], v[0:1]
	v_pk_mov_b32 v[104:105], v[0:1], v[0:1]
	v_pk_mov_b32 v[106:107], v[0:1], v[0:1]
	v_pk_mov_b32 v[108:109], v[0:1], v[0:1]
	v_pk_mov_b32 v[110:111], v[0:1], v[0:1]
	v_pk_mov_b32 v[120:121], v[0:1], v[0:1]
	v_pk_mov_b32 v[122:123], v[0:1], v[0:1]
	v_pk_mov_b32 v[124:125], v[0:1], v[0:1]
	v_pk_mov_b32 v[126:127], v[0:1], v[0:1]
	s_add_i32 s80, s12, 2
	s_cmp_eq_u32 s73, s12
	s_cselect_b32 s22, s42, s48
	s_cselect_b32 s23, s43, s49
	s_cselect_b32 s20, s44, s46
	s_cselect_b32 s21, s45, s47
	s_add_u32 s12, s22, 0x80
	s_addc_u32 s13, s23, 0
	s_add_i32 s81, 0, 0x10000
	v_add_u32_e32 v128, s81, v135
; #define PG8_STAGE(bufoff, gbase, voff) do { const char* _gb = (const char*)(gbase); asm volatile("" : "+s"(_gb)); _Pragma("unroll") for (int _i = 0; _i < 2; ++_i) { unsigned _vo = (voff)[_i]; asm volatile("" : "+v"(_vo)); \
;         __builtin_amdgcn_global_load_lds((const GAS unsigned*)(_gb + _vo), (LAS unsigned*)(lds + (bufoff) + ldsw + _i * 8192), 16, 0, 0); } } while (0)
; #define PG8_LDA(dst, b, h) do { _Pragma("unroll") for (int m = 0; m < 4; ++m) _Pragma("unroll") for (int k = 0; k < 2; ++k) dst[m][k] = *(const LAS bf16x8*)(lds + PG8_SA(b, h) + aoff + m * 2048 + k * 1024); } while (0)
; #define PG8_LDB(dst, b, h) do { _Pragma("unroll") for (int n = 0; n < 2; ++n) _Pragma("unroll") for (int k = 0; k < 2; ++k) dst[n][k] = *(const LAS bf16x8*)(lds + PG8_SB(b, h) + boff + n * 2048 + k * 1024); } while (0)
; #define PG8_MMA(ai, bj, At, Bt) do { __builtin_amdgcn_s_setprio(1); _Pragma("unroll") for (int m = 0; m < 4; ++m) _Pragma("unroll") for (int n = 0; n < 2; ++n) _Pragma("unroll") for (int k = 0; k < 2; ++k) \
;         acc[ai][bj][m][n] = __builtin_amdgcn_mfma_f32_16x16x32_bf16(Bt[n][k], At[m][k], acc[ai][bj][m][n], 0, 0, 0); __builtin_amdgcn_s_setprio(0); } while (0)
; #define PG8_WAIT_L(n) asm volatile("s_waitcnt lgkmcnt(" #n ")" ::: "memory")
; #define PG8_BAR __builtin_amdgcn_s_barrier()
; #define PG8_SCHED __builtin_amdgcn_sched_barrier(0)
; template <class Epi, class Ord>
; __device__ __forceinline__ void gemm_phase(LAS unsigned char* lds, const Gemm g, const Ord& S, const Epi& E) {
;     ...
;             PG8_LDB(B0, 0, 0); PG8_SCHED; PG8_LDA(At, 0, 0); PG8_STAGE(PG8_SA(1, 1), a1 + hstep, voffA);
;             PG8_WAIT_L(8); PG8_BAR; PG8_WAIT_L(0); PG8_MMA(0, 0, At, B0); PG8_BAR; PG8_SCHED;
;             PG8_LDB(B1, 0, 1); PG8_STAGE(PG8_SB(0, 0), b2, voffB);
;             PG8_BAR; PG8_WAIT_L(0); PG8_MMA(0, 1, At, B1); PG8_BAR;
;             PG8_LDA(At, 0, 1); PG8_STAGE(PG8_SA(0, 0), a2, voffA);
;             PG8_BAR; PG8_WAIT_L(0); PG8_MMA(1, 0, At, B0); PG8_BAR; PG8_SCHED;
.LBB0_498:
	ds_read_b128 v[142:145], v128
	ds_read_b128 v[146:149], v128 offset:1024
	ds_read_b128 v[150:153], v128 offset:2048
	ds_read_b128 v[154:157], v128 offset:3072
	s_add_u32 s24, s48, s0
	s_addc_u32 s25, s49, s1
	s_add_u32 s24, s24, 0xffffff80
	s_addc_u32 s25, s25, -1
	v_mov_b32_e32 v128, v130
	ds_read_b128 v[192:195], v140
	ds_read_b128 v[196:199], v140 offset:1024
	ds_read_b128 v[200:203], v140 offset:2048
	ds_read_b128 v[204:207], v140 offset:3072
	ds_read_b128 v[212:215], v140 offset:4096
	ds_read_b128 v[216:219], v140 offset:5120
	ds_read_b128 v[220:223], v140 offset:6144
	ds_read_b128 v[224:227], v140 offset:7168
	s_add_i32 m0, s64, 0xc000
	s_nop 0
	global_load_lds_dwordx4 v128, s[24:25]
	v_mov_b32_e32 v128, v132
	s_add_i32 m0, s64, 0xe000
	s_nop 0
	global_load_lds_dwordx4 v128, s[24:25]
	s_waitcnt lgkmcnt(8)
	s_barrier
	s_waitcnt lgkmcnt(0)
	s_setprio 1
	s_waitcnt lgkmcnt(0)
	v_mfma_f32_16x16x32_bf16 v[124:127], v[142:145], v[192:195], v[124:127]
	v_mfma_f32_16x16x32_bf16 v[120:123], v[150:153], v[192:195], v[120:123]
	v_mfma_f32_16x16x32_bf16 v[108:111], v[142:145], v[200:203], v[108:111]
	v_mfma_f32_16x16x32_bf16 v[104:107], v[150:153], v[200:203], v[104:107]
	v_mfma_f32_16x16x32_bf16 v[92:95], v[142:145], v[212:215], v[92:95]
	v_mfma_f32_16x16x32_bf16 v[88:91], v[150:153], v[212:215], v[88:91]
	v_mfma_f32_16x16x32_bf16 v[76:79], v[142:145], v[220:223], v[76:79]
	v_mfma_f32_16x16x32_bf16 v[72:75], v[150:153], v[220:223], v[72:75]
	v_mfma_f32_16x16x32_bf16 v[124:127], v[146:149], v[196:199], v[124:127]
	v_mfma_f32_16x16x32_bf16 v[120:123], v[154:157], v[196:199], v[120:123]
	v_mfma_f32_16x16x32_bf16 v[108:111], v[146:149], v[204:207], v[108:111]
	v_mfma_f32_16x16x32_bf16 v[104:107], v[154:157], v[204:207], v[104:107]
	v_mfma_f32_16x16x32_bf16 v[92:95], v[146:149], v[216:219], v[92:95]
	v_mfma_f32_16x16x32_bf16 v[88:91], v[154:157], v[216:219], v[88:91]
	v_mfma_f32_16x16x32_bf16 v[76:79], v[146:149], v[224:227], v[76:79]
	v_mfma_f32_16x16x32_bf16 v[72:75], v[154:157], v[224:227], v[72:75]
	s_setprio 0
	s_barrier
	s_add_i32 s84, 0, 0x14000
	v_add_u32_e32 v128, s84, v135
	ds_read_b128 v[228:231], v128
	ds_read_b128 v[232:235], v128 offset:1024
	ds_read_b128 v[236:239], v128 offset:2048
	ds_read_b128 v[240:243], v128 offset:3072
	s_mov_b64 s[24:25], s[20:21]
	v_mov_b32_e32 v128, v131
	s_add_i32 s81, s81, s57
	s_mov_b32 m0, s81
	s_nop 0
	global_load_lds_dwordx4 v128, s[24:25]
	v_mov_b32_e32 v128, v133
	s_add_i32 m0, s81, 0x2000
	s_nop 0
	global_load_lds_dwordx4 v128, s[24:25]
	s_barrier
	s_waitcnt lgkmcnt(0)
	s_setprio 1
	s_waitcnt lgkmcnt(0)
	v_mfma_f32_16x16x32_bf16 v[116:119], v[228:231], v[192:195], v[116:119]
	v_mfma_f32_16x16x32_bf16 v[112:115], v[236:239], v[192:195], v[112:115]
	v_mfma_f32_16x16x32_bf16 v[100:103], v[228:231], v[200:203], v[100:103]
	v_mfma_f32_16x16x32_bf16 v[96:99], v[236:239], v[200:203], v[96:99]
	v_mfma_f32_16x16x32_bf16 v[84:87], v[228:231], v[212:215], v[84:87]
	v_mfma_f32_16x16x32_bf16 v[80:83], v[236:239], v[212:215], v[80:83]
	v_mfma_f32_16x16x32_bf16 v[68:71], v[228:231], v[220:223], v[68:71]
	v_mfma_f32_16x16x32_bf16 v[64:67], v[236:239], v[220:223], v[64:67]
	v_mfma_f32_16x16x32_bf16 v[116:119], v[232:235], v[196:199], v[116:119]
	v_mfma_f32_16x16x32_bf16 v[112:115], v[240:243], v[196:199], v[112:115]
	v_mfma_f32_16x16x32_bf16 v[100:103], v[232:235], v[204:207], v[100:103]
	v_mfma_f32_16x16x32_bf16 v[96:99], v[240:243], v[204:207], v[96:99]
	v_mfma_f32_16x16x32_bf16 v[84:87], v[232:235], v[216:219], v[84:87]
	v_mfma_f32_16x16x32_bf16 v[80:83], v[240:243], v[216:219], v[80:83]
	v_mfma_f32_16x16x32_bf16 v[68:71], v[232:235], v[224:227], v[68:71]
	v_mfma_f32_16x16x32_bf16 v[64:67], v[240:243], v[224:227], v[64:67]
	s_setprio 0
	s_mov_b64 s[24:25], s[22:23]
	v_mov_b32_e32 v128, v130
	s_mov_b32 m0, s64
	s_barrier
	ds_read_b128 v[192:195], v140 offset:16384
	ds_read_b128 v[196:199], v140 offset:17408
	ds_read_b128 v[200:203], v140 offset:18432
	ds_read_b128 v[204:207], v140 offset:19456
	ds_read_b128 v[212:215], v140 offset:20480
	ds_read_b128 v[216:219], v140 offset:21504
	ds_read_b128 v[220:223], v140 offset:22528
	ds_read_b128 v[224:227], v140 offset:23552
	s_nop 0
	global_load_lds_dwordx4 v128, s[24:25]
	v_mov_b32_e32 v128, v132
	s_mov_b32 m0, s65
	s_nop 0
	global_load_lds_dwordx4 v128, s[24:25]
	s_barrier
	s_waitcnt lgkmcnt(0)
	s_setprio 1
	s_waitcnt lgkmcnt(0)
	v_mfma_f32_16x16x32_bf16 v[60:63], v[142:145], v[192:195], v[60:63]
	v_mfma_f32_16x16x32_bf16 v[56:59], v[150:153], v[192:195], v[56:59]
	v_mfma_f32_16x16x32_bf16 v[44:47], v[142:145], v[200:203], v[44:47]
	v_mfma_f32_16x16x32_bf16 v[40:43], v[150:153], v[200:203], v[40:43]
	v_mfma_f32_16x16x32_bf16 v[28:31], v[142:145], v[212:215], v[28:31]
	v_mfma_f32_16x16x32_bf16 v[24:27], v[150:153], v[212:215], v[24:27]
	v_mfma_f32_16x16x32_bf16 v[12:15], v[142:145], v[220:223], v[12:15]
	v_mfma_f32_16x16x32_bf16 v[8:11], v[150:153], v[220:223], v[8:11]
	v_mfma_f32_16x16x32_bf16 v[60:63], v[146:149], v[196:199], v[60:63]
	v_mfma_f32_16x16x32_bf16 v[56:59], v[154:157], v[196:199], v[56:59]
	v_mfma_f32_16x16x32_bf16 v[44:47], v[146:149], v[204:207], v[44:47]
	v_mfma_f32_16x16x32_bf16 v[40:43], v[154:157], v[204:207], v[40:43]
	v_mfma_f32_16x16x32_bf16 v[28:31], v[146:149], v[216:219], v[28:31]
	v_mfma_f32_16x16x32_bf16 v[24:27], v[154:157], v[216:219], v[24:27]
	v_mfma_f32_16x16x32_bf16 v[12:15], v[146:149], v[224:227], v[12:15]
	v_mfma_f32_16x16x32_bf16 v[8:11], v[154:157], v[224:227], v[8:11]
	s_setprio 0
	s_barrier
; #define PG8_STAGE(bufoff, gbase, voff) do { const char* _gb = (const char*)(gbase); asm volatile("" : "+s"(_gb)); _Pragma("unroll") for (int _i = 0; _i < 2; ++_i) { unsigned _vo = (voff)[_i]; asm volatile("" : "+v"(_vo)); \
;         __builtin_amdgcn_global_load_lds((const GAS unsigned*)(_gb + _vo), (LAS unsigned*)(lds + (bufoff) + ldsw + _i * 8192), 16, 0, 0); } } while (0)
; #define PG8_LDA(dst, b, h) do { _Pragma("unroll") for (int m = 0; m < 4; ++m) _Pragma("unroll") for (int k = 0; k < 2; ++k) dst[m][k] = *(const LAS bf16x8*)(lds + PG8_SA(b, h) + aoff + m * 2048 + k * 1024); } while (0)
; #define PG8_LDB(dst, b, h) do { _Pragma("unroll") for (int n = 0; n < 2; ++n) _Pragma("unroll") for (int k = 0; k < 2; ++k) dst[n][k] = *(const LAS bf16x8*)(lds + PG8_SB(b, h) + boff + n * 2048 + k * 1024); } while (0)
; #define PG8_MMA(ai, bj, At, Bt) do { __builtin_amdgcn_s_setprio(1); _Pragma("unroll") for (int m = 0; m < 4; ++m) _Pragma("unroll") for (int n = 0; n < 2; ++n) _Pragma("unroll") for (int k = 0; k < 2; ++k) \
;         acc[ai][bj][m][n] = __builtin_amdgcn_mfma_f32_16x16x32_bf16(Bt[n][k], At[m][k], acc[ai][bj][m][n], 0, 0, 0); __builtin_amdgcn_s_setprio(0); } while (0)
; #define PG8_WAIT_V(n) asm volatile("s_waitcnt vmcnt(" #n ")" ::: "memory")
; #define PG8_WAIT_L(n) asm volatile("s_waitcnt lgkmcnt(" #n ")" ::: "memory")
; #define PG8_BAR __builtin_amdgcn_s_barrier()
; #define PG8_SCHED __builtin_amdgcn_sched_barrier(0)
; template <class Epi, class Ord>
; __device__ __forceinline__ void gemm_phase(LAS unsigned char* lds, const Gemm g, const Ord& S, const Epi& E) {
;     ...
;             PG8_STAGE(PG8_SB(0, 1), b2 + hstep, voffB);
;             PG8_WAIT_V(6); PG8_BAR; PG8_MMA(1, 1, At, B1); PG8_BAR;
;             PG8_LDB(B0, 1, 0); PG8_SCHED; PG8_LDA(At, 1, 0); PG8_STAGE(PG8_SA(0, 1), a2 + hstep, voffA);
;             PG8_WAIT_L(8); PG8_BAR; PG8_WAIT_L(0); PG8_MMA(0, 0, At, B0); PG8_BAR; PG8_SCHED;
;             PG8_LDB(B1, 1, 1); PG8_STAGE(PG8_SB(1, 0), b3, voffB);
	s_add_u32 s24, s20, s0
	s_addc_u32 s25, s21, s1
	s_mov_b64 s[82:83], s[24:25]
	v_mov_b32_e32 v128, v131
	s_add_i32 s81, s84, s57
	s_mov_b32 m0, s81
	s_nop 0
	global_load_lds_dwordx4 v128, s[82:83]
	v_mov_b32_e32 v128, v133
	s_add_i32 m0, s81, 0x2000
	s_nop 0
	global_load_lds_dwordx4 v128, s[82:83]
	s_waitcnt vmcnt(6)
	s_barrier
	s_setprio 1
	v_mfma_f32_16x16x32_bf16 v[52:55], v[228:231], v[192:195], v[52:55]
	v_mfma_f32_16x16x32_bf16 v[48:51], v[236:239], v[192:195], v[48:51]
	v_mfma_f32_16x16x32_bf16 v[36:39], v[228:231], v[200:203], v[36:39]
	v_mfma_f32_16x16x32_bf16 v[32:35], v[236:239], v[200:203], v[32:35]
	v_mfma_f32_16x16x32_bf16 v[20:23], v[228:231], v[212:215], v[20:23]
	v_mfma_f32_16x16x32_bf16 v[16:19], v[236:239], v[212:215], v[16:19]
	v_mfma_f32_16x16x32_bf16 v[4:7], v[228:231], v[220:223], v[4:7]
	v_mfma_f32_16x16x32_bf16 v[0:3], v[236:239], v[220:223], v[0:3]
	v_mfma_f32_16x16x32_bf16 v[52:55], v[232:235], v[196:199], v[52:55]
	v_mfma_f32_16x16x32_bf16 v[48:51], v[240:243], v[196:199], v[48:51]
	v_mfma_f32_16x16x32_bf16 v[36:39], v[232:235], v[204:207], v[36:39]
	v_mfma_f32_16x16x32_bf16 v[32:35], v[240:243], v[204:207], v[32:35]
	v_mfma_f32_16x16x32_bf16 v[20:23], v[232:235], v[216:219], v[20:23]
	v_mfma_f32_16x16x32_bf16 v[16:19], v[240:243], v[216:219], v[16:19]
	v_mfma_f32_16x16x32_bf16 v[4:7], v[232:235], v[224:227], v[4:7]
	v_mfma_f32_16x16x32_bf16 v[0:3], v[240:243], v[224:227], v[0:3]
	s_setprio 0
	s_add_i32 s81, 0, 0x18000
	v_add_u32_e32 v128, s81, v135
	s_barrier
	ds_read_b128 v[142:145], v128
	ds_read_b128 v[146:149], v128 offset:1024
	ds_read_b128 v[150:153], v128 offset:2048
	ds_read_b128 v[154:157], v128 offset:3072
	s_add_u32 s22, s22, s0
	s_addc_u32 s23, s23, s1
	v_mov_b32_e32 v128, v130
	s_mov_b32 m0, s68
	ds_read_b128 v[192:195], v140 offset:32768
	ds_read_b128 v[196:199], v140 offset:33792
	ds_read_b128 v[200:203], v140 offset:34816
	ds_read_b128 v[204:207], v140 offset:35840
	ds_read_b128 v[212:215], v140 offset:36864
	ds_read_b128 v[216:219], v140 offset:37888
	ds_read_b128 v[220:223], v140 offset:38912
	ds_read_b128 v[224:227], v140 offset:39936
	s_nop 0
	global_load_lds_dwordx4 v128, s[22:23]
	v_mov_b32_e32 v128, v132
	s_mov_b32 m0, s69
	s_nop 0
	global_load_lds_dwordx4 v128, s[22:23]
	s_waitcnt lgkmcnt(8)
	s_barrier
	s_waitcnt lgkmcnt(0)
	s_setprio 1
	s_waitcnt lgkmcnt(0)
	v_mfma_f32_16x16x32_bf16 v[124:127], v[142:145], v[192:195], v[124:127]
	v_mfma_f32_16x16x32_bf16 v[120:123], v[150:153], v[192:195], v[120:123]
	v_mfma_f32_16x16x32_bf16 v[108:111], v[142:145], v[200:203], v[108:111]
	v_mfma_f32_16x16x32_bf16 v[104:107], v[150:153], v[200:203], v[104:107]
	v_mfma_f32_16x16x32_bf16 v[92:95], v[142:145], v[212:215], v[92:95]
	v_mfma_f32_16x16x32_bf16 v[88:91], v[150:153], v[212:215], v[88:91]
	v_mfma_f32_16x16x32_bf16 v[76:79], v[142:145], v[220:223], v[76:79]
	v_mfma_f32_16x16x32_bf16 v[72:75], v[150:153], v[220:223], v[72:75]
	v_mfma_f32_16x16x32_bf16 v[124:127], v[146:149], v[196:199], v[124:127]
	v_mfma_f32_16x16x32_bf16 v[120:123], v[154:157], v[196:199], v[120:123]
	v_mfma_f32_16x16x32_bf16 v[108:111], v[146:149], v[204:207], v[108:111]
	v_mfma_f32_16x16x32_bf16 v[104:107], v[154:157], v[204:207], v[104:107]
	v_mfma_f32_16x16x32_bf16 v[92:95], v[146:149], v[216:219], v[92:95]
	v_mfma_f32_16x16x32_bf16 v[88:91], v[154:157], v[216:219], v[88:91]
	v_mfma_f32_16x16x32_bf16 v[76:79], v[146:149], v[224:227], v[76:79]
	v_mfma_f32_16x16x32_bf16 v[72:75], v[154:157], v[224:227], v[72:75]
	s_setprio 0
	s_barrier
	s_add_i32 s22, 0, 0x1c000
	v_add_u32_e32 v128, s22, v135
	s_add_u32 s20, s20, 0x80
	ds_read_b128 v[228:231], v128
	ds_read_b128 v[232:235], v128 offset:1024
	ds_read_b128 v[236:239], v128 offset:2048
	ds_read_b128 v[240:243], v128 offset:3072
	s_addc_u32 s21, s21, 0
	v_mov_b32_e32 v128, v131
	s_add_i32 s23, s81, s57
	s_mov_b32 m0, s23
	s_nop 0
	global_load_lds_dwordx4 v128, s[20:21]
	v_mov_b32_e32 v128, v133
	s_add_i32 m0, s23, 0x2000
	s_nop 0
	global_load_lds_dwordx4 v128, s[20:21]
	s_barrier
; #define PG8_STAGE(bufoff, gbase, voff) do { const char* _gb = (const char*)(gbase); asm volatile("" : "+s"(_gb)); _Pragma("unroll") for (int _i = 0; _i < 2; ++_i) { unsigned _vo = (voff)[_i]; asm volatile("" : "+v"(_vo)); \
;         __builtin_amdgcn_global_load_lds((const GAS unsigned*)(_gb + _vo), (LAS unsigned*)(lds + (bufoff) + ldsw + _i * 8192), 16, 0, 0); } } while (0)
; #define PG8_LDA(dst, b, h) do { _Pragma("unroll") for (int m = 0; m < 4; ++m) _Pragma("unroll") for (int k = 0; k < 2; ++k) dst[m][k] = *(const LAS bf16x8*)(lds + PG8_SA(b, h) + aoff + m * 2048 + k * 1024); } while (0)
; #define PG8_MMA(ai, bj, At, Bt) do { __builtin_amdgcn_s_setprio(1); _Pragma("unroll") for (int m = 0; m < 4; ++m) _Pragma("unroll") for (int n = 0; n < 2; ++n) _Pragma("unroll") for (int k = 0; k < 2; ++k) \
;         acc[ai][bj][m][n] = __builtin_amdgcn_mfma_f32_16x16x32_bf16(Bt[n][k], At[m][k], acc[ai][bj][m][n], 0, 0, 0); __builtin_amdgcn_s_setprio(0); } while (0)
; #define PG8_WAIT_V(n) asm volatile("s_waitcnt vmcnt(" #n ")" ::: "memory")
; #define PG8_WAIT_L(n) asm volatile("s_waitcnt lgkmcnt(" #n ")" ::: "memory")
; #define PG8_BAR __builtin_amdgcn_s_barrier()
; #define PG8_SCHED __builtin_amdgcn_sched_barrier(0)
; template <class Epi, class Ord>
; __device__ __forceinline__ void gemm_phase(LAS unsigned char* lds, const Gemm g, const Ord& S, const Epi& E) {
;     ...
;             PG8_BAR; PG8_WAIT_L(0); PG8_MMA(0, 1, At, B1); PG8_BAR;
;             PG8_LDA(At, 1, 1); PG8_STAGE(PG8_SA(1, 0), a3, voffA);
;             PG8_BAR; PG8_WAIT_L(0); PG8_MMA(1, 0, At, B0); PG8_BAR; PG8_SCHED;
;             PG8_STAGE(PG8_SB(1, 1), b3 + hstep, voffB);
;             PG8_WAIT_V(6); PG8_BAR; PG8_MMA(1, 1, At, B1); PG8_BAR;
;         }
	s_waitcnt lgkmcnt(0)
	s_setprio 1
	s_waitcnt lgkmcnt(0)
	v_mfma_f32_16x16x32_bf16 v[116:119], v[228:231], v[192:195], v[116:119]
	v_mfma_f32_16x16x32_bf16 v[112:115], v[236:239], v[192:195], v[112:115]
	v_mfma_f32_16x16x32_bf16 v[100:103], v[228:231], v[200:203], v[100:103]
	v_mfma_f32_16x16x32_bf16 v[96:99], v[236:239], v[200:203], v[96:99]
	v_mfma_f32_16x16x32_bf16 v[84:87], v[228:231], v[212:215], v[84:87]
	v_mfma_f32_16x16x32_bf16 v[80:83], v[236:239], v[212:215], v[80:83]
	v_mfma_f32_16x16x32_bf16 v[68:71], v[228:231], v[220:223], v[68:71]
	v_mfma_f32_16x16x32_bf16 v[64:67], v[236:239], v[220:223], v[64:67]
	v_mfma_f32_16x16x32_bf16 v[116:119], v[232:235], v[196:199], v[116:119]
	v_mfma_f32_16x16x32_bf16 v[112:115], v[240:243], v[196:199], v[112:115]
	v_mfma_f32_16x16x32_bf16 v[100:103], v[232:235], v[204:207], v[100:103]
	v_mfma_f32_16x16x32_bf16 v[96:99], v[240:243], v[204:207], v[96:99]
	v_mfma_f32_16x16x32_bf16 v[84:87], v[232:235], v[216:219], v[84:87]
	v_mfma_f32_16x16x32_bf16 v[80:83], v[240:243], v[216:219], v[80:83]
	v_mfma_f32_16x16x32_bf16 v[68:71], v[232:235], v[224:227], v[68:71]
	v_mfma_f32_16x16x32_bf16 v[64:67], v[240:243], v[224:227], v[64:67]
	s_setprio 0
	v_mov_b32_e32 v128, v130
	s_mov_b32 m0, s71
	s_barrier
	ds_read_b128 v[192:195], v140 offset:49152
	ds_read_b128 v[196:199], v140 offset:50176
	ds_read_b128 v[200:203], v140 offset:51200
	ds_read_b128 v[204:207], v140 offset:52224
	ds_read_b128 v[212:215], v140 offset:53248
	ds_read_b128 v[216:219], v140 offset:54272
	ds_read_b128 v[220:223], v140 offset:55296
	ds_read_b128 v[224:227], v140 offset:56320
	s_nop 0
	global_load_lds_dwordx4 v128, s[12:13]
	v_mov_b32_e32 v128, v132
	s_mov_b32 m0, s72
	s_nop 0
	global_load_lds_dwordx4 v128, s[12:13]
	s_barrier
	s_waitcnt lgkmcnt(0)
	s_setprio 1
	s_waitcnt lgkmcnt(0)
	v_mfma_f32_16x16x32_bf16 v[60:63], v[142:145], v[192:195], v[60:63]
	v_mfma_f32_16x16x32_bf16 v[56:59], v[150:153], v[192:195], v[56:59]
	v_mfma_f32_16x16x32_bf16 v[44:47], v[142:145], v[200:203], v[44:47]
	v_mfma_f32_16x16x32_bf16 v[40:43], v[150:153], v[200:203], v[40:43]
	v_mfma_f32_16x16x32_bf16 v[28:31], v[142:145], v[212:215], v[28:31]
	v_mfma_f32_16x16x32_bf16 v[24:27], v[150:153], v[212:215], v[24:27]
	v_mfma_f32_16x16x32_bf16 v[12:15], v[142:145], v[220:223], v[12:15]
	v_mfma_f32_16x16x32_bf16 v[8:11], v[150:153], v[220:223], v[8:11]
	v_mfma_f32_16x16x32_bf16 v[60:63], v[146:149], v[196:199], v[60:63]
	v_mfma_f32_16x16x32_bf16 v[56:59], v[154:157], v[196:199], v[56:59]
	v_mfma_f32_16x16x32_bf16 v[44:47], v[146:149], v[204:207], v[44:47]
	v_mfma_f32_16x16x32_bf16 v[40:43], v[154:157], v[204:207], v[40:43]
	v_mfma_f32_16x16x32_bf16 v[28:31], v[146:149], v[216:219], v[28:31]
	v_mfma_f32_16x16x32_bf16 v[24:27], v[154:157], v[216:219], v[24:27]
	v_mfma_f32_16x16x32_bf16 v[12:15], v[146:149], v[224:227], v[12:15]
	v_mfma_f32_16x16x32_bf16 v[8:11], v[154:157], v[224:227], v[8:11]
	s_setprio 0
	s_barrier
	s_add_u32 s12, s24, 0x80
	s_addc_u32 s13, s25, 0
	v_mov_b32_e32 v128, v131
	s_add_i32 s20, s22, s57
	s_mov_b32 m0, s20
	s_nop 0
	global_load_lds_dwordx4 v128, s[12:13]
	v_mov_b32_e32 v128, v133
	s_add_i32 m0, s20, 0x2000
	s_nop 0
	global_load_lds_dwordx4 v128, s[12:13]
	s_waitcnt vmcnt(6)
	s_barrier
	s_setprio 1
	v_mfma_f32_16x16x32_bf16 v[52:55], v[228:231], v[192:195], v[52:55]
	v_mfma_f32_16x16x32_bf16 v[48:51], v[236:239], v[192:195], v[48:51]
	v_mfma_f32_16x16x32_bf16 v[36:39], v[228:231], v[200:203], v[36:39]
	v_mfma_f32_16x16x32_bf16 v[32:35], v[236:239], v[200:203], v[32:35]
	v_mfma_f32_16x16x32_bf16 v[20:23], v[228:231], v[212:215], v[20:23]
	v_mfma_f32_16x16x32_bf16 v[16:19], v[236:239], v[212:215], v[16:19]
	v_mfma_f32_16x16x32_bf16 v[4:7], v[228:231], v[220:223], v[4:7]
	v_mfma_f32_16x16x32_bf16 v[0:3], v[236:239], v[220:223], v[0:3]
	v_mfma_f32_16x16x32_bf16 v[52:55], v[232:235], v[196:199], v[52:55]
	v_mfma_f32_16x16x32_bf16 v[48:51], v[240:243], v[196:199], v[48:51]
	v_mfma_f32_16x16x32_bf16 v[36:39], v[232:235], v[204:207], v[36:39]
	v_mfma_f32_16x16x32_bf16 v[32:35], v[240:243], v[204:207], v[32:35]
	v_mfma_f32_16x16x32_bf16 v[20:23], v[232:235], v[216:219], v[20:23]
	v_mfma_f32_16x16x32_bf16 v[16:19], v[240:243], v[216:219], v[16:19]
	v_mfma_f32_16x16x32_bf16 v[4:7], v[232:235], v[224:227], v[4:7]
	v_mfma_f32_16x16x32_bf16 v[0:3], v[240:243], v[224:227], v[0:3]
	s_setprio 0
	s_add_u32 s46, s46, 0x100
	s_addc_u32 s47, s47, 0
	s_add_u32 s48, s48, 0x100
	s_addc_u32 s49, s49, 0
	s_mov_b32 s12, s80
	s_add_i32 s80, s12, 2
	s_cmp_eq_u32 s73, s12
	s_cselect_b32 s22, s42, s48
	s_cselect_b32 s23, s43, s49
	s_cselect_b32 s20, s44, s46
	s_cselect_b32 s21, s45, s47
	s_add_u32 s12, s22, 0x80
	s_addc_u32 s13, s23, 0
	s_add_i32 s81, 0, 0x10000
	v_add_u32_e32 v128, s81, v135
	s_sub_i32 s98, s80, 2
	s_cmp_ge_i32 s98, s70
	s_barrier
	s_cbranch_scc0 .LBB0_498
	s_branch .LBB0_484

; template <class Epi, class Ord>
; __device__ __forceinline__ void gemm_phase(LAS unsigned char* lds, const Gemm g, const Ord& S, const Epi& E) {
;     ...
;             const bool last = (t == nt - 2);
;             const char* a1 = cA + (size_t)(t + 1) * kstep;
;             const char* a2 = last ? nA : cA + (size_t)(t + 2) * kstep; const char* b2 = last ? nB : cB + (size_t)(t + 2) * kstep;
;             const char* a3 = a2 + kstep; const char* b3 = b2 + kstep;
;     ...
;         for (int a = 0; a < 2; ++a)
; #pragma unroll
;             for (int b = 0; b < 2; ++b)
; #pragma unroll
;                 for (int m = 0; m < 4; ++m)
; #pragma unroll
;                     for (int n = 0; n < 2; ++n) acc[a][b][m][n] = (f32x4){0.f, 0.f, 0.f, 0.f};
;         cur = nxt; cA = nA; cB = nB; ++ui;
.LBB0_526:
	v_mov_b32_e32 v155, 0
	s_andn2_b64 vcc, exec, s[46:47]
	v_mov_b32_e32 v154, 0
	v_mov_b32_e32 v193, 0
	v_mov_b32_e32 v192, 0
	v_mov_b32_e32 v157, 0
	v_mov_b32_e32 v156, 0
	v_mov_b32_e32 v159, 0
	v_mov_b32_e32 v158, 0
	v_mov_b32_e32 v147, 0
	v_mov_b32_e32 v146, 0
	v_mov_b32_e32 v145, 0
	v_mov_b32_e32 v144, 0
	v_mov_b32_e32 v143, 0
	v_mov_b32_e32 v142, 0
	v_mov_b32_e32 v141, 0
	v_mov_b32_e32 v140, 0
	v_mov_b32_e32 v123, 0
	v_mov_b32_e32 v122, 0
	v_mov_b32_e32 v121, 0
	v_mov_b32_e32 v120, 0
	v_mov_b32_e32 v119, 0
	v_mov_b32_e32 v118, 0
	v_mov_b32_e32 v117, 0
	v_mov_b32_e32 v116, 0
	v_mov_b32_e32 v107, 0
	v_mov_b32_e32 v106, 0
	v_mov_b32_e32 v105, 0
	v_mov_b32_e32 v104, 0
	v_mov_b32_e32 v103, 0
	v_mov_b32_e32 v102, 0
	v_mov_b32_e32 v101, 0
	v_mov_b32_e32 v100, 0
	v_mov_b32_e32 v151, 0
	v_mov_b32_e32 v150, 0
	v_mov_b32_e32 v153, 0
	v_mov_b32_e32 v152, 0
	v_mov_b32_e32 v127, 0
	v_mov_b32_e32 v126, 0
	v_mov_b32_e32 v125, 0
	v_mov_b32_e32 v124, 0
	v_mov_b32_e32 v139, 0
	v_mov_b32_e32 v138, 0
	v_mov_b32_e32 v137, 0
	v_mov_b32_e32 v136, 0
	v_mov_b32_e32 v135, 0
	v_mov_b32_e32 v134, 0
	v_mov_b32_e32 v133, 0
	v_mov_b32_e32 v132, 0
	v_mov_b32_e32 v115, 0
	v_mov_b32_e32 v114, 0
	v_mov_b32_e32 v113, 0
	v_mov_b32_e32 v112, 0
	v_mov_b32_e32 v111, 0
	v_mov_b32_e32 v110, 0
	v_mov_b32_e32 v109, 0
	v_mov_b32_e32 v108, 0
	v_mov_b32_e32 v99, 0
	v_mov_b32_e32 v98, 0
	v_mov_b32_e32 v97, 0
	v_mov_b32_e32 v96, 0
	v_mov_b32_e32 v95, 0
	v_mov_b32_e32 v94, 0
	v_mov_b32_e32 v93, 0
	v_mov_b32_e32 v92, 0
	v_mov_b32_e32 v87, 0
	v_mov_b32_e32 v86, 0
	v_mov_b32_e32 v91, 0
	v_mov_b32_e32 v90, 0
	v_mov_b32_e32 v85, 0
	v_mov_b32_e32 v84, 0
	v_mov_b32_e32 v89, 0
	v_mov_b32_e32 v88, 0
	v_mov_b32_e32 v75, 0
	v_mov_b32_e32 v74, 0
	v_mov_b32_e32 v73, 0
	v_mov_b32_e32 v72, 0
	v_mov_b32_e32 v71, 0
	v_mov_b32_e32 v70, 0
	v_mov_b32_e32 v69, 0
	v_mov_b32_e32 v68, 0
	v_mov_b32_e32 v59, 0
	v_mov_b32_e32 v58, 0
	v_mov_b32_e32 v57, 0
	v_mov_b32_e32 v56, 0
	v_mov_b32_e32 v55, 0
	v_mov_b32_e32 v54, 0
	v_mov_b32_e32 v53, 0
	v_mov_b32_e32 v52, 0
	v_mov_b32_e32 v43, 0
	v_mov_b32_e32 v42, 0
	v_mov_b32_e32 v41, 0
	v_mov_b32_e32 v40, 0
	v_mov_b32_e32 v39, 0
	v_mov_b32_e32 v38, 0
	v_mov_b32_e32 v37, 0
	v_mov_b32_e32 v36, 0
	v_mov_b32_e32 v81, 0
	v_mov_b32_e32 v80, 0
	v_mov_b32_e32 v83, 0
	v_mov_b32_e32 v82, 0
	v_mov_b32_e32 v79, 0
	v_mov_b32_e32 v78, 0
	v_mov_b32_e32 v77, 0
	v_mov_b32_e32 v76, 0
	v_mov_b32_e32 v67, 0
	v_mov_b32_e32 v66, 0
	v_mov_b32_e32 v65, 0
	v_mov_b32_e32 v64, 0
	v_mov_b32_e32 v63, 0
	v_mov_b32_e32 v62, 0
	v_mov_b32_e32 v61, 0
	v_mov_b32_e32 v60, 0
	v_mov_b32_e32 v51, 0
	v_mov_b32_e32 v50, 0
	v_mov_b32_e32 v49, 0
	v_mov_b32_e32 v48, 0
	v_mov_b32_e32 v47, 0
	v_mov_b32_e32 v46, 0
	v_mov_b32_e32 v45, 0
	v_mov_b32_e32 v44, 0
	v_mov_b32_e32 v35, 0
	v_mov_b32_e32 v34, 0
	v_mov_b32_e32 v33, 0
	v_mov_b32_e32 v32, 0
	v_mov_b32_e32 v31, 0
	v_mov_b32_e32 v30, 0
	v_mov_b32_e32 v29, 0
	v_mov_b32_e32 v28, 0
	s_cbranch_vccnz .LBB0_530
	s_add_u32 s48, s52, 0x100
	s_addc_u32 s49, s53, 0
	s_add_u32 s52, s56, 0x100
	v_mov_b32_e32 v0, 0
	s_addc_u32 s53, s57, 0
	s_mov_b32 s12, 0
	s_waitcnt lgkmcnt(0)
	v_mov_b32_e32 v1, v0
	v_mov_b32_e32 v2, v0
	v_mov_b32_e32 v3, v0
	v_mov_b32_e32 v4, v0
	v_mov_b32_e32 v5, v0
	v_mov_b32_e32 v6, v0
	v_mov_b32_e32 v7, v0
	v_mov_b32_e32 v8, v0
	v_mov_b32_e32 v9, v0
	v_mov_b32_e32 v10, v0
	v_mov_b32_e32 v11, v0
	v_mov_b32_e32 v12, v0
	v_mov_b32_e32 v13, v0
	v_mov_b32_e32 v14, v0
	v_mov_b32_e32 v15, v0
	v_mov_b32_e32 v20, v0
	v_mov_b32_e32 v21, v0
	v_mov_b32_e32 v22, v0
	v_mov_b32_e32 v23, v0
	v_mov_b32_e32 v28, v0
	v_mov_b32_e32 v29, v0
	v_mov_b32_e32 v30, v0
	v_mov_b32_e32 v31, v0
	v_mov_b32_e32 v36, v0
	v_mov_b32_e32 v37, v0
	v_mov_b32_e32 v38, v0
	v_mov_b32_e32 v39, v0
	v_mov_b32_e32 v44, v0
	v_mov_b32_e32 v45, v0
	v_mov_b32_e32 v46, v0
	v_mov_b32_e32 v47, v0
	v_mov_b32_e32 v16, v0
	v_mov_b32_e32 v17, v0
	v_mov_b32_e32 v18, v0
	v_mov_b32_e32 v19, v0
	v_mov_b32_e32 v24, v0
	v_mov_b32_e32 v25, v0
	v_mov_b32_e32 v26, v0
	v_mov_b32_e32 v27, v0
	v_mov_b32_e32 v32, v0
	v_mov_b32_e32 v33, v0
	v_mov_b32_e32 v34, v0
	v_mov_b32_e32 v35, v0
	v_mov_b32_e32 v40, v0
	v_mov_b32_e32 v41, v0
	v_mov_b32_e32 v42, v0
	v_mov_b32_e32 v43, v0
	v_mov_b32_e32 v48, v0
	v_mov_b32_e32 v49, v0
	v_mov_b32_e32 v50, v0
	v_mov_b32_e32 v51, v0
	v_mov_b32_e32 v52, v0
	v_mov_b32_e32 v53, v0
	v_mov_b32_e32 v54, v0
	v_mov_b32_e32 v55, v0
	v_mov_b32_e32 v56, v0
	v_mov_b32_e32 v57, v0
	v_mov_b32_e32 v58, v0
	v_mov_b32_e32 v59, v0
	v_mov_b32_e32 v60, v0
	v_mov_b32_e32 v61, v0
	v_mov_b32_e32 v62, v0
	v_mov_b32_e32 v63, v0
	v_mov_b32_e32 v64, v0
	v_mov_b32_e32 v65, v0
	v_mov_b32_e32 v66, v0
	v_mov_b32_e32 v67, v0
	v_mov_b32_e32 v68, v0
	v_mov_b32_e32 v69, v0
	v_mov_b32_e32 v70, v0
	v_mov_b32_e32 v71, v0
	v_mov_b32_e32 v72, v0
	v_mov_b32_e32 v73, v0
	v_mov_b32_e32 v74, v0
	v_mov_b32_e32 v75, v0
	v_mov_b32_e32 v76, v0
	v_mov_b32_e32 v77, v0
	v_mov_b32_e32 v78, v0
	v_mov_b32_e32 v79, v0
	v_mov_b32_e32 v88, v0
	v_mov_b32_e32 v89, v0
	v_mov_b32_e32 v90, v0
	v_mov_b32_e32 v91, v0
	v_mov_b32_e32 v92, v0
	v_mov_b32_e32 v93, v0
	v_mov_b32_e32 v94, v0
	v_mov_b32_e32 v95, v0
	v_mov_b32_e32 v104, v0
	v_mov_b32_e32 v105, v0
	v_mov_b32_e32 v106, v0
	v_mov_b32_e32 v107, v0
	v_mov_b32_e32 v108, v0
	v_mov_b32_e32 v109, v0
	v_mov_b32_e32 v110, v0
	v_mov_b32_e32 v111, v0
	v_mov_b32_e32 v80, v0
	v_mov_b32_e32 v81, v0
	v_mov_b32_e32 v82, v0
	v_mov_b32_e32 v83, v0
	v_mov_b32_e32 v84, v0
	v_mov_b32_e32 v85, v0
	v_mov_b32_e32 v86, v0
	v_mov_b32_e32 v87, v0
	v_mov_b32_e32 v96, v0
	v_mov_b32_e32 v97, v0
	v_mov_b32_e32 v98, v0
	v_mov_b32_e32 v99, v0
	v_mov_b32_e32 v100, v0
	v_mov_b32_e32 v101, v0
	v_mov_b32_e32 v102, v0
	v_mov_b32_e32 v103, v0
	v_mov_b32_e32 v112, v0
	v_mov_b32_e32 v113, v0
	v_mov_b32_e32 v114, v0
	v_mov_b32_e32 v115, v0
	v_mov_b32_e32 v116, v0
	v_mov_b32_e32 v117, v0
	v_mov_b32_e32 v118, v0
	v_mov_b32_e32 v119, v0
	v_mov_b32_e32 v120, v0
	v_mov_b32_e32 v121, v0
	v_mov_b32_e32 v122, v0
	v_mov_b32_e32 v123, v0
	v_mov_b32_e32 v124, v0
	v_mov_b32_e32 v125, v0
	v_mov_b32_e32 v126, v0
	v_mov_b32_e32 v127, v0
	s_add_i32 s56, s12, 2
	s_cmp_eq_u32 s81, s12
	s_cselect_b32 s22, s0, s52
	s_cselect_b32 s23, s1, s53
	s_cselect_b32 s20, s16, s48
	s_cselect_b32 s21, s17, s49
	s_add_u32 s12, s22, 0x80
	s_addc_u32 s13, s23, 0
	s_add_i32 s57, 0, 0x10000
	v_add_u32_e32 v144, s57, v204
; #define PG8_STAGE(bufoff, gbase, voff) do { const char* _gb = (const char*)(gbase); asm volatile("" : "+s"(_gb)); _Pragma("unroll") for (int _i = 0; _i < 2; ++_i) { unsigned _vo = (voff)[_i]; asm volatile("" : "+v"(_vo)); \
;         __builtin_amdgcn_global_load_lds((const GAS unsigned*)(_gb + _vo), (LAS unsigned*)(lds + (bufoff) + ldsw + _i * 8192), 16, 0, 0); } } while (0)
; #define PG8_LDA(dst, b, h) do { _Pragma("unroll") for (int m = 0; m < 4; ++m) _Pragma("unroll") for (int k = 0; k < 2; ++k) dst[m][k] = *(const LAS bf16x8*)(lds + PG8_SA(b, h) + aoff + m * 2048 + k * 1024); } while (0)
; #define PG8_LDB(dst, b, h) do { _Pragma("unroll") for (int n = 0; n < 2; ++n) _Pragma("unroll") for (int k = 0; k < 2; ++k) dst[n][k] = *(const LAS bf16x8*)(lds + PG8_SB(b, h) + boff + n * 2048 + k * 1024); } while (0)
; #define PG8_MMA(ai, bj, At, Bt) do { __builtin_amdgcn_s_setprio(1); _Pragma("unroll") for (int m = 0; m < 4; ++m) _Pragma("unroll") for (int n = 0; n < 2; ++n) _Pragma("unroll") for (int k = 0; k < 2; ++k) \
;         acc[ai][bj][m][n] = __builtin_amdgcn_mfma_f32_16x16x32_bf16(Bt[n][k], At[m][k], acc[ai][bj][m][n], 0, 0, 0); __builtin_amdgcn_s_setprio(0); } while (0)
; #define PG8_WAIT_L(n) asm volatile("s_waitcnt lgkmcnt(" #n ")" ::: "memory")
; #define PG8_BAR __builtin_amdgcn_s_barrier()
; #define PG8_SCHED __builtin_amdgcn_sched_barrier(0)
; template <class Epi, class Ord>
; __device__ __forceinline__ void gemm_phase(LAS unsigned char* lds, const Gemm g, const Ord& S, const Epi& E) {
;     ...
;             PG8_LDB(B0, 0, 0); PG8_SCHED; PG8_LDA(At, 0, 0); PG8_STAGE(PG8_SA(1, 1), a1 + hstep, voffA);
;             PG8_WAIT_L(8); PG8_BAR; PG8_WAIT_L(0); PG8_MMA(0, 0, At, B0); PG8_BAR; PG8_SCHED;
;             PG8_LDB(B1, 0, 1); PG8_STAGE(PG8_SB(0, 0), b2, voffB);
;             PG8_BAR; PG8_WAIT_L(0); PG8_MMA(0, 1, At, B1); PG8_BAR;
;             PG8_LDA(At, 0, 1); PG8_STAGE(PG8_SA(0, 0), a2, voffA);
;             PG8_BAR; PG8_WAIT_L(0); PG8_MMA(1, 0, At, B0); PG8_BAR; PG8_SCHED;
.LBB0_528:
	ds_read_b128 v[132:135], v144
	ds_read_b128 v[136:139], v144 offset:1024
	ds_read_b128 v[140:143], v144 offset:2048
	ds_read_b128 v[144:147], v144 offset:3072
	s_add_u32 s24, s52, s10
	s_addc_u32 s25, s53, s11
	s_add_u32 s24, s24, 0xffffff80
	s_addc_u32 s25, s25, -1
	v_mov_b32_e32 v168, v129
	ds_read_b128 v[148:151], v206
	ds_read_b128 v[152:155], v206 offset:1024
	ds_read_b128 v[156:159], v206 offset:2048
	ds_read_b128 v[192:195], v206 offset:3072
	ds_read_b128 v[196:199], v206 offset:4096
	ds_read_b128 v[212:215], v206 offset:5120
	ds_read_b128 v[216:219], v206 offset:6144
	ds_read_b128 v[220:223], v206 offset:7168
	s_add_i32 m0, s69, 0xc000
	s_nop 0
	global_load_lds_dwordx4 v168, s[24:25]
	v_mov_b32_e32 v168, v201
	s_add_i32 m0, s69, 0xe000
	s_nop 0
	global_load_lds_dwordx4 v168, s[24:25]
	s_waitcnt lgkmcnt(8)
	s_barrier
	s_waitcnt lgkmcnt(0)
	s_setprio 1
	s_waitcnt lgkmcnt(0)
	v_mfma_f32_16x16x32_bf16 v[124:127], v[132:135], v[148:151], v[124:127]
	v_mfma_f32_16x16x32_bf16 v[120:123], v[140:143], v[148:151], v[120:123]
	v_mfma_f32_16x16x32_bf16 v[116:119], v[132:135], v[156:159], v[116:119]
	v_mfma_f32_16x16x32_bf16 v[112:115], v[140:143], v[156:159], v[112:115]
	v_mfma_f32_16x16x32_bf16 v[100:103], v[132:135], v[196:199], v[100:103]
	v_mfma_f32_16x16x32_bf16 v[96:99], v[140:143], v[196:199], v[96:99]
	v_mfma_f32_16x16x32_bf16 v[84:87], v[132:135], v[216:219], v[84:87]
	v_mfma_f32_16x16x32_bf16 v[80:83], v[140:143], v[216:219], v[80:83]
	v_mfma_f32_16x16x32_bf16 v[124:127], v[136:139], v[152:155], v[124:127]
	v_mfma_f32_16x16x32_bf16 v[120:123], v[144:147], v[152:155], v[120:123]
	v_mfma_f32_16x16x32_bf16 v[116:119], v[136:139], v[192:195], v[116:119]
	v_mfma_f32_16x16x32_bf16 v[112:115], v[144:147], v[192:195], v[112:115]
	v_mfma_f32_16x16x32_bf16 v[100:103], v[136:139], v[212:215], v[100:103]
	v_mfma_f32_16x16x32_bf16 v[96:99], v[144:147], v[212:215], v[96:99]
	v_mfma_f32_16x16x32_bf16 v[84:87], v[136:139], v[220:223], v[84:87]
	v_mfma_f32_16x16x32_bf16 v[80:83], v[144:147], v[220:223], v[80:83]
	s_setprio 0
	s_barrier
	s_add_i32 s84, 0, 0x14000
	v_add_u32_e32 v168, s84, v204
	ds_read_b128 v[224:227], v168
	ds_read_b128 v[228:231], v168 offset:1024
	ds_read_b128 v[232:235], v168 offset:2048
	ds_read_b128 v[236:239], v168 offset:3072
	s_mov_b64 s[24:25], s[20:21]
	v_mov_b32_e32 v168, v200
	s_add_i32 s57, s57, s68
	s_mov_b32 m0, s57
	s_nop 0
	global_load_lds_dwordx4 v168, s[24:25]
	v_mov_b32_e32 v168, v202
	s_add_i32 m0, s57, 0x2000
	s_nop 0
	global_load_lds_dwordx4 v168, s[24:25]
	s_barrier
	s_waitcnt lgkmcnt(0)
	s_setprio 1
	s_waitcnt lgkmcnt(0)
	v_mfma_f32_16x16x32_bf16 v[108:111], v[224:227], v[148:151], v[108:111]
	v_mfma_f32_16x16x32_bf16 v[104:107], v[232:235], v[148:151], v[104:107]
	v_mfma_f32_16x16x32_bf16 v[92:95], v[224:227], v[156:159], v[92:95]
	v_mfma_f32_16x16x32_bf16 v[88:91], v[232:235], v[156:159], v[88:91]
	v_mfma_f32_16x16x32_bf16 v[76:79], v[224:227], v[196:199], v[76:79]
	v_mfma_f32_16x16x32_bf16 v[72:75], v[232:235], v[196:199], v[72:75]
	v_mfma_f32_16x16x32_bf16 v[68:71], v[224:227], v[216:219], v[68:71]
	v_mfma_f32_16x16x32_bf16 v[64:67], v[232:235], v[216:219], v[64:67]
	v_mfma_f32_16x16x32_bf16 v[108:111], v[228:231], v[152:155], v[108:111]
	v_mfma_f32_16x16x32_bf16 v[104:107], v[236:239], v[152:155], v[104:107]
	v_mfma_f32_16x16x32_bf16 v[92:95], v[228:231], v[192:195], v[92:95]
	v_mfma_f32_16x16x32_bf16 v[88:91], v[236:239], v[192:195], v[88:91]
	v_mfma_f32_16x16x32_bf16 v[76:79], v[228:231], v[212:215], v[76:79]
	v_mfma_f32_16x16x32_bf16 v[72:75], v[236:239], v[212:215], v[72:75]
	v_mfma_f32_16x16x32_bf16 v[68:71], v[228:231], v[220:223], v[68:71]
	v_mfma_f32_16x16x32_bf16 v[64:67], v[236:239], v[220:223], v[64:67]
	s_setprio 0
	s_mov_b64 s[24:25], s[22:23]
	v_mov_b32_e32 v168, v129
	s_mov_b32 m0, s69
	s_barrier
	ds_read_b128 v[148:151], v206 offset:16384
	ds_read_b128 v[152:155], v206 offset:17408
	ds_read_b128 v[156:159], v206 offset:18432
	ds_read_b128 v[192:195], v206 offset:19456
	ds_read_b128 v[196:199], v206 offset:20480
	ds_read_b128 v[212:215], v206 offset:21504
	ds_read_b128 v[216:219], v206 offset:22528
	ds_read_b128 v[220:223], v206 offset:23552
	s_nop 0
	global_load_lds_dwordx4 v168, s[24:25]
	v_mov_b32_e32 v168, v201
	s_mov_b32 m0, s70
	s_nop 0
	global_load_lds_dwordx4 v168, s[24:25]
	s_barrier
	s_waitcnt lgkmcnt(0)
	s_setprio 1
	s_waitcnt lgkmcnt(0)
	v_mfma_f32_16x16x32_bf16 v[60:63], v[132:135], v[148:151], v[60:63]
	v_mfma_f32_16x16x32_bf16 v[56:59], v[140:143], v[148:151], v[56:59]
	v_mfma_f32_16x16x32_bf16 v[52:55], v[132:135], v[156:159], v[52:55]
	v_mfma_f32_16x16x32_bf16 v[48:51], v[140:143], v[156:159], v[48:51]
	v_mfma_f32_16x16x32_bf16 v[40:43], v[132:135], v[196:199], v[40:43]
	v_mfma_f32_16x16x32_bf16 v[32:35], v[140:143], v[196:199], v[32:35]
	v_mfma_f32_16x16x32_bf16 v[24:27], v[132:135], v[216:219], v[24:27]
	v_mfma_f32_16x16x32_bf16 v[16:19], v[140:143], v[216:219], v[16:19]
	v_mfma_f32_16x16x32_bf16 v[60:63], v[136:139], v[152:155], v[60:63]
	v_mfma_f32_16x16x32_bf16 v[56:59], v[144:147], v[152:155], v[56:59]
	v_mfma_f32_16x16x32_bf16 v[52:55], v[136:139], v[192:195], v[52:55]
	v_mfma_f32_16x16x32_bf16 v[48:51], v[144:147], v[192:195], v[48:51]
	v_mfma_f32_16x16x32_bf16 v[40:43], v[136:139], v[212:215], v[40:43]
	v_mfma_f32_16x16x32_bf16 v[32:35], v[144:147], v[212:215], v[32:35]
	v_mfma_f32_16x16x32_bf16 v[24:27], v[136:139], v[220:223], v[24:27]
	v_mfma_f32_16x16x32_bf16 v[16:19], v[144:147], v[220:223], v[16:19]
	s_setprio 0
	s_barrier
; #define PG8_STAGE(bufoff, gbase, voff) do { const char* _gb = (const char*)(gbase); asm volatile("" : "+s"(_gb)); _Pragma("unroll") for (int _i = 0; _i < 2; ++_i) { unsigned _vo = (voff)[_i]; asm volatile("" : "+v"(_vo)); \
;         __builtin_amdgcn_global_load_lds((const GAS unsigned*)(_gb + _vo), (LAS unsigned*)(lds + (bufoff) + ldsw + _i * 8192), 16, 0, 0); } } while (0)
; #define PG8_LDA(dst, b, h) do { _Pragma("unroll") for (int m = 0; m < 4; ++m) _Pragma("unroll") for (int k = 0; k < 2; ++k) dst[m][k] = *(const LAS bf16x8*)(lds + PG8_SA(b, h) + aoff + m * 2048 + k * 1024); } while (0)
; #define PG8_LDB(dst, b, h) do { _Pragma("unroll") for (int n = 0; n < 2; ++n) _Pragma("unroll") for (int k = 0; k < 2; ++k) dst[n][k] = *(const LAS bf16x8*)(lds + PG8_SB(b, h) + boff + n * 2048 + k * 1024); } while (0)
; #define PG8_MMA(ai, bj, At, Bt) do { __builtin_amdgcn_s_setprio(1); _Pragma("unroll") for (int m = 0; m < 4; ++m) _Pragma("unroll") for (int n = 0; n < 2; ++n) _Pragma("unroll") for (int k = 0; k < 2; ++k) \
;         acc[ai][bj][m][n] = __builtin_amdgcn_mfma_f32_16x16x32_bf16(Bt[n][k], At[m][k], acc[ai][bj][m][n], 0, 0, 0); __builtin_amdgcn_s_setprio(0); } while (0)
; #define PG8_WAIT_V(n) asm volatile("s_waitcnt vmcnt(" #n ")" ::: "memory")
; #define PG8_WAIT_L(n) asm volatile("s_waitcnt lgkmcnt(" #n ")" ::: "memory")
; #define PG8_BAR __builtin_amdgcn_s_barrier()
; #define PG8_SCHED __builtin_amdgcn_sched_barrier(0)
; template <class Epi, class Ord>
; __device__ __forceinline__ void gemm_phase(LAS unsigned char* lds, const Gemm g, const Ord& S, const Epi& E) {
;     ...
;             PG8_STAGE(PG8_SB(0, 1), b2 + hstep, voffB);
;             PG8_WAIT_V(6); PG8_BAR; PG8_MMA(1, 1, At, B1); PG8_BAR;
;             PG8_LDB(B0, 1, 0); PG8_SCHED; PG8_LDA(At, 1, 0); PG8_STAGE(PG8_SA(0, 1), a2 + hstep, voffA);
;             PG8_WAIT_L(8); PG8_BAR; PG8_WAIT_L(0); PG8_MMA(0, 0, At, B0); PG8_BAR; PG8_SCHED;
;             PG8_LDB(B1, 1, 1); PG8_STAGE(PG8_SB(1, 0), b3, voffB);
;             PG8_BAR; PG8_WAIT_L(0); PG8_MMA(0, 1, At, B1); PG8_BAR;
;             PG8_LDA(At, 1, 1); PG8_STAGE(PG8_SA(1, 0), a3, voffA);
	s_add_u32 s24, s20, s10
	s_addc_u32 s25, s21, s11
	s_mov_b64 s[82:83], s[24:25]
	v_mov_b32_e32 v132, v200
	s_add_i32 s57, s84, s68
	s_mov_b32 m0, s57
	s_nop 0
	global_load_lds_dwordx4 v132, s[82:83]
	v_mov_b32_e32 v132, v202
	s_add_i32 m0, s57, 0x2000
	s_nop 0
	global_load_lds_dwordx4 v132, s[82:83]
	s_waitcnt vmcnt(6)
	s_barrier
	s_setprio 1
	v_mfma_f32_16x16x32_bf16 v[44:47], v[224:227], v[148:151], v[44:47]
	v_mfma_f32_16x16x32_bf16 v[36:39], v[232:235], v[148:151], v[36:39]
	v_mfma_f32_16x16x32_bf16 v[28:31], v[224:227], v[156:159], v[28:31]
	v_mfma_f32_16x16x32_bf16 v[20:23], v[232:235], v[156:159], v[20:23]
	v_mfma_f32_16x16x32_bf16 v[12:15], v[224:227], v[196:199], v[12:15]
	v_mfma_f32_16x16x32_bf16 v[8:11], v[232:235], v[196:199], v[8:11]
	v_mfma_f32_16x16x32_bf16 v[4:7], v[224:227], v[216:219], v[4:7]
	v_mfma_f32_16x16x32_bf16 v[0:3], v[232:235], v[216:219], v[0:3]
	v_mfma_f32_16x16x32_bf16 v[44:47], v[228:231], v[152:155], v[44:47]
	v_mfma_f32_16x16x32_bf16 v[36:39], v[236:239], v[152:155], v[36:39]
	v_mfma_f32_16x16x32_bf16 v[28:31], v[228:231], v[192:195], v[28:31]
	v_mfma_f32_16x16x32_bf16 v[20:23], v[236:239], v[192:195], v[20:23]
	v_mfma_f32_16x16x32_bf16 v[12:15], v[228:231], v[212:215], v[12:15]
	v_mfma_f32_16x16x32_bf16 v[8:11], v[236:239], v[212:215], v[8:11]
	v_mfma_f32_16x16x32_bf16 v[4:7], v[228:231], v[220:223], v[4:7]
	v_mfma_f32_16x16x32_bf16 v[0:3], v[236:239], v[220:223], v[0:3]
	s_setprio 0
	s_add_i32 s57, 0, 0x18000
	v_add_u32_e32 v144, s57, v204
	s_barrier
	ds_read_b128 v[132:135], v144
	ds_read_b128 v[136:139], v144 offset:1024
	ds_read_b128 v[140:143], v144 offset:2048
	ds_read_b128 v[144:147], v144 offset:3072
	s_add_u32 s22, s22, s10
	s_addc_u32 s23, s23, s11
	v_mov_b32_e32 v168, v129
	s_mov_b32 m0, s71
	ds_read_b128 v[148:151], v206 offset:32768
	ds_read_b128 v[152:155], v206 offset:33792
	ds_read_b128 v[156:159], v206 offset:34816
	ds_read_b128 v[192:195], v206 offset:35840
	ds_read_b128 v[196:199], v206 offset:36864
	ds_read_b128 v[212:215], v206 offset:37888
	ds_read_b128 v[216:219], v206 offset:38912
	ds_read_b128 v[220:223], v206 offset:39936
	s_nop 0
	global_load_lds_dwordx4 v168, s[22:23]
	v_mov_b32_e32 v168, v201
	s_mov_b32 m0, s72
	s_nop 0
	global_load_lds_dwordx4 v168, s[22:23]
	s_waitcnt lgkmcnt(8)
	s_barrier
	s_waitcnt lgkmcnt(0)
	s_setprio 1
	s_waitcnt lgkmcnt(0)
	v_mfma_f32_16x16x32_bf16 v[124:127], v[132:135], v[148:151], v[124:127]
	v_mfma_f32_16x16x32_bf16 v[120:123], v[140:143], v[148:151], v[120:123]
	v_mfma_f32_16x16x32_bf16 v[116:119], v[132:135], v[156:159], v[116:119]
	v_mfma_f32_16x16x32_bf16 v[112:115], v[140:143], v[156:159], v[112:115]
	v_mfma_f32_16x16x32_bf16 v[100:103], v[132:135], v[196:199], v[100:103]
	v_mfma_f32_16x16x32_bf16 v[96:99], v[140:143], v[196:199], v[96:99]
	v_mfma_f32_16x16x32_bf16 v[84:87], v[132:135], v[216:219], v[84:87]
	v_mfma_f32_16x16x32_bf16 v[80:83], v[140:143], v[216:219], v[80:83]
	v_mfma_f32_16x16x32_bf16 v[124:127], v[136:139], v[152:155], v[124:127]
	v_mfma_f32_16x16x32_bf16 v[120:123], v[144:147], v[152:155], v[120:123]
	v_mfma_f32_16x16x32_bf16 v[116:119], v[136:139], v[192:195], v[116:119]
	v_mfma_f32_16x16x32_bf16 v[112:115], v[144:147], v[192:195], v[112:115]
	v_mfma_f32_16x16x32_bf16 v[100:103], v[136:139], v[212:215], v[100:103]
	v_mfma_f32_16x16x32_bf16 v[96:99], v[144:147], v[212:215], v[96:99]
	v_mfma_f32_16x16x32_bf16 v[84:87], v[136:139], v[220:223], v[84:87]
	v_mfma_f32_16x16x32_bf16 v[80:83], v[144:147], v[220:223], v[80:83]
	s_setprio 0
	s_barrier
	s_add_i32 s22, 0, 0x1c000
	v_add_u32_e32 v168, s22, v204
	s_add_u32 s20, s20, 0x80
	ds_read_b128 v[224:227], v168
	ds_read_b128 v[228:231], v168 offset:1024
	ds_read_b128 v[232:235], v168 offset:2048
	ds_read_b128 v[236:239], v168 offset:3072
	s_addc_u32 s21, s21, 0
	v_mov_b32_e32 v168, v200
	s_add_i32 s23, s57, s68
	s_mov_b32 m0, s23
	s_nop 0
	global_load_lds_dwordx4 v168, s[20:21]
	v_mov_b32_e32 v168, v202
	s_add_i32 m0, s23, 0x2000
	s_nop 0
	global_load_lds_dwordx4 v168, s[20:21]
	s_barrier
	s_waitcnt lgkmcnt(0)
	s_setprio 1
	s_waitcnt lgkmcnt(0)
	v_mfma_f32_16x16x32_bf16 v[108:111], v[224:227], v[148:151], v[108:111]
	v_mfma_f32_16x16x32_bf16 v[104:107], v[232:235], v[148:151], v[104:107]
	v_mfma_f32_16x16x32_bf16 v[92:95], v[224:227], v[156:159], v[92:95]
	v_mfma_f32_16x16x32_bf16 v[88:91], v[232:235], v[156:159], v[88:91]
	v_mfma_f32_16x16x32_bf16 v[76:79], v[224:227], v[196:199], v[76:79]
	v_mfma_f32_16x16x32_bf16 v[72:75], v[232:235], v[196:199], v[72:75]
	v_mfma_f32_16x16x32_bf16 v[68:71], v[224:227], v[216:219], v[68:71]
	v_mfma_f32_16x16x32_bf16 v[64:67], v[232:235], v[216:219], v[64:67]
	v_mfma_f32_16x16x32_bf16 v[108:111], v[228:231], v[152:155], v[108:111]
	v_mfma_f32_16x16x32_bf16 v[104:107], v[236:239], v[152:155], v[104:107]
	v_mfma_f32_16x16x32_bf16 v[92:95], v[228:231], v[192:195], v[92:95]
	v_mfma_f32_16x16x32_bf16 v[88:91], v[236:239], v[192:195], v[88:91]
	v_mfma_f32_16x16x32_bf16 v[76:79], v[228:231], v[212:215], v[76:79]
	v_mfma_f32_16x16x32_bf16 v[72:75], v[236:239], v[212:215], v[72:75]
	v_mfma_f32_16x16x32_bf16 v[68:71], v[228:231], v[220:223], v[68:71]
	v_mfma_f32_16x16x32_bf16 v[64:67], v[236:239], v[220:223], v[64:67]
	s_setprio 0
	v_mov_b32_e32 v168, v129
	s_mov_b32 m0, s78
	s_barrier
	ds_read_b128 v[148:151], v206 offset:49152
	ds_read_b128 v[152:155], v206 offset:50176
	ds_read_b128 v[156:159], v206 offset:51200
	ds_read_b128 v[192:195], v206 offset:52224
	ds_read_b128 v[196:199], v206 offset:53248
	ds_read_b128 v[212:215], v206 offset:54272
	ds_read_b128 v[216:219], v206 offset:55296
	ds_read_b128 v[220:223], v206 offset:56320
	s_nop 0
	global_load_lds_dwordx4 v168, s[12:13]
	v_mov_b32_e32 v168, v201
	s_mov_b32 m0, s79
	s_nop 0
	global_load_lds_dwordx4 v168, s[12:13]
	s_barrier
; #define PG8_STAGE(bufoff, gbase, voff) do { const char* _gb = (const char*)(gbase); asm volatile("" : "+s"(_gb)); _Pragma("unroll") for (int _i = 0; _i < 2; ++_i) { unsigned _vo = (voff)[_i]; asm volatile("" : "+v"(_vo)); \
;         __builtin_amdgcn_global_load_lds((const GAS unsigned*)(_gb + _vo), (LAS unsigned*)(lds + (bufoff) + ldsw + _i * 8192), 16, 0, 0); } } while (0)
; #define PG8_MMA(ai, bj, At, Bt) do { __builtin_amdgcn_s_setprio(1); _Pragma("unroll") for (int m = 0; m < 4; ++m) _Pragma("unroll") for (int n = 0; n < 2; ++n) _Pragma("unroll") for (int k = 0; k < 2; ++k) \
;         acc[ai][bj][m][n] = __builtin_amdgcn_mfma_f32_16x16x32_bf16(Bt[n][k], At[m][k], acc[ai][bj][m][n], 0, 0, 0); __builtin_amdgcn_s_setprio(0); } while (0)
; #define PG8_WAIT_V(n) asm volatile("s_waitcnt vmcnt(" #n ")" ::: "memory")
; #define PG8_WAIT_L(n) asm volatile("s_waitcnt lgkmcnt(" #n ")" ::: "memory")
; #define PG8_BAR __builtin_amdgcn_s_barrier()
; #define PG8_SCHED __builtin_amdgcn_sched_barrier(0)
; template <class Epi, class Ord>
; __device__ __forceinline__ void gemm_phase(LAS unsigned char* lds, const Gemm g, const Ord& S, const Epi& E) {
;     ...
;             PG8_BAR; PG8_WAIT_L(0); PG8_MMA(1, 0, At, B0); PG8_BAR; PG8_SCHED;
;             PG8_STAGE(PG8_SB(1, 1), b3 + hstep, voffB);
;             PG8_WAIT_V(6); PG8_BAR; PG8_MMA(1, 1, At, B1); PG8_BAR;
;         }
;     template <int NM> __device__ __forceinline__ void round(const AccT& acc, const Unit& u, int ai, int m0, int wr, int wc, int fr, int fq) const {
;     ...
;                 if (MODE == 0) { d0 = acc[ai][bj][m][0] * alpha; d1 = acc[ai][bj][m][1] * alpha; }
	s_waitcnt lgkmcnt(0)
	s_setprio 1
	s_waitcnt lgkmcnt(0)
	v_mfma_f32_16x16x32_bf16 v[60:63], v[132:135], v[148:151], v[60:63]
	v_mfma_f32_16x16x32_bf16 v[56:59], v[140:143], v[148:151], v[56:59]
	v_mfma_f32_16x16x32_bf16 v[52:55], v[132:135], v[156:159], v[52:55]
	v_mfma_f32_16x16x32_bf16 v[48:51], v[140:143], v[156:159], v[48:51]
	v_mfma_f32_16x16x32_bf16 v[40:43], v[132:135], v[196:199], v[40:43]
	v_mfma_f32_16x16x32_bf16 v[32:35], v[140:143], v[196:199], v[32:35]
	v_mfma_f32_16x16x32_bf16 v[24:27], v[132:135], v[216:219], v[24:27]
	v_mfma_f32_16x16x32_bf16 v[16:19], v[140:143], v[216:219], v[16:19]
	v_mfma_f32_16x16x32_bf16 v[60:63], v[136:139], v[152:155], v[60:63]
	v_mfma_f32_16x16x32_bf16 v[56:59], v[144:147], v[152:155], v[56:59]
	v_mfma_f32_16x16x32_bf16 v[52:55], v[136:139], v[192:195], v[52:55]
	v_mfma_f32_16x16x32_bf16 v[48:51], v[144:147], v[192:195], v[48:51]
	v_mfma_f32_16x16x32_bf16 v[40:43], v[136:139], v[212:215], v[40:43]
	v_mfma_f32_16x16x32_bf16 v[32:35], v[144:147], v[212:215], v[32:35]
	v_mfma_f32_16x16x32_bf16 v[24:27], v[136:139], v[220:223], v[24:27]
	v_mfma_f32_16x16x32_bf16 v[16:19], v[144:147], v[220:223], v[16:19]
	s_setprio 0
	s_barrier
	s_add_u32 s12, s24, 0x80
	s_addc_u32 s13, s25, 0
	v_mov_b32_e32 v132, v200
	s_add_i32 s20, s22, s68
	s_mov_b32 m0, s20
	s_nop 0
	global_load_lds_dwordx4 v132, s[12:13]
	v_mov_b32_e32 v132, v202
	s_add_i32 m0, s20, 0x2000
	s_nop 0
	global_load_lds_dwordx4 v132, s[12:13]
	s_waitcnt vmcnt(6)
	s_barrier
	s_setprio 1
	v_mfma_f32_16x16x32_bf16 v[44:47], v[224:227], v[148:151], v[44:47]
	v_mfma_f32_16x16x32_bf16 v[36:39], v[232:235], v[148:151], v[36:39]
	v_mfma_f32_16x16x32_bf16 v[28:31], v[224:227], v[156:159], v[28:31]
	v_mfma_f32_16x16x32_bf16 v[20:23], v[232:235], v[156:159], v[20:23]
	v_mfma_f32_16x16x32_bf16 v[12:15], v[224:227], v[196:199], v[12:15]
	v_mfma_f32_16x16x32_bf16 v[8:11], v[232:235], v[196:199], v[8:11]
	v_mfma_f32_16x16x32_bf16 v[4:7], v[224:227], v[216:219], v[4:7]
	v_mfma_f32_16x16x32_bf16 v[0:3], v[232:235], v[216:219], v[0:3]
	v_mfma_f32_16x16x32_bf16 v[44:47], v[228:231], v[152:155], v[44:47]
	v_mfma_f32_16x16x32_bf16 v[36:39], v[236:239], v[152:155], v[36:39]
	v_mfma_f32_16x16x32_bf16 v[28:31], v[228:231], v[192:195], v[28:31]
	v_mfma_f32_16x16x32_bf16 v[20:23], v[236:239], v[192:195], v[20:23]
	v_mfma_f32_16x16x32_bf16 v[12:15], v[228:231], v[212:215], v[12:15]
	v_mfma_f32_16x16x32_bf16 v[8:11], v[236:239], v[212:215], v[8:11]
	v_mfma_f32_16x16x32_bf16 v[4:7], v[228:231], v[220:223], v[4:7]
	v_mfma_f32_16x16x32_bf16 v[0:3], v[236:239], v[220:223], v[0:3]
	s_setprio 0
	s_add_u32 s48, s48, 0x100
	s_addc_u32 s49, s49, 0
	s_add_u32 s52, s52, 0x100
	s_addc_u32 s53, s53, 0
	s_mov_b32 s12, s56
	s_add_i32 s56, s12, 2
	s_cmp_eq_u32 s81, s12
	s_cselect_b32 s22, s0, s52
	s_cselect_b32 s23, s1, s53
	s_cselect_b32 s20, s16, s48
	s_cselect_b32 s21, s17, s49
	s_add_u32 s12, s22, 0x80
	s_addc_u32 s13, s23, 0
	s_add_i32 s57, 0, 0x10000
	v_add_u32_e32 v144, s57, v204
	s_sub_i32 s98, s56, 2
	s_cmp_ge_i32 s98, s76
	s_barrier
	s_cbranch_scc0 .LBB0_528
	v_pk_mul_f32 v[154:155], v[126:127], 0.5 op_sel_hi:[1,0]
	v_pk_mul_f32 v[192:193], v[124:125], 0.5 op_sel_hi:[1,0]
	v_pk_mul_f32 v[156:157], v[122:123], 0.5 op_sel_hi:[1,0]
	v_pk_mul_f32 v[158:159], v[120:121], 0.5 op_sel_hi:[1,0]
	v_pk_mul_f32 v[150:151], v[110:111], 0.5 op_sel_hi:[1,0]
	v_pk_mul_f32 v[152:153], v[108:109], 0.5 op_sel_hi:[1,0]
	v_pk_mul_f32 v[126:127], v[106:107], 0.5 op_sel_hi:[1,0]
	v_pk_mul_f32 v[124:125], v[104:105], 0.5 op_sel_hi:[1,0]
	v_pk_mul_f32 v[146:147], v[118:119], 0.5 op_sel_hi:[1,0]
	v_pk_mul_f32 v[144:145], v[116:117], 0.5 op_sel_hi:[1,0]
	v_pk_mul_f32 v[142:143], v[114:115], 0.5 op_sel_hi:[1,0]
	v_pk_mul_f32 v[140:141], v[112:113], 0.5 op_sel_hi:[1,0]
	v_pk_mul_f32 v[138:139], v[94:95], 0.5 op_sel_hi:[1,0]
	v_pk_mul_f32 v[136:137], v[92:93], 0.5 op_sel_hi:[1,0]
	v_pk_mul_f32 v[134:135], v[90:91], 0.5 op_sel_hi:[1,0]
	v_pk_mul_f32 v[132:133], v[88:89], 0.5 op_sel_hi:[1,0]
	v_pk_mul_f32 v[122:123], v[102:103], 0.5 op_sel_hi:[1,0]
	v_pk_mul_f32 v[120:121], v[100:101], 0.5 op_sel_hi:[1,0]
	v_pk_mul_f32 v[118:119], v[98:99], 0.5 op_sel_hi:[1,0]
	v_pk_mul_f32 v[116:117], v[96:97], 0.5 op_sel_hi:[1,0]
	v_pk_mul_f32 v[114:115], v[78:79], 0.5 op_sel_hi:[1,0]
	v_pk_mul_f32 v[112:113], v[76:77], 0.5 op_sel_hi:[1,0]
	v_pk_mul_f32 v[110:111], v[74:75], 0.5 op_sel_hi:[1,0]
	v_pk_mul_f32 v[108:109], v[72:73], 0.5 op_sel_hi:[1,0]
	v_pk_mul_f32 v[106:107], v[86:87], 0.5 op_sel_hi:[1,0]
	v_pk_mul_f32 v[104:105], v[84:85], 0.5 op_sel_hi:[1,0]
	v_pk_mul_f32 v[102:103], v[82:83], 0.5 op_sel_hi:[1,0]
	v_pk_mul_f32 v[100:101], v[80:81], 0.5 op_sel_hi:[1,0]
	v_pk_mul_f32 v[98:99], v[70:71], 0.5 op_sel_hi:[1,0]
	v_pk_mul_f32 v[96:97], v[68:69], 0.5 op_sel_hi:[1,0]
	v_pk_mul_f32 v[94:95], v[66:67], 0.5 op_sel_hi:[1,0]
	v_pk_mul_f32 v[92:93], v[64:65], 0.5 op_sel_hi:[1,0]
	v_pk_mul_f32 v[86:87], v[62:63], 0.5 op_sel_hi:[1,0]
	v_pk_mul_f32 v[90:91], v[60:61], 0.5 op_sel_hi:[1,0]
	v_pk_mul_f32 v[84:85], v[58:59], 0.5 op_sel_hi:[1,0]
	v_pk_mul_f32 v[88:89], v[56:57], 0.5 op_sel_hi:[1,0]
	v_pk_mul_f32 v[80:81], v[46:47], 0.5 op_sel_hi:[1,0]
	v_pk_mul_f32 v[82:83], v[44:45], 0.5 op_sel_hi:[1,0]
	v_pk_mul_f32 v[78:79], v[38:39], 0.5 op_sel_hi:[1,0]
	v_pk_mul_f32 v[76:77], v[36:37], 0.5 op_sel_hi:[1,0]
	v_pk_mul_f32 v[74:75], v[54:55], 0.5 op_sel_hi:[1,0]
	v_pk_mul_f32 v[72:73], v[52:53], 0.5 op_sel_hi:[1,0]
	v_pk_mul_f32 v[70:71], v[50:51], 0.5 op_sel_hi:[1,0]
	v_pk_mul_f32 v[68:69], v[48:49], 0.5 op_sel_hi:[1,0]
	v_pk_mul_f32 v[66:67], v[30:31], 0.5 op_sel_hi:[1,0]
	v_pk_mul_f32 v[64:65], v[28:29], 0.5 op_sel_hi:[1,0]
	v_pk_mul_f32 v[62:63], v[22:23], 0.5 op_sel_hi:[1,0]
	v_pk_mul_f32 v[60:61], v[20:21], 0.5 op_sel_hi:[1,0]
	v_pk_mul_f32 v[58:59], v[42:43], 0.5 op_sel_hi:[1,0]
	v_pk_mul_f32 v[56:57], v[40:41], 0.5 op_sel_hi:[1,0]
	v_pk_mul_f32 v[54:55], v[34:35], 0.5 op_sel_hi:[1,0]
	v_pk_mul_f32 v[52:53], v[32:33], 0.5 op_sel_hi:[1,0]
	v_pk_mul_f32 v[50:51], v[14:15], 0.5 op_sel_hi:[1,0]
	v_pk_mul_f32 v[48:49], v[12:13], 0.5 op_sel_hi:[1,0]
	v_pk_mul_f32 v[46:47], v[10:11], 0.5 op_sel_hi:[1,0]
	v_pk_mul_f32 v[44:45], v[8:9], 0.5 op_sel_hi:[1,0]
	v_pk_mul_f32 v[42:43], v[26:27], 0.5 op_sel_hi:[1,0]
	v_pk_mul_f32 v[40:41], v[24:25], 0.5 op_sel_hi:[1,0]
	v_pk_mul_f32 v[38:39], v[18:19], 0.5 op_sel_hi:[1,0]
	v_pk_mul_f32 v[36:37], v[16:17], 0.5 op_sel_hi:[1,0]
	v_pk_mul_f32 v[34:35], v[6:7], 0.5 op_sel_hi:[1,0]
	v_pk_mul_f32 v[32:33], v[4:5], 0.5 op_sel_hi:[1,0]
	v_pk_mul_f32 v[30:31], v[2:3], 0.5 op_sel_hi:[1,0]
	v_pk_mul_f32 v[28:29], v[0:1], 0.5 op_sel_hi:[1,0]

; template <class Epi, class Ord>
; __device__ __forceinline__ void gemm_phase(LAS unsigned char* lds, const Gemm g, const Ord& S, const Epi& E) {
;     ...
;             const bool last = (t == nt - 2);
;             const char* a1 = cA + (size_t)(t + 1) * kstep;
;             const char* a2 = last ? nA : cA + (size_t)(t + 2) * kstep; const char* b2 = last ? nB : cB + (size_t)(t + 2) * kstep;
;             const char* a3 = a2 + kstep; const char* b3 = b2 + kstep;
;     ...
;         for (int a = 0; a < 2; ++a)
; #pragma unroll
;             for (int b = 0; b < 2; ++b)
; #pragma unroll
;                 for (int m = 0; m < 4; ++m)
; #pragma unroll
;                     for (int n = 0; n < 2; ++n) acc[a][b][m][n] = (f32x4){0.f, 0.f, 0.f, 0.f};
;         cur = nxt; cA = nA; cB = nB; ++ui;
.LBB0_574:
	v_mov_b32_e32 v127, 0
	s_andn2_b64 vcc, exec, s[10:11]
	v_mov_b32_e32 v126, v127
	v_mov_b32_e32 v125, v127
	v_mov_b32_e32 v124, v127
	v_mov_b32_e32 v123, v127
	v_mov_b32_e32 v122, v127
	v_mov_b32_e32 v121, v127
	v_mov_b32_e32 v120, v127
	v_mov_b32_e32 v111, v127
	v_mov_b32_e32 v110, v127
	v_mov_b32_e32 v109, v127
	v_mov_b32_e32 v108, v127
	v_mov_b32_e32 v107, v127
	v_mov_b32_e32 v106, v127
	v_mov_b32_e32 v105, v127
	v_mov_b32_e32 v104, v127
	v_mov_b32_e32 v95, v127
	v_mov_b32_e32 v94, v127
	v_mov_b32_e32 v93, v127
	v_mov_b32_e32 v92, v127
	v_mov_b32_e32 v91, v127
	v_mov_b32_e32 v90, v127
	v_mov_b32_e32 v89, v127
	v_mov_b32_e32 v88, v127
	v_mov_b32_e32 v79, v127
	v_mov_b32_e32 v78, v127
	v_mov_b32_e32 v77, v127
	v_mov_b32_e32 v76, v127
	v_mov_b32_e32 v75, v127
	v_mov_b32_e32 v74, v127
	v_mov_b32_e32 v73, v127
	v_mov_b32_e32 v72, v127
	v_mov_b32_e32 v119, v127
	v_mov_b32_e32 v118, v127
	v_mov_b32_e32 v117, v127
	v_mov_b32_e32 v116, v127
	v_mov_b32_e32 v115, v127
	v_mov_b32_e32 v114, v127
	v_mov_b32_e32 v113, v127
	v_mov_b32_e32 v112, v127
	v_mov_b32_e32 v103, v127
	v_mov_b32_e32 v102, v127
	v_mov_b32_e32 v101, v127
	v_mov_b32_e32 v100, v127
	v_mov_b32_e32 v99, v127
	v_mov_b32_e32 v98, v127
	v_mov_b32_e32 v97, v127
	v_mov_b32_e32 v96, v127
	v_mov_b32_e32 v87, v127
	v_mov_b32_e32 v86, v127
	v_mov_b32_e32 v85, v127
	v_mov_b32_e32 v84, v127
	v_mov_b32_e32 v83, v127
	v_mov_b32_e32 v82, v127
	v_mov_b32_e32 v81, v127
	v_mov_b32_e32 v80, v127
	v_mov_b32_e32 v71, v127
	v_mov_b32_e32 v70, v127
	v_mov_b32_e32 v69, v127
	v_mov_b32_e32 v68, v127
	v_mov_b32_e32 v67, v127
	v_mov_b32_e32 v66, v127
	v_mov_b32_e32 v65, v127
	v_mov_b32_e32 v64, v127
	v_mov_b32_e32 v63, v127
	v_mov_b32_e32 v62, v127
	v_mov_b32_e32 v61, v127
	v_mov_b32_e32 v60, v127
	v_mov_b32_e32 v59, v127
	v_mov_b32_e32 v58, v127
	v_mov_b32_e32 v57, v127
	v_mov_b32_e32 v56, v127
	v_mov_b32_e32 v47, v127
	v_mov_b32_e32 v46, v127
	v_mov_b32_e32 v45, v127
	v_mov_b32_e32 v44, v127
	v_mov_b32_e32 v43, v127
	v_mov_b32_e32 v42, v127
	v_mov_b32_e32 v41, v127
	v_mov_b32_e32 v40, v127
	v_mov_b32_e32 v31, v127
	v_mov_b32_e32 v30, v127
	v_mov_b32_e32 v29, v127
	v_mov_b32_e32 v28, v127
	v_mov_b32_e32 v27, v127
	v_mov_b32_e32 v26, v127
	v_mov_b32_e32 v25, v127
	v_mov_b32_e32 v24, v127
	v_mov_b32_e32 v15, v127
	v_mov_b32_e32 v14, v127
	v_mov_b32_e32 v13, v127
	v_mov_b32_e32 v12, v127
	v_mov_b32_e32 v11, v127
	v_mov_b32_e32 v10, v127
	v_mov_b32_e32 v9, v127
	v_mov_b32_e32 v8, v127
	v_mov_b32_e32 v55, v127
	v_mov_b32_e32 v54, v127
	v_mov_b32_e32 v53, v127
	v_mov_b32_e32 v52, v127
	v_mov_b32_e32 v51, v127
	v_mov_b32_e32 v50, v127
	v_mov_b32_e32 v49, v127
	v_mov_b32_e32 v48, v127
	v_mov_b32_e32 v39, v127
	v_mov_b32_e32 v38, v127
	v_mov_b32_e32 v37, v127
	v_mov_b32_e32 v36, v127
	v_mov_b32_e32 v35, v127
	v_mov_b32_e32 v34, v127
	v_mov_b32_e32 v33, v127
	v_mov_b32_e32 v32, v127
	v_mov_b32_e32 v23, v127
	v_mov_b32_e32 v22, v127
	v_mov_b32_e32 v21, v127
	v_mov_b32_e32 v20, v127
	v_mov_b32_e32 v19, v127
	v_mov_b32_e32 v18, v127
	v_mov_b32_e32 v17, v127
	v_mov_b32_e32 v16, v127
	v_mov_b32_e32 v7, v127
	v_mov_b32_e32 v6, v127
	v_mov_b32_e32 v5, v127
	v_mov_b32_e32 v4, v127
	v_mov_b32_e32 v3, v127
	v_mov_b32_e32 v2, v127
	s_waitcnt lgkmcnt(0)
	v_mov_b32_e32 v1, v127
	v_mov_b32_e32 v0, v127
	s_cbranch_vccnz .LBB0_577
	s_add_u32 s90, s16, 0x100
	s_addc_u32 s91, s17, 0
	s_add_u32 s46, s46, 0x100
	v_mov_b32_e32 v0, 0
	v_mov_b32_e32 v1, 0
	s_addc_u32 s47, s47, 0
	s_mov_b32 s12, 0
	v_pk_mov_b32 v[2:3], v[0:1], v[0:1]
	v_pk_mov_b32 v[4:5], v[0:1], v[0:1]
	v_pk_mov_b32 v[6:7], v[0:1], v[0:1]
	v_pk_mov_b32 v[16:17], v[0:1], v[0:1]
	v_pk_mov_b32 v[18:19], v[0:1], v[0:1]
	v_pk_mov_b32 v[20:21], v[0:1], v[0:1]
	v_pk_mov_b32 v[22:23], v[0:1], v[0:1]
	v_pk_mov_b32 v[32:33], v[0:1], v[0:1]
	v_pk_mov_b32 v[34:35], v[0:1], v[0:1]
	v_pk_mov_b32 v[36:37], v[0:1], v[0:1]
	v_pk_mov_b32 v[38:39], v[0:1], v[0:1]
	v_pk_mov_b32 v[48:49], v[0:1], v[0:1]
	v_pk_mov_b32 v[50:51], v[0:1], v[0:1]
	v_pk_mov_b32 v[52:53], v[0:1], v[0:1]
	v_pk_mov_b32 v[54:55], v[0:1], v[0:1]
	v_pk_mov_b32 v[8:9], v[0:1], v[0:1]
	v_pk_mov_b32 v[10:11], v[0:1], v[0:1]
	v_pk_mov_b32 v[12:13], v[0:1], v[0:1]
	v_pk_mov_b32 v[14:15], v[0:1], v[0:1]
	v_pk_mov_b32 v[24:25], v[0:1], v[0:1]
	v_pk_mov_b32 v[26:27], v[0:1], v[0:1]
	v_pk_mov_b32 v[28:29], v[0:1], v[0:1]
	v_pk_mov_b32 v[30:31], v[0:1], v[0:1]
	v_pk_mov_b32 v[40:41], v[0:1], v[0:1]
	v_pk_mov_b32 v[42:43], v[0:1], v[0:1]
	v_pk_mov_b32 v[44:45], v[0:1], v[0:1]
	v_pk_mov_b32 v[46:47], v[0:1], v[0:1]
	v_pk_mov_b32 v[56:57], v[0:1], v[0:1]
	v_pk_mov_b32 v[58:59], v[0:1], v[0:1]
	v_pk_mov_b32 v[60:61], v[0:1], v[0:1]
	v_pk_mov_b32 v[62:63], v[0:1], v[0:1]
	v_pk_mov_b32 v[64:65], v[0:1], v[0:1]
	v_pk_mov_b32 v[66:67], v[0:1], v[0:1]
	v_pk_mov_b32 v[68:69], v[0:1], v[0:1]
	v_pk_mov_b32 v[70:71], v[0:1], v[0:1]
	v_pk_mov_b32 v[80:81], v[0:1], v[0:1]
	v_pk_mov_b32 v[82:83], v[0:1], v[0:1]
	v_pk_mov_b32 v[84:85], v[0:1], v[0:1]
	v_pk_mov_b32 v[86:87], v[0:1], v[0:1]
	v_pk_mov_b32 v[96:97], v[0:1], v[0:1]
	v_pk_mov_b32 v[98:99], v[0:1], v[0:1]
	v_pk_mov_b32 v[100:101], v[0:1], v[0:1]
	v_pk_mov_b32 v[102:103], v[0:1], v[0:1]
	v_pk_mov_b32 v[112:113], v[0:1], v[0:1]
	v_pk_mov_b32 v[114:115], v[0:1], v[0:1]
	v_pk_mov_b32 v[116:117], v[0:1], v[0:1]
	v_pk_mov_b32 v[118:119], v[0:1], v[0:1]
	v_pk_mov_b32 v[72:73], v[0:1], v[0:1]
	v_pk_mov_b32 v[74:75], v[0:1], v[0:1]
	v_pk_mov_b32 v[76:77], v[0:1], v[0:1]
	v_pk_mov_b32 v[78:79], v[0:1], v[0:1]
	v_pk_mov_b32 v[88:89], v[0:1], v[0:1]
	v_pk_mov_b32 v[90:91], v[0:1], v[0:1]
	v_pk_mov_b32 v[92:93], v[0:1], v[0:1]
	v_pk_mov_b32 v[94:95], v[0:1], v[0:1]
	v_pk_mov_b32 v[104:105], v[0:1], v[0:1]
	v_pk_mov_b32 v[106:107], v[0:1], v[0:1]
	v_pk_mov_b32 v[108:109], v[0:1], v[0:1]
	v_pk_mov_b32 v[110:111], v[0:1], v[0:1]
	v_pk_mov_b32 v[120:121], v[0:1], v[0:1]
	v_pk_mov_b32 v[122:123], v[0:1], v[0:1]
	v_pk_mov_b32 v[124:125], v[0:1], v[0:1]
	v_pk_mov_b32 v[126:127], v[0:1], v[0:1]
	s_add_i32 s92, s12, 2
	s_cmp_eq_u32 s72, s12
	s_cselect_b32 s20, s0, s46
	s_cselect_b32 s21, s1, s47
	s_cselect_b32 s16, s48, s90
	s_cselect_b32 s17, s49, s91
	s_add_u32 s12, s20, 0x80
	s_addc_u32 s13, s21, 0
	s_add_i32 s82, 0, 0x10000
	v_add_u32_e32 v140, s82, v197
; #define PG8_STAGE(bufoff, gbase, voff) do { const char* _gb = (const char*)(gbase); asm volatile("" : "+s"(_gb)); _Pragma("unroll") for (int _i = 0; _i < 2; ++_i) { unsigned _vo = (voff)[_i]; asm volatile("" : "+v"(_vo)); \
;         __builtin_amdgcn_global_load_lds((const GAS unsigned*)(_gb + _vo), (LAS unsigned*)(lds + (bufoff) + ldsw + _i * 8192), 16, 0, 0); } } while (0)
; #define PG8_LDA(dst, b, h) do { _Pragma("unroll") for (int m = 0; m < 4; ++m) _Pragma("unroll") for (int k = 0; k < 2; ++k) dst[m][k] = *(const LAS bf16x8*)(lds + PG8_SA(b, h) + aoff + m * 2048 + k * 1024); } while (0)
; #define PG8_LDB(dst, b, h) do { _Pragma("unroll") for (int n = 0; n < 2; ++n) _Pragma("unroll") for (int k = 0; k < 2; ++k) dst[n][k] = *(const LAS bf16x8*)(lds + PG8_SB(b, h) + boff + n * 2048 + k * 1024); } while (0)
; #define PG8_MMA(ai, bj, At, Bt) do { __builtin_amdgcn_s_setprio(1); _Pragma("unroll") for (int m = 0; m < 4; ++m) _Pragma("unroll") for (int n = 0; n < 2; ++n) _Pragma("unroll") for (int k = 0; k < 2; ++k) \
;         acc[ai][bj][m][n] = __builtin_amdgcn_mfma_f32_16x16x32_bf16(Bt[n][k], At[m][k], acc[ai][bj][m][n], 0, 0, 0); __builtin_amdgcn_s_setprio(0); } while (0)
; #define PG8_WAIT_L(n) asm volatile("s_waitcnt lgkmcnt(" #n ")" ::: "memory")
; #define PG8_BAR __builtin_amdgcn_s_barrier()
; #define PG8_SCHED __builtin_amdgcn_sched_barrier(0)
; template <class Epi, class Ord>
; __device__ __forceinline__ void gemm_phase(LAS unsigned char* lds, const Gemm g, const Ord& S, const Epi& E) {
;     ...
;             const bool last = (t == nt - 2);
;             const char* a1 = cA + (size_t)(t + 1) * kstep;
;             const char* a2 = last ? nA : cA + (size_t)(t + 2) * kstep; const char* b2 = last ? nB : cB + (size_t)(t + 2) * kstep;
;             const char* a3 = a2 + kstep; const char* b3 = b2 + kstep;
;             PG8_LDB(B0, 0, 0); PG8_SCHED; PG8_LDA(At, 0, 0); PG8_STAGE(PG8_SA(1, 1), a1 + hstep, voffA);
;             PG8_WAIT_L(8); PG8_BAR; PG8_WAIT_L(0); PG8_MMA(0, 0, At, B0); PG8_BAR; PG8_SCHED;
;             PG8_LDB(B1, 0, 1); PG8_STAGE(PG8_SB(0, 0), b2, voffB);
;             PG8_BAR; PG8_WAIT_L(0); PG8_MMA(0, 1, At, B1); PG8_BAR;
;             PG8_LDA(At, 0, 1); PG8_STAGE(PG8_SA(0, 0), a2, voffA);
;             PG8_BAR; PG8_WAIT_L(0); PG8_MMA(1, 0, At, B0); PG8_BAR; PG8_SCHED;
.LBB0_576:
	ds_read_b128 v[128:131], v140
	ds_read_b128 v[132:135], v140 offset:1024
	ds_read_b128 v[136:139], v140 offset:2048
	ds_read_b128 v[140:143], v140 offset:3072
	s_add_u32 s22, s46, s52
	s_addc_u32 s23, s47, s53
	s_add_u32 s22, s22, 0xffffff80
	s_addc_u32 s23, s23, -1
	v_mov_b32_e32 v158, v151
	ds_read_b128 v[144:147], v202
	ds_read_b128 v[204:207], v202 offset:1024
	ds_read_b128 v[212:215], v202 offset:2048
	ds_read_b128 v[216:219], v202 offset:3072
	ds_read_b128 v[220:223], v202 offset:4096
	ds_read_b128 v[224:227], v202 offset:5120
	ds_read_b128 v[228:231], v202 offset:6144
	ds_read_b128 v[232:235], v202 offset:7168
	s_add_i32 m0, s37, 0xc000
	s_nop 0
	global_load_lds_dwordx4 v158, s[22:23]
	v_mov_b32_e32 v158, v195
	s_add_i32 m0, s37, 0xe000
	s_nop 0
	global_load_lds_dwordx4 v158, s[22:23]
	s_waitcnt lgkmcnt(8)
	s_barrier
	s_waitcnt lgkmcnt(0)
	s_setprio 1
	s_waitcnt lgkmcnt(0)
	v_mfma_f32_16x16x32_bf16 v[124:127], v[128:131], v[144:147], v[124:127]
	v_mfma_f32_16x16x32_bf16 v[120:123], v[136:139], v[144:147], v[120:123]
	v_mfma_f32_16x16x32_bf16 v[108:111], v[128:131], v[212:215], v[108:111]
	v_mfma_f32_16x16x32_bf16 v[104:107], v[136:139], v[212:215], v[104:107]
	v_mfma_f32_16x16x32_bf16 v[92:95], v[128:131], v[220:223], v[92:95]
	v_mfma_f32_16x16x32_bf16 v[88:91], v[136:139], v[220:223], v[88:91]
	v_mfma_f32_16x16x32_bf16 v[76:79], v[128:131], v[228:231], v[76:79]
	v_mfma_f32_16x16x32_bf16 v[72:75], v[136:139], v[228:231], v[72:75]
	v_mfma_f32_16x16x32_bf16 v[124:127], v[132:135], v[204:207], v[124:127]
	v_mfma_f32_16x16x32_bf16 v[120:123], v[140:143], v[204:207], v[120:123]
	v_mfma_f32_16x16x32_bf16 v[108:111], v[132:135], v[216:219], v[108:111]
	v_mfma_f32_16x16x32_bf16 v[104:107], v[140:143], v[216:219], v[104:107]
	v_mfma_f32_16x16x32_bf16 v[92:95], v[132:135], v[224:227], v[92:95]
	v_mfma_f32_16x16x32_bf16 v[88:91], v[140:143], v[224:227], v[88:91]
	v_mfma_f32_16x16x32_bf16 v[76:79], v[132:135], v[232:235], v[76:79]
	v_mfma_f32_16x16x32_bf16 v[72:75], v[140:143], v[232:235], v[72:75]
	s_setprio 0
	s_barrier
	s_add_i32 s84, 0, 0x14000
	v_add_u32_e32 v158, s84, v197
	ds_read_b128 v[236:239], v158
	ds_read_b128 v[240:243], v158 offset:1024
	ds_read_b128 v[244:247], v158 offset:2048
	ds_read_b128 v[248:251], v158 offset:3072
	s_mov_b64 s[22:23], s[16:17]
	v_mov_b32_e32 v158, v194
	s_add_i32 s82, s82, s36
	s_mov_b32 m0, s82
	s_nop 0
	global_load_lds_dwordx4 v158, s[22:23]
	v_mov_b32_e32 v158, v196
	s_add_i32 m0, s82, 0x2000
	s_nop 0
	global_load_lds_dwordx4 v158, s[22:23]
	s_barrier
	s_waitcnt lgkmcnt(0)
	s_setprio 1
	s_waitcnt lgkmcnt(0)
	v_mfma_f32_16x16x32_bf16 v[116:119], v[236:239], v[144:147], v[116:119]
	v_mfma_f32_16x16x32_bf16 v[112:115], v[244:247], v[144:147], v[112:115]
	v_mfma_f32_16x16x32_bf16 v[100:103], v[236:239], v[212:215], v[100:103]
	v_mfma_f32_16x16x32_bf16 v[96:99], v[244:247], v[212:215], v[96:99]
	v_mfma_f32_16x16x32_bf16 v[84:87], v[236:239], v[220:223], v[84:87]
	v_mfma_f32_16x16x32_bf16 v[80:83], v[244:247], v[220:223], v[80:83]
	v_mfma_f32_16x16x32_bf16 v[68:71], v[236:239], v[228:231], v[68:71]
	v_mfma_f32_16x16x32_bf16 v[64:67], v[244:247], v[228:231], v[64:67]
	v_mfma_f32_16x16x32_bf16 v[116:119], v[240:243], v[204:207], v[116:119]
	v_mfma_f32_16x16x32_bf16 v[112:115], v[248:251], v[204:207], v[112:115]
	v_mfma_f32_16x16x32_bf16 v[100:103], v[240:243], v[216:219], v[100:103]
	v_mfma_f32_16x16x32_bf16 v[96:99], v[248:251], v[216:219], v[96:99]
	v_mfma_f32_16x16x32_bf16 v[84:87], v[240:243], v[224:227], v[84:87]
	v_mfma_f32_16x16x32_bf16 v[80:83], v[248:251], v[224:227], v[80:83]
	v_mfma_f32_16x16x32_bf16 v[68:71], v[240:243], v[232:235], v[68:71]
	v_mfma_f32_16x16x32_bf16 v[64:67], v[248:251], v[232:235], v[64:67]
	s_setprio 0
	s_mov_b64 s[22:23], s[20:21]
	v_mov_b32_e32 v158, v151
	s_mov_b32 m0, s37
	s_barrier
	ds_read_b128 v[144:147], v202 offset:16384
	ds_read_b128 v[204:207], v202 offset:17408
	ds_read_b128 v[212:215], v202 offset:18432
	ds_read_b128 v[216:219], v202 offset:19456
	ds_read_b128 v[220:223], v202 offset:20480
	ds_read_b128 v[224:227], v202 offset:21504
	ds_read_b128 v[228:231], v202 offset:22528
	ds_read_b128 v[232:235], v202 offset:23552
	s_nop 0
	global_load_lds_dwordx4 v158, s[22:23]
	v_mov_b32_e32 v158, v195
	s_mov_b32 m0, s68
	s_nop 0
	global_load_lds_dwordx4 v158, s[22:23]
	s_barrier
	s_waitcnt lgkmcnt(0)
	s_setprio 1
	s_waitcnt lgkmcnt(0)
	v_mfma_f32_16x16x32_bf16 v[60:63], v[128:131], v[144:147], v[60:63]
	v_mfma_f32_16x16x32_bf16 v[56:59], v[136:139], v[144:147], v[56:59]
	v_mfma_f32_16x16x32_bf16 v[44:47], v[128:131], v[212:215], v[44:47]
	v_mfma_f32_16x16x32_bf16 v[40:43], v[136:139], v[212:215], v[40:43]
	v_mfma_f32_16x16x32_bf16 v[28:31], v[128:131], v[220:223], v[28:31]
	v_mfma_f32_16x16x32_bf16 v[24:27], v[136:139], v[220:223], v[24:27]
	v_mfma_f32_16x16x32_bf16 v[12:15], v[128:131], v[228:231], v[12:15]
	v_mfma_f32_16x16x32_bf16 v[8:11], v[136:139], v[228:231], v[8:11]
	v_mfma_f32_16x16x32_bf16 v[60:63], v[132:135], v[204:207], v[60:63]
	v_mfma_f32_16x16x32_bf16 v[56:59], v[140:143], v[204:207], v[56:59]
	v_mfma_f32_16x16x32_bf16 v[44:47], v[132:135], v[216:219], v[44:47]
	v_mfma_f32_16x16x32_bf16 v[40:43], v[140:143], v[216:219], v[40:43]
	v_mfma_f32_16x16x32_bf16 v[28:31], v[132:135], v[224:227], v[28:31]
	v_mfma_f32_16x16x32_bf16 v[24:27], v[140:143], v[224:227], v[24:27]
	v_mfma_f32_16x16x32_bf16 v[12:15], v[132:135], v[232:235], v[12:15]
	v_mfma_f32_16x16x32_bf16 v[8:11], v[140:143], v[232:235], v[8:11]
	s_setprio 0
	s_barrier
; #define PG8_STAGE(bufoff, gbase, voff) do { const char* _gb = (const char*)(gbase); asm volatile("" : "+s"(_gb)); _Pragma("unroll") for (int _i = 0; _i < 2; ++_i) { unsigned _vo = (voff)[_i]; asm volatile("" : "+v"(_vo)); \
;         __builtin_amdgcn_global_load_lds((const GAS unsigned*)(_gb + _vo), (LAS unsigned*)(lds + (bufoff) + ldsw + _i * 8192), 16, 0, 0); } } while (0)
; #define PG8_LDA(dst, b, h) do { _Pragma("unroll") for (int m = 0; m < 4; ++m) _Pragma("unroll") for (int k = 0; k < 2; ++k) dst[m][k] = *(const LAS bf16x8*)(lds + PG8_SA(b, h) + aoff + m * 2048 + k * 1024); } while (0)
; #define PG8_LDB(dst, b, h) do { _Pragma("unroll") for (int n = 0; n < 2; ++n) _Pragma("unroll") for (int k = 0; k < 2; ++k) dst[n][k] = *(const LAS bf16x8*)(lds + PG8_SB(b, h) + boff + n * 2048 + k * 1024); } while (0)
; #define PG8_MMA(ai, bj, At, Bt) do { __builtin_amdgcn_s_setprio(1); _Pragma("unroll") for (int m = 0; m < 4; ++m) _Pragma("unroll") for (int n = 0; n < 2; ++n) _Pragma("unroll") for (int k = 0; k < 2; ++k) \
;         acc[ai][bj][m][n] = __builtin_amdgcn_mfma_f32_16x16x32_bf16(Bt[n][k], At[m][k], acc[ai][bj][m][n], 0, 0, 0); __builtin_amdgcn_s_setprio(0); } while (0)
; #define PG8_WAIT_V(n) asm volatile("s_waitcnt vmcnt(" #n ")" ::: "memory")
; #define PG8_WAIT_L(n) asm volatile("s_waitcnt lgkmcnt(" #n ")" ::: "memory")
; #define PG8_BAR __builtin_amdgcn_s_barrier()
; #define PG8_SCHED __builtin_amdgcn_sched_barrier(0)
; template <class Epi, class Ord>
; __device__ __forceinline__ void gemm_phase(LAS unsigned char* lds, const Gemm g, const Ord& S, const Epi& E) {
;     ...
;             PG8_STAGE(PG8_SB(0, 1), b2 + hstep, voffB);
;             PG8_WAIT_V(6); PG8_BAR; PG8_MMA(1, 1, At, B1); PG8_BAR;
;             PG8_LDB(B0, 1, 0); PG8_SCHED; PG8_LDA(At, 1, 0); PG8_STAGE(PG8_SA(0, 1), a2 + hstep, voffA);
;             PG8_WAIT_L(8); PG8_BAR; PG8_WAIT_L(0); PG8_MMA(0, 0, At, B0); PG8_BAR; PG8_SCHED;
;             PG8_LDB(B1, 1, 1); PG8_STAGE(PG8_SB(1, 0), b3, voffB);
;             PG8_BAR; PG8_WAIT_L(0); PG8_MMA(0, 1, At, B1); PG8_BAR;
;             PG8_LDA(At, 1, 1); PG8_STAGE(PG8_SA(1, 0), a3, voffA);
	s_add_u32 s22, s16, s52
	s_addc_u32 s23, s17, s53
	s_mov_b64 s[82:83], s[22:23]
	v_mov_b32_e32 v128, v194
	s_add_i32 s84, s84, s36
	s_mov_b32 m0, s84
	s_nop 0
	global_load_lds_dwordx4 v128, s[82:83]
	v_mov_b32_e32 v128, v196
	s_add_i32 m0, s84, 0x2000
	s_nop 0
	global_load_lds_dwordx4 v128, s[82:83]
	s_waitcnt vmcnt(6)
	s_barrier
	s_setprio 1
	v_mfma_f32_16x16x32_bf16 v[52:55], v[236:239], v[144:147], v[52:55]
	v_mfma_f32_16x16x32_bf16 v[48:51], v[244:247], v[144:147], v[48:51]
	v_mfma_f32_16x16x32_bf16 v[36:39], v[236:239], v[212:215], v[36:39]
	v_mfma_f32_16x16x32_bf16 v[32:35], v[244:247], v[212:215], v[32:35]
	v_mfma_f32_16x16x32_bf16 v[20:23], v[236:239], v[220:223], v[20:23]
	v_mfma_f32_16x16x32_bf16 v[16:19], v[244:247], v[220:223], v[16:19]
	v_mfma_f32_16x16x32_bf16 v[4:7], v[236:239], v[228:231], v[4:7]
	v_mfma_f32_16x16x32_bf16 v[0:3], v[244:247], v[228:231], v[0:3]
	v_mfma_f32_16x16x32_bf16 v[52:55], v[240:243], v[204:207], v[52:55]
	v_mfma_f32_16x16x32_bf16 v[48:51], v[248:251], v[204:207], v[48:51]
	v_mfma_f32_16x16x32_bf16 v[36:39], v[240:243], v[216:219], v[36:39]
	v_mfma_f32_16x16x32_bf16 v[32:35], v[248:251], v[216:219], v[32:35]
	v_mfma_f32_16x16x32_bf16 v[20:23], v[240:243], v[224:227], v[20:23]
	v_mfma_f32_16x16x32_bf16 v[16:19], v[248:251], v[224:227], v[16:19]
	v_mfma_f32_16x16x32_bf16 v[4:7], v[240:243], v[232:235], v[4:7]
	v_mfma_f32_16x16x32_bf16 v[0:3], v[248:251], v[232:235], v[0:3]
	s_setprio 0
	s_add_i32 s82, 0, 0x18000
	v_add_u32_e32 v140, s82, v197
	s_barrier
	ds_read_b128 v[128:131], v140
	ds_read_b128 v[132:135], v140 offset:1024
	ds_read_b128 v[136:139], v140 offset:2048
	ds_read_b128 v[140:143], v140 offset:3072
	s_add_u32 s20, s20, s52
	s_addc_u32 s21, s21, s53
	v_mov_b32_e32 v158, v151
	s_mov_b32 m0, s69
	ds_read_b128 v[144:147], v202 offset:32768
	ds_read_b128 v[204:207], v202 offset:33792
	ds_read_b128 v[212:215], v202 offset:34816
	ds_read_b128 v[216:219], v202 offset:35840
	ds_read_b128 v[220:223], v202 offset:36864
	ds_read_b128 v[224:227], v202 offset:37888
	ds_read_b128 v[228:231], v202 offset:38912
	ds_read_b128 v[232:235], v202 offset:39936
	s_nop 0
	global_load_lds_dwordx4 v158, s[20:21]
	v_mov_b32_e32 v158, v195
	s_mov_b32 m0, s64
	s_nop 0
	global_load_lds_dwordx4 v158, s[20:21]
	s_waitcnt lgkmcnt(8)
	s_barrier
	s_waitcnt lgkmcnt(0)
	s_setprio 1
	s_waitcnt lgkmcnt(0)
	v_mfma_f32_16x16x32_bf16 v[124:127], v[128:131], v[144:147], v[124:127]
	v_mfma_f32_16x16x32_bf16 v[120:123], v[136:139], v[144:147], v[120:123]
	v_mfma_f32_16x16x32_bf16 v[108:111], v[128:131], v[212:215], v[108:111]
	v_mfma_f32_16x16x32_bf16 v[104:107], v[136:139], v[212:215], v[104:107]
	v_mfma_f32_16x16x32_bf16 v[92:95], v[128:131], v[220:223], v[92:95]
	v_mfma_f32_16x16x32_bf16 v[88:91], v[136:139], v[220:223], v[88:91]
	v_mfma_f32_16x16x32_bf16 v[76:79], v[128:131], v[228:231], v[76:79]
	v_mfma_f32_16x16x32_bf16 v[72:75], v[136:139], v[228:231], v[72:75]
	v_mfma_f32_16x16x32_bf16 v[124:127], v[132:135], v[204:207], v[124:127]
	v_mfma_f32_16x16x32_bf16 v[120:123], v[140:143], v[204:207], v[120:123]
	v_mfma_f32_16x16x32_bf16 v[108:111], v[132:135], v[216:219], v[108:111]
	v_mfma_f32_16x16x32_bf16 v[104:107], v[140:143], v[216:219], v[104:107]
	v_mfma_f32_16x16x32_bf16 v[92:95], v[132:135], v[224:227], v[92:95]
	v_mfma_f32_16x16x32_bf16 v[88:91], v[140:143], v[224:227], v[88:91]
	v_mfma_f32_16x16x32_bf16 v[76:79], v[132:135], v[232:235], v[76:79]
	v_mfma_f32_16x16x32_bf16 v[72:75], v[140:143], v[232:235], v[72:75]
	s_setprio 0
	s_barrier
	s_add_i32 s20, 0, 0x1c000
	v_add_u32_e32 v158, s20, v197
	s_add_u32 s16, s16, 0x80
	ds_read_b128 v[236:239], v158
	ds_read_b128 v[240:243], v158 offset:1024
	ds_read_b128 v[244:247], v158 offset:2048
	ds_read_b128 v[248:251], v158 offset:3072
	s_addc_u32 s17, s17, 0
	v_mov_b32_e32 v158, v194
	s_add_i32 s21, s82, s36
	s_mov_b32 m0, s21
	s_nop 0
	global_load_lds_dwordx4 v158, s[16:17]
	v_mov_b32_e32 v158, v196
	s_add_i32 m0, s21, 0x2000
	s_nop 0
	global_load_lds_dwordx4 v158, s[16:17]
	s_barrier
; #define PG8_STAGE(bufoff, gbase, voff) do { const char* _gb = (const char*)(gbase); asm volatile("" : "+s"(_gb)); _Pragma("unroll") for (int _i = 0; _i < 2; ++_i) { unsigned _vo = (voff)[_i]; asm volatile("" : "+v"(_vo)); \
;         __builtin_amdgcn_global_load_lds((const GAS unsigned*)(_gb + _vo), (LAS unsigned*)(lds + (bufoff) + ldsw + _i * 8192), 16, 0, 0); } } while (0)
; #define PG8_LDA(dst, b, h) do { _Pragma("unroll") for (int m = 0; m < 4; ++m) _Pragma("unroll") for (int k = 0; k < 2; ++k) dst[m][k] = *(const LAS bf16x8*)(lds + PG8_SA(b, h) + aoff + m * 2048 + k * 1024); } while (0)
; #define PG8_MMA(ai, bj, At, Bt) do { __builtin_amdgcn_s_setprio(1); _Pragma("unroll") for (int m = 0; m < 4; ++m) _Pragma("unroll") for (int n = 0; n < 2; ++n) _Pragma("unroll") for (int k = 0; k < 2; ++k) \
;         acc[ai][bj][m][n] = __builtin_amdgcn_mfma_f32_16x16x32_bf16(Bt[n][k], At[m][k], acc[ai][bj][m][n], 0, 0, 0); __builtin_amdgcn_s_setprio(0); } while (0)
; #define PG8_WAIT_V(n) asm volatile("s_waitcnt vmcnt(" #n ")" ::: "memory")
; #define PG8_WAIT_L(n) asm volatile("s_waitcnt lgkmcnt(" #n ")" ::: "memory")
; #define PG8_BAR __builtin_amdgcn_s_barrier()
; #define PG8_SCHED __builtin_amdgcn_sched_barrier(0)
; template <class Epi, class Ord>
; __device__ __forceinline__ void gemm_phase(LAS unsigned char* lds, const Gemm g, const Ord& S, const Epi& E) {
;     ...
;             const bool last = (t == nt - 2);
;             const char* a1 = cA + (size_t)(t + 1) * kstep;
;             const char* a2 = last ? nA : cA + (size_t)(t + 2) * kstep; const char* b2 = last ? nB : cB + (size_t)(t + 2) * kstep;
;             const char* a3 = a2 + kstep; const char* b3 = b2 + kstep;
;     ...
;             PG8_LDA(At, 1, 1); PG8_STAGE(PG8_SA(1, 0), a3, voffA);
;             PG8_BAR; PG8_WAIT_L(0); PG8_MMA(1, 0, At, B0); PG8_BAR; PG8_SCHED;
;             PG8_STAGE(PG8_SB(1, 1), b3 + hstep, voffB);
;             PG8_WAIT_V(6); PG8_BAR; PG8_MMA(1, 1, At, B1); PG8_BAR;
	s_waitcnt lgkmcnt(0)
	s_setprio 1
	s_waitcnt lgkmcnt(0)
	v_mfma_f32_16x16x32_bf16 v[116:119], v[236:239], v[144:147], v[116:119]
	v_mfma_f32_16x16x32_bf16 v[112:115], v[244:247], v[144:147], v[112:115]
	v_mfma_f32_16x16x32_bf16 v[100:103], v[236:239], v[212:215], v[100:103]
	v_mfma_f32_16x16x32_bf16 v[96:99], v[244:247], v[212:215], v[96:99]
	v_mfma_f32_16x16x32_bf16 v[84:87], v[236:239], v[220:223], v[84:87]
	v_mfma_f32_16x16x32_bf16 v[80:83], v[244:247], v[220:223], v[80:83]
	v_mfma_f32_16x16x32_bf16 v[68:71], v[236:239], v[228:231], v[68:71]
	v_mfma_f32_16x16x32_bf16 v[64:67], v[244:247], v[228:231], v[64:67]
	v_mfma_f32_16x16x32_bf16 v[116:119], v[240:243], v[204:207], v[116:119]
	v_mfma_f32_16x16x32_bf16 v[112:115], v[248:251], v[204:207], v[112:115]
	v_mfma_f32_16x16x32_bf16 v[100:103], v[240:243], v[216:219], v[100:103]
	v_mfma_f32_16x16x32_bf16 v[96:99], v[248:251], v[216:219], v[96:99]
	v_mfma_f32_16x16x32_bf16 v[84:87], v[240:243], v[224:227], v[84:87]
	v_mfma_f32_16x16x32_bf16 v[80:83], v[248:251], v[224:227], v[80:83]
	v_mfma_f32_16x16x32_bf16 v[68:71], v[240:243], v[232:235], v[68:71]
	v_mfma_f32_16x16x32_bf16 v[64:67], v[248:251], v[232:235], v[64:67]
	s_setprio 0
	v_mov_b32_e32 v158, v151
	s_mov_b32 m0, s73
	s_barrier
	ds_read_b128 v[144:147], v202 offset:49152
	ds_read_b128 v[204:207], v202 offset:50176
	ds_read_b128 v[212:215], v202 offset:51200
	ds_read_b128 v[216:219], v202 offset:52224
	ds_read_b128 v[220:223], v202 offset:53248
	ds_read_b128 v[224:227], v202 offset:54272
	ds_read_b128 v[228:231], v202 offset:55296
	ds_read_b128 v[232:235], v202 offset:56320
	s_nop 0
	global_load_lds_dwordx4 v158, s[12:13]
	v_mov_b32_e32 v158, v195
	s_mov_b32 m0, s74
	s_nop 0
	global_load_lds_dwordx4 v158, s[12:13]
	s_barrier
	s_waitcnt lgkmcnt(0)
	s_setprio 1
	s_waitcnt lgkmcnt(0)
	v_mfma_f32_16x16x32_bf16 v[60:63], v[128:131], v[144:147], v[60:63]
	v_mfma_f32_16x16x32_bf16 v[56:59], v[136:139], v[144:147], v[56:59]
	v_mfma_f32_16x16x32_bf16 v[44:47], v[128:131], v[212:215], v[44:47]
	v_mfma_f32_16x16x32_bf16 v[40:43], v[136:139], v[212:215], v[40:43]
	v_mfma_f32_16x16x32_bf16 v[28:31], v[128:131], v[220:223], v[28:31]
	v_mfma_f32_16x16x32_bf16 v[24:27], v[136:139], v[220:223], v[24:27]
	v_mfma_f32_16x16x32_bf16 v[12:15], v[128:131], v[228:231], v[12:15]
	v_mfma_f32_16x16x32_bf16 v[8:11], v[136:139], v[228:231], v[8:11]
	v_mfma_f32_16x16x32_bf16 v[60:63], v[132:135], v[204:207], v[60:63]
	v_mfma_f32_16x16x32_bf16 v[56:59], v[140:143], v[204:207], v[56:59]
	v_mfma_f32_16x16x32_bf16 v[44:47], v[132:135], v[216:219], v[44:47]
	v_mfma_f32_16x16x32_bf16 v[40:43], v[140:143], v[216:219], v[40:43]
	v_mfma_f32_16x16x32_bf16 v[28:31], v[132:135], v[224:227], v[28:31]
	v_mfma_f32_16x16x32_bf16 v[24:27], v[140:143], v[224:227], v[24:27]
	v_mfma_f32_16x16x32_bf16 v[12:15], v[132:135], v[232:235], v[12:15]
	v_mfma_f32_16x16x32_bf16 v[8:11], v[140:143], v[232:235], v[8:11]
	s_setprio 0
	s_barrier
	s_add_u32 s12, s22, 0x80
	s_addc_u32 s13, s23, 0
	v_mov_b32_e32 v128, v194
	s_add_i32 s16, s20, s36
	s_mov_b32 m0, s16
	s_nop 0
	global_load_lds_dwordx4 v128, s[12:13]
	v_mov_b32_e32 v128, v196
	s_add_i32 m0, s16, 0x2000
	s_nop 0
	global_load_lds_dwordx4 v128, s[12:13]
	s_waitcnt vmcnt(6)
	s_barrier
	s_setprio 1
	v_mfma_f32_16x16x32_bf16 v[52:55], v[236:239], v[144:147], v[52:55]
	v_mfma_f32_16x16x32_bf16 v[48:51], v[244:247], v[144:147], v[48:51]
	v_mfma_f32_16x16x32_bf16 v[36:39], v[236:239], v[212:215], v[36:39]
	v_mfma_f32_16x16x32_bf16 v[32:35], v[244:247], v[212:215], v[32:35]
	v_mfma_f32_16x16x32_bf16 v[20:23], v[236:239], v[220:223], v[20:23]
	v_mfma_f32_16x16x32_bf16 v[16:19], v[244:247], v[220:223], v[16:19]
	v_mfma_f32_16x16x32_bf16 v[4:7], v[236:239], v[228:231], v[4:7]
	v_mfma_f32_16x16x32_bf16 v[0:3], v[244:247], v[228:231], v[0:3]
	v_mfma_f32_16x16x32_bf16 v[52:55], v[240:243], v[204:207], v[52:55]
	v_mfma_f32_16x16x32_bf16 v[48:51], v[248:251], v[204:207], v[48:51]
	v_mfma_f32_16x16x32_bf16 v[36:39], v[240:243], v[216:219], v[36:39]
	v_mfma_f32_16x16x32_bf16 v[32:35], v[248:251], v[216:219], v[32:35]
	v_mfma_f32_16x16x32_bf16 v[20:23], v[240:243], v[224:227], v[20:23]
	v_mfma_f32_16x16x32_bf16 v[16:19], v[248:251], v[224:227], v[16:19]
	v_mfma_f32_16x16x32_bf16 v[4:7], v[240:243], v[232:235], v[4:7]
	v_mfma_f32_16x16x32_bf16 v[0:3], v[248:251], v[232:235], v[0:3]
	s_setprio 0
	s_add_u32 s90, s90, 0x100
	s_addc_u32 s91, s91, 0
	s_add_u32 s46, s46, 0x100
	s_addc_u32 s47, s47, 0
	s_mov_b32 s12, s92
	s_add_i32 s92, s12, 2
	s_cmp_eq_u32 s72, s12
	s_cselect_b32 s20, s0, s46
	s_cselect_b32 s21, s1, s47
	s_cselect_b32 s16, s48, s90
	s_cselect_b32 s17, s49, s91
	s_add_u32 s12, s20, 0x80
	s_addc_u32 s13, s21, 0
	s_add_i32 s82, 0, 0x10000
	v_add_u32_e32 v140, s82, v197
	s_sub_i32 s98, s92, 2
	s_cmp_ge_i32 s98, s76
	s_barrier
	s_cbranch_scc0 .LBB0_576

; template <class Epi, class Ord>
; __device__ __forceinline__ void gemm_phase(LAS unsigned char* lds, const Gemm g, const Ord& S, const Epi& E) {
;     ...
;             const bool last = (t == nt - 2);
;             const char* a1 = cA + (size_t)(t + 1) * kstep;
;             const char* a2 = last ? nA : cA + (size_t)(t + 2) * kstep; const char* b2 = last ? nB : cB + (size_t)(t + 2) * kstep;
;             const char* a3 = a2 + kstep; const char* b3 = b2 + kstep;
;     ...
;         if (!has_next) break;
; #pragma unroll
;         for (int a = 0; a < 2; ++a)
; #pragma unroll
;             for (int b = 0; b < 2; ++b)
; #pragma unroll
;                 for (int m = 0; m < 4; ++m)
; #pragma unroll
;                     for (int n = 0; n < 2; ++n) acc[a][b][m][n] = (f32x4){0.f, 0.f, 0.f, 0.f};
;         cur = nxt; cA = nA; cB = nB; ++ui;
.LBB0_611:
	v_mov_b32_e32 v123, 0
	v_mov_b32_e32 v122, 0
	s_andn2_b64 vcc, exec, s[16:17]
	v_pk_mov_b32 v[120:121], v[122:123], v[122:123]
	v_pk_mov_b32 v[114:115], v[122:123], v[122:123]
	v_pk_mov_b32 v[112:113], v[122:123], v[122:123]
	v_pk_mov_b32 v[106:107], v[122:123], v[122:123]
	v_pk_mov_b32 v[104:105], v[122:123], v[122:123]
	v_pk_mov_b32 v[98:99], v[122:123], v[122:123]
	v_pk_mov_b32 v[96:97], v[122:123], v[122:123]
	v_pk_mov_b32 v[90:91], v[122:123], v[122:123]
	v_pk_mov_b32 v[88:89], v[122:123], v[122:123]
	v_pk_mov_b32 v[82:83], v[122:123], v[122:123]
	v_pk_mov_b32 v[80:81], v[122:123], v[122:123]
	v_pk_mov_b32 v[74:75], v[122:123], v[122:123]
	v_pk_mov_b32 v[72:73], v[122:123], v[122:123]
	v_pk_mov_b32 v[66:67], v[122:123], v[122:123]
	v_pk_mov_b32 v[64:65], v[122:123], v[122:123]
	v_pk_mov_b32 v[126:127], v[122:123], v[122:123]
	v_pk_mov_b32 v[124:125], v[122:123], v[122:123]
	v_pk_mov_b32 v[118:119], v[122:123], v[122:123]
	v_pk_mov_b32 v[116:117], v[122:123], v[122:123]
	v_pk_mov_b32 v[110:111], v[122:123], v[122:123]
	v_pk_mov_b32 v[108:109], v[122:123], v[122:123]
	v_pk_mov_b32 v[102:103], v[122:123], v[122:123]
	v_pk_mov_b32 v[100:101], v[122:123], v[122:123]
	v_pk_mov_b32 v[94:95], v[122:123], v[122:123]
	v_pk_mov_b32 v[92:93], v[122:123], v[122:123]
	v_pk_mov_b32 v[86:87], v[122:123], v[122:123]
	v_pk_mov_b32 v[84:85], v[122:123], v[122:123]
	v_pk_mov_b32 v[78:79], v[122:123], v[122:123]
	v_pk_mov_b32 v[76:77], v[122:123], v[122:123]
	v_pk_mov_b32 v[70:71], v[122:123], v[122:123]
	v_pk_mov_b32 v[68:69], v[122:123], v[122:123]
	v_pk_mov_b32 v[58:59], v[122:123], v[122:123]
	v_pk_mov_b32 v[56:57], v[122:123], v[122:123]
	v_pk_mov_b32 v[50:51], v[122:123], v[122:123]
	v_pk_mov_b32 v[48:49], v[122:123], v[122:123]
	v_pk_mov_b32 v[42:43], v[122:123], v[122:123]
	v_pk_mov_b32 v[40:41], v[122:123], v[122:123]
	v_pk_mov_b32 v[34:35], v[122:123], v[122:123]
	v_pk_mov_b32 v[32:33], v[122:123], v[122:123]
	v_pk_mov_b32 v[26:27], v[122:123], v[122:123]
	v_pk_mov_b32 v[24:25], v[122:123], v[122:123]
	v_pk_mov_b32 v[18:19], v[122:123], v[122:123]
	v_pk_mov_b32 v[16:17], v[122:123], v[122:123]
	v_pk_mov_b32 v[10:11], v[122:123], v[122:123]
	v_pk_mov_b32 v[8:9], v[122:123], v[122:123]
	v_pk_mov_b32 v[2:3], v[122:123], v[122:123]
	v_pk_mov_b32 v[0:1], v[122:123], v[122:123]
	v_pk_mov_b32 v[62:63], v[122:123], v[122:123]
	v_pk_mov_b32 v[60:61], v[122:123], v[122:123]
	v_pk_mov_b32 v[54:55], v[122:123], v[122:123]
	v_pk_mov_b32 v[52:53], v[122:123], v[122:123]
	v_pk_mov_b32 v[46:47], v[122:123], v[122:123]
	v_pk_mov_b32 v[44:45], v[122:123], v[122:123]
	v_pk_mov_b32 v[38:39], v[122:123], v[122:123]
	v_pk_mov_b32 v[36:37], v[122:123], v[122:123]
	v_pk_mov_b32 v[30:31], v[122:123], v[122:123]
	v_pk_mov_b32 v[28:29], v[122:123], v[122:123]
	v_pk_mov_b32 v[22:23], v[122:123], v[122:123]
	v_pk_mov_b32 v[20:21], v[122:123], v[122:123]
	v_pk_mov_b32 v[14:15], v[122:123], v[122:123]
	v_pk_mov_b32 v[12:13], v[122:123], v[122:123]
	v_pk_mov_b32 v[6:7], v[122:123], v[122:123]
	v_pk_mov_b32 v[4:5], v[122:123], v[122:123]
	s_cbranch_vccnz .LBB0_603
	s_add_u32 s44, s44, 0x100
	s_addc_u32 s45, s45, 0
	s_add_u32 s46, s46, 0x100
	v_mov_b32_e32 v4, 0
	v_mov_b32_e32 v5, 0
	s_addc_u32 s47, s47, 0
	s_mov_b32 s12, 0
	v_pk_mov_b32 v[6:7], v[4:5], v[4:5]
	v_pk_mov_b32 v[12:13], v[4:5], v[4:5]
	v_pk_mov_b32 v[14:15], v[4:5], v[4:5]
	v_pk_mov_b32 v[20:21], v[4:5], v[4:5]
	v_pk_mov_b32 v[22:23], v[4:5], v[4:5]
	v_pk_mov_b32 v[28:29], v[4:5], v[4:5]
	v_pk_mov_b32 v[30:31], v[4:5], v[4:5]
	v_pk_mov_b32 v[36:37], v[4:5], v[4:5]
	v_pk_mov_b32 v[38:39], v[4:5], v[4:5]
	v_pk_mov_b32 v[44:45], v[4:5], v[4:5]
	v_pk_mov_b32 v[46:47], v[4:5], v[4:5]
	v_pk_mov_b32 v[52:53], v[4:5], v[4:5]
	v_pk_mov_b32 v[54:55], v[4:5], v[4:5]
	v_pk_mov_b32 v[60:61], v[4:5], v[4:5]
	v_pk_mov_b32 v[62:63], v[4:5], v[4:5]
	v_pk_mov_b32 v[0:1], v[4:5], v[4:5]
	v_pk_mov_b32 v[2:3], v[4:5], v[4:5]
	v_pk_mov_b32 v[8:9], v[4:5], v[4:5]
	v_pk_mov_b32 v[10:11], v[4:5], v[4:5]
	v_pk_mov_b32 v[16:17], v[4:5], v[4:5]
	v_pk_mov_b32 v[18:19], v[4:5], v[4:5]
	v_pk_mov_b32 v[24:25], v[4:5], v[4:5]
	v_pk_mov_b32 v[26:27], v[4:5], v[4:5]
	v_pk_mov_b32 v[32:33], v[4:5], v[4:5]
	v_pk_mov_b32 v[34:35], v[4:5], v[4:5]
	v_pk_mov_b32 v[40:41], v[4:5], v[4:5]
	v_pk_mov_b32 v[42:43], v[4:5], v[4:5]
	v_pk_mov_b32 v[48:49], v[4:5], v[4:5]
	v_pk_mov_b32 v[50:51], v[4:5], v[4:5]
	v_pk_mov_b32 v[56:57], v[4:5], v[4:5]
	v_pk_mov_b32 v[58:59], v[4:5], v[4:5]
	v_pk_mov_b32 v[68:69], v[4:5], v[4:5]
	v_pk_mov_b32 v[70:71], v[4:5], v[4:5]
	v_pk_mov_b32 v[76:77], v[4:5], v[4:5]
	v_pk_mov_b32 v[78:79], v[4:5], v[4:5]
	v_pk_mov_b32 v[84:85], v[4:5], v[4:5]
	v_pk_mov_b32 v[86:87], v[4:5], v[4:5]
	v_pk_mov_b32 v[92:93], v[4:5], v[4:5]
	v_pk_mov_b32 v[94:95], v[4:5], v[4:5]
	v_pk_mov_b32 v[100:101], v[4:5], v[4:5]
	v_pk_mov_b32 v[102:103], v[4:5], v[4:5]
	v_pk_mov_b32 v[108:109], v[4:5], v[4:5]
	v_pk_mov_b32 v[110:111], v[4:5], v[4:5]
	v_pk_mov_b32 v[116:117], v[4:5], v[4:5]
	v_pk_mov_b32 v[118:119], v[4:5], v[4:5]
	v_pk_mov_b32 v[124:125], v[4:5], v[4:5]
	v_pk_mov_b32 v[126:127], v[4:5], v[4:5]
	v_pk_mov_b32 v[64:65], v[4:5], v[4:5]
	v_pk_mov_b32 v[66:67], v[4:5], v[4:5]
	v_pk_mov_b32 v[72:73], v[4:5], v[4:5]
	v_pk_mov_b32 v[74:75], v[4:5], v[4:5]
	v_pk_mov_b32 v[80:81], v[4:5], v[4:5]
	v_pk_mov_b32 v[82:83], v[4:5], v[4:5]
	v_pk_mov_b32 v[88:89], v[4:5], v[4:5]
	v_pk_mov_b32 v[90:91], v[4:5], v[4:5]
	v_pk_mov_b32 v[96:97], v[4:5], v[4:5]
	v_pk_mov_b32 v[98:99], v[4:5], v[4:5]
	v_pk_mov_b32 v[104:105], v[4:5], v[4:5]
	v_pk_mov_b32 v[106:107], v[4:5], v[4:5]
	v_pk_mov_b32 v[112:113], v[4:5], v[4:5]
	v_pk_mov_b32 v[114:115], v[4:5], v[4:5]
	v_pk_mov_b32 v[120:121], v[4:5], v[4:5]
	v_pk_mov_b32 v[122:123], v[4:5], v[4:5]
	s_add_i32 s74, s12, 2
	s_cmp_eq_u32 s67, s12
	s_cselect_b32 s22, s38, s46
	s_cselect_b32 s23, s39, s47
	s_cselect_b32 s20, s42, s44
	s_cselect_b32 s21, s43, s45
	s_add_u32 s12, s22, 0x80
	s_addc_u32 s13, s23, 0
	s_add_i32 s75, 0, 0x10000
	v_add_u32_e32 v152, s75, v133
; #define PG8_STAGE(bufoff, gbase, voff) do { const char* _gb = (const char*)(gbase); asm volatile("" : "+s"(_gb)); _Pragma("unroll") for (int _i = 0; _i < 2; ++_i) { unsigned _vo = (voff)[_i]; asm volatile("" : "+v"(_vo)); \
;         __builtin_amdgcn_global_load_lds((const GAS unsigned*)(_gb + _vo), (LAS unsigned*)(lds + (bufoff) + ldsw + _i * 8192), 16, 0, 0); } } while (0)
; #define PG8_LDA(dst, b, h) do { _Pragma("unroll") for (int m = 0; m < 4; ++m) _Pragma("unroll") for (int k = 0; k < 2; ++k) dst[m][k] = *(const LAS bf16x8*)(lds + PG8_SA(b, h) + aoff + m * 2048 + k * 1024); } while (0)
; #define PG8_LDB(dst, b, h) do { _Pragma("unroll") for (int n = 0; n < 2; ++n) _Pragma("unroll") for (int k = 0; k < 2; ++k) dst[n][k] = *(const LAS bf16x8*)(lds + PG8_SB(b, h) + boff + n * 2048 + k * 1024); } while (0)
; #define PG8_MMA(ai, bj, At, Bt) do { __builtin_amdgcn_s_setprio(1); _Pragma("unroll") for (int m = 0; m < 4; ++m) _Pragma("unroll") for (int n = 0; n < 2; ++n) _Pragma("unroll") for (int k = 0; k < 2; ++k) \
;         acc[ai][bj][m][n] = __builtin_amdgcn_mfma_f32_16x16x32_bf16(Bt[n][k], At[m][k], acc[ai][bj][m][n], 0, 0, 0); __builtin_amdgcn_s_setprio(0); } while (0)
; #define PG8_WAIT_L(n) asm volatile("s_waitcnt lgkmcnt(" #n ")" ::: "memory")
; #define PG8_BAR __builtin_amdgcn_s_barrier()
; #define PG8_SCHED __builtin_amdgcn_sched_barrier(0)
; template <class Epi, class Ord>
; __device__ __forceinline__ void gemm_phase(LAS unsigned char* lds, const Gemm g, const Ord& S, const Epi& E) {
;     ...
;             const bool last = (t == nt - 2);
;             const char* a1 = cA + (size_t)(t + 1) * kstep;
;             const char* a2 = last ? nA : cA + (size_t)(t + 2) * kstep; const char* b2 = last ? nB : cB + (size_t)(t + 2) * kstep;
;             const char* a3 = a2 + kstep; const char* b3 = b2 + kstep;
;             PG8_LDB(B0, 0, 0); PG8_SCHED; PG8_LDA(At, 0, 0); PG8_STAGE(PG8_SA(1, 1), a1 + hstep, voffA);
;             PG8_WAIT_L(8); PG8_BAR; PG8_WAIT_L(0); PG8_MMA(0, 0, At, B0); PG8_BAR; PG8_SCHED;
;             PG8_LDB(B1, 0, 1); PG8_STAGE(PG8_SB(0, 0), b2, voffB);
;             PG8_BAR; PG8_WAIT_L(0); PG8_MMA(0, 1, At, B1); PG8_BAR;
;             PG8_LDA(At, 0, 1); PG8_STAGE(PG8_SA(0, 0), a2, voffA);
;             PG8_BAR; PG8_WAIT_L(0); PG8_MMA(1, 0, At, B0); PG8_BAR; PG8_SCHED;
.LBB0_613:
	ds_read_b128 v[140:143], v152
	ds_read_b128 v[144:147], v152 offset:1024
	ds_read_b128 v[148:151], v152 offset:2048
	ds_read_b128 v[152:155], v152 offset:3072
	s_add_u32 s24, s46, s0
	s_addc_u32 s25, s47, s1
	s_add_u32 s24, s24, 0xffffff80
	s_addc_u32 s25, s25, -1
	v_mov_b32_e32 v168, v128
	ds_read_b128 v[156:159], v139
	ds_read_b128 v[192:195], v139 offset:1024
	ds_read_b128 v[196:199], v139 offset:2048
	ds_read_b128 v[200:203], v139 offset:3072
	ds_read_b128 v[204:207], v139 offset:4096
	ds_read_b128 v[212:215], v139 offset:5120
	ds_read_b128 v[216:219], v139 offset:6144
	ds_read_b128 v[220:223], v139 offset:7168
	s_add_i32 m0, s53, 0xc000
	s_nop 0
	global_load_lds_dwordx4 v168, s[24:25]
	v_mov_b32_e32 v168, v130
	s_add_i32 m0, s53, 0xe000
	s_nop 0
	global_load_lds_dwordx4 v168, s[24:25]
	s_waitcnt lgkmcnt(8)
	s_barrier
	s_waitcnt lgkmcnt(0)
	s_setprio 1
	s_waitcnt lgkmcnt(0)
	v_mfma_f32_16x16x32_bf16 v[120:123], v[140:143], v[156:159], v[120:123]
	v_mfma_f32_16x16x32_bf16 v[112:115], v[148:151], v[156:159], v[112:115]
	v_mfma_f32_16x16x32_bf16 v[104:107], v[140:143], v[196:199], v[104:107]
	v_mfma_f32_16x16x32_bf16 v[96:99], v[148:151], v[196:199], v[96:99]
	v_mfma_f32_16x16x32_bf16 v[88:91], v[140:143], v[204:207], v[88:91]
	v_mfma_f32_16x16x32_bf16 v[80:83], v[148:151], v[204:207], v[80:83]
	v_mfma_f32_16x16x32_bf16 v[72:75], v[140:143], v[216:219], v[72:75]
	v_mfma_f32_16x16x32_bf16 v[64:67], v[148:151], v[216:219], v[64:67]
	v_mfma_f32_16x16x32_bf16 v[120:123], v[144:147], v[192:195], v[120:123]
	v_mfma_f32_16x16x32_bf16 v[112:115], v[152:155], v[192:195], v[112:115]
	v_mfma_f32_16x16x32_bf16 v[104:107], v[144:147], v[200:203], v[104:107]
	v_mfma_f32_16x16x32_bf16 v[96:99], v[152:155], v[200:203], v[96:99]
	v_mfma_f32_16x16x32_bf16 v[88:91], v[144:147], v[212:215], v[88:91]
	v_mfma_f32_16x16x32_bf16 v[80:83], v[152:155], v[212:215], v[80:83]
	v_mfma_f32_16x16x32_bf16 v[72:75], v[144:147], v[220:223], v[72:75]
	v_mfma_f32_16x16x32_bf16 v[64:67], v[152:155], v[220:223], v[64:67]
	s_setprio 0
	s_barrier
	s_add_i32 s78, 0, 0x14000
	v_add_u32_e32 v168, s78, v133
	ds_read_b128 v[224:227], v168
	ds_read_b128 v[228:231], v168 offset:1024
	ds_read_b128 v[232:235], v168 offset:2048
	ds_read_b128 v[236:239], v168 offset:3072
	s_mov_b64 s[24:25], s[20:21]
	v_mov_b32_e32 v168, v129
	s_add_i32 s75, s75, s52
	s_mov_b32 m0, s75
	s_nop 0
	global_load_lds_dwordx4 v168, s[24:25]
	v_mov_b32_e32 v168, v131
	s_add_i32 m0, s75, 0x2000
	s_nop 0
	global_load_lds_dwordx4 v168, s[24:25]
	s_barrier
	s_waitcnt lgkmcnt(0)
	s_setprio 1
	s_waitcnt lgkmcnt(0)
	v_mfma_f32_16x16x32_bf16 v[124:127], v[224:227], v[156:159], v[124:127]
	v_mfma_f32_16x16x32_bf16 v[116:119], v[232:235], v[156:159], v[116:119]
	v_mfma_f32_16x16x32_bf16 v[108:111], v[224:227], v[196:199], v[108:111]
	v_mfma_f32_16x16x32_bf16 v[100:103], v[232:235], v[196:199], v[100:103]
	v_mfma_f32_16x16x32_bf16 v[92:95], v[224:227], v[204:207], v[92:95]
	v_mfma_f32_16x16x32_bf16 v[84:87], v[232:235], v[204:207], v[84:87]
	v_mfma_f32_16x16x32_bf16 v[76:79], v[224:227], v[216:219], v[76:79]
	v_mfma_f32_16x16x32_bf16 v[68:71], v[232:235], v[216:219], v[68:71]
	v_mfma_f32_16x16x32_bf16 v[124:127], v[228:231], v[192:195], v[124:127]
	v_mfma_f32_16x16x32_bf16 v[116:119], v[236:239], v[192:195], v[116:119]
	v_mfma_f32_16x16x32_bf16 v[108:111], v[228:231], v[200:203], v[108:111]
	v_mfma_f32_16x16x32_bf16 v[100:103], v[236:239], v[200:203], v[100:103]
	v_mfma_f32_16x16x32_bf16 v[92:95], v[228:231], v[212:215], v[92:95]
	v_mfma_f32_16x16x32_bf16 v[84:87], v[236:239], v[212:215], v[84:87]
	v_mfma_f32_16x16x32_bf16 v[76:79], v[228:231], v[220:223], v[76:79]
	v_mfma_f32_16x16x32_bf16 v[68:71], v[236:239], v[220:223], v[68:71]
	s_setprio 0
	s_mov_b64 s[24:25], s[22:23]
	v_mov_b32_e32 v168, v128
	s_mov_b32 m0, s53
	s_barrier
	ds_read_b128 v[156:159], v139 offset:16384
	ds_read_b128 v[192:195], v139 offset:17408
	ds_read_b128 v[196:199], v139 offset:18432
	ds_read_b128 v[200:203], v139 offset:19456
	ds_read_b128 v[204:207], v139 offset:20480
	ds_read_b128 v[212:215], v139 offset:21504
	ds_read_b128 v[216:219], v139 offset:22528
	ds_read_b128 v[220:223], v139 offset:23552
	s_nop 0
	global_load_lds_dwordx4 v168, s[24:25]
	v_mov_b32_e32 v168, v130
	s_mov_b32 m0, s56
	s_nop 0
	global_load_lds_dwordx4 v168, s[24:25]
	s_barrier
	s_waitcnt lgkmcnt(0)
	s_setprio 1
	s_waitcnt lgkmcnt(0)
	v_mfma_f32_16x16x32_bf16 v[56:59], v[140:143], v[156:159], v[56:59]
	v_mfma_f32_16x16x32_bf16 v[48:51], v[148:151], v[156:159], v[48:51]
	v_mfma_f32_16x16x32_bf16 v[40:43], v[140:143], v[196:199], v[40:43]
	v_mfma_f32_16x16x32_bf16 v[32:35], v[148:151], v[196:199], v[32:35]
	v_mfma_f32_16x16x32_bf16 v[24:27], v[140:143], v[204:207], v[24:27]
	v_mfma_f32_16x16x32_bf16 v[16:19], v[148:151], v[204:207], v[16:19]
	v_mfma_f32_16x16x32_bf16 v[8:11], v[140:143], v[216:219], v[8:11]
	v_mfma_f32_16x16x32_bf16 v[0:3], v[148:151], v[216:219], v[0:3]
	v_mfma_f32_16x16x32_bf16 v[56:59], v[144:147], v[192:195], v[56:59]
	v_mfma_f32_16x16x32_bf16 v[48:51], v[152:155], v[192:195], v[48:51]
	v_mfma_f32_16x16x32_bf16 v[40:43], v[144:147], v[200:203], v[40:43]
	v_mfma_f32_16x16x32_bf16 v[32:35], v[152:155], v[200:203], v[32:35]
	v_mfma_f32_16x16x32_bf16 v[24:27], v[144:147], v[212:215], v[24:27]
	v_mfma_f32_16x16x32_bf16 v[16:19], v[152:155], v[212:215], v[16:19]
	v_mfma_f32_16x16x32_bf16 v[8:11], v[144:147], v[220:223], v[8:11]
	v_mfma_f32_16x16x32_bf16 v[0:3], v[152:155], v[220:223], v[0:3]
	s_setprio 0
	s_barrier
; #define PG8_STAGE(bufoff, gbase, voff) do { const char* _gb = (const char*)(gbase); asm volatile("" : "+s"(_gb)); _Pragma("unroll") for (int _i = 0; _i < 2; ++_i) { unsigned _vo = (voff)[_i]; asm volatile("" : "+v"(_vo)); \
;         __builtin_amdgcn_global_load_lds((const GAS unsigned*)(_gb + _vo), (LAS unsigned*)(lds + (bufoff) + ldsw + _i * 8192), 16, 0, 0); } } while (0)
; #define PG8_LDA(dst, b, h) do { _Pragma("unroll") for (int m = 0; m < 4; ++m) _Pragma("unroll") for (int k = 0; k < 2; ++k) dst[m][k] = *(const LAS bf16x8*)(lds + PG8_SA(b, h) + aoff + m * 2048 + k * 1024); } while (0)
; #define PG8_LDB(dst, b, h) do { _Pragma("unroll") for (int n = 0; n < 2; ++n) _Pragma("unroll") for (int k = 0; k < 2; ++k) dst[n][k] = *(const LAS bf16x8*)(lds + PG8_SB(b, h) + boff + n * 2048 + k * 1024); } while (0)
; #define PG8_MMA(ai, bj, At, Bt) do { __builtin_amdgcn_s_setprio(1); _Pragma("unroll") for (int m = 0; m < 4; ++m) _Pragma("unroll") for (int n = 0; n < 2; ++n) _Pragma("unroll") for (int k = 0; k < 2; ++k) \
;         acc[ai][bj][m][n] = __builtin_amdgcn_mfma_f32_16x16x32_bf16(Bt[n][k], At[m][k], acc[ai][bj][m][n], 0, 0, 0); __builtin_amdgcn_s_setprio(0); } while (0)
; #define PG8_WAIT_V(n) asm volatile("s_waitcnt vmcnt(" #n ")" ::: "memory")
; #define PG8_WAIT_L(n) asm volatile("s_waitcnt lgkmcnt(" #n ")" ::: "memory")
; #define PG8_BAR __builtin_amdgcn_s_barrier()
; #define PG8_SCHED __builtin_amdgcn_sched_barrier(0)
; template <class Epi, class Ord>
; __device__ __forceinline__ void gemm_phase(LAS unsigned char* lds, const Gemm g, const Ord& S, const Epi& E) {
;     ...
;             PG8_STAGE(PG8_SB(0, 1), b2 + hstep, voffB);
;             PG8_WAIT_V(6); PG8_BAR; PG8_MMA(1, 1, At, B1); PG8_BAR;
;             PG8_LDB(B0, 1, 0); PG8_SCHED; PG8_LDA(At, 1, 0); PG8_STAGE(PG8_SA(0, 1), a2 + hstep, voffA);
;             PG8_WAIT_L(8); PG8_BAR; PG8_WAIT_L(0); PG8_MMA(0, 0, At, B0); PG8_BAR; PG8_SCHED;
;             PG8_LDB(B1, 1, 1); PG8_STAGE(PG8_SB(1, 0), b3, voffB);
;             PG8_BAR; PG8_WAIT_L(0); PG8_MMA(0, 1, At, B1); PG8_BAR;
;             PG8_LDA(At, 1, 1); PG8_STAGE(PG8_SA(1, 0), a3, voffA);
	s_add_u32 s24, s20, s0
	s_addc_u32 s25, s21, s1
	s_mov_b64 s[76:77], s[24:25]
	v_mov_b32_e32 v140, v129
	s_add_i32 s75, s78, s52
	s_mov_b32 m0, s75
	s_nop 0
	global_load_lds_dwordx4 v140, s[76:77]
	v_mov_b32_e32 v140, v131
	s_add_i32 m0, s75, 0x2000
	s_nop 0
	global_load_lds_dwordx4 v140, s[76:77]
	s_waitcnt vmcnt(6)
	s_barrier
	s_setprio 1
	v_mfma_f32_16x16x32_bf16 v[60:63], v[224:227], v[156:159], v[60:63]
	v_mfma_f32_16x16x32_bf16 v[52:55], v[232:235], v[156:159], v[52:55]
	v_mfma_f32_16x16x32_bf16 v[44:47], v[224:227], v[196:199], v[44:47]
	v_mfma_f32_16x16x32_bf16 v[36:39], v[232:235], v[196:199], v[36:39]
	v_mfma_f32_16x16x32_bf16 v[28:31], v[224:227], v[204:207], v[28:31]
	v_mfma_f32_16x16x32_bf16 v[20:23], v[232:235], v[204:207], v[20:23]
	v_mfma_f32_16x16x32_bf16 v[12:15], v[224:227], v[216:219], v[12:15]
	v_mfma_f32_16x16x32_bf16 v[4:7], v[232:235], v[216:219], v[4:7]
	v_mfma_f32_16x16x32_bf16 v[60:63], v[228:231], v[192:195], v[60:63]
	v_mfma_f32_16x16x32_bf16 v[52:55], v[236:239], v[192:195], v[52:55]
	v_mfma_f32_16x16x32_bf16 v[44:47], v[228:231], v[200:203], v[44:47]
	v_mfma_f32_16x16x32_bf16 v[36:39], v[236:239], v[200:203], v[36:39]
	v_mfma_f32_16x16x32_bf16 v[28:31], v[228:231], v[212:215], v[28:31]
	v_mfma_f32_16x16x32_bf16 v[20:23], v[236:239], v[212:215], v[20:23]
	v_mfma_f32_16x16x32_bf16 v[12:15], v[228:231], v[220:223], v[12:15]
	v_mfma_f32_16x16x32_bf16 v[4:7], v[236:239], v[220:223], v[4:7]
	s_setprio 0
	s_add_i32 s75, 0, 0x18000
	v_add_u32_e32 v152, s75, v133
	s_barrier
	ds_read_b128 v[140:143], v152
	ds_read_b128 v[144:147], v152 offset:1024
	ds_read_b128 v[148:151], v152 offset:2048
	ds_read_b128 v[152:155], v152 offset:3072
	s_add_u32 s22, s22, s0
	s_addc_u32 s23, s23, s1
	v_mov_b32_e32 v168, v128
	s_mov_b32 m0, s57
	ds_read_b128 v[156:159], v139 offset:32768
	ds_read_b128 v[192:195], v139 offset:33792
	ds_read_b128 v[196:199], v139 offset:34816
	ds_read_b128 v[200:203], v139 offset:35840
	ds_read_b128 v[204:207], v139 offset:36864
	ds_read_b128 v[212:215], v139 offset:37888
	ds_read_b128 v[216:219], v139 offset:38912
	ds_read_b128 v[220:223], v139 offset:39936
	s_nop 0
	global_load_lds_dwordx4 v168, s[22:23]
	v_mov_b32_e32 v168, v130
	s_mov_b32 m0, s62
	s_nop 0
	global_load_lds_dwordx4 v168, s[22:23]
	s_waitcnt lgkmcnt(8)
	s_barrier
	s_waitcnt lgkmcnt(0)
	s_setprio 1
	s_waitcnt lgkmcnt(0)
	v_mfma_f32_16x16x32_bf16 v[120:123], v[140:143], v[156:159], v[120:123]
	v_mfma_f32_16x16x32_bf16 v[112:115], v[148:151], v[156:159], v[112:115]
	v_mfma_f32_16x16x32_bf16 v[104:107], v[140:143], v[196:199], v[104:107]
	v_mfma_f32_16x16x32_bf16 v[96:99], v[148:151], v[196:199], v[96:99]
	v_mfma_f32_16x16x32_bf16 v[88:91], v[140:143], v[204:207], v[88:91]
	v_mfma_f32_16x16x32_bf16 v[80:83], v[148:151], v[204:207], v[80:83]
	v_mfma_f32_16x16x32_bf16 v[72:75], v[140:143], v[216:219], v[72:75]
	v_mfma_f32_16x16x32_bf16 v[64:67], v[148:151], v[216:219], v[64:67]
	v_mfma_f32_16x16x32_bf16 v[120:123], v[144:147], v[192:195], v[120:123]
	v_mfma_f32_16x16x32_bf16 v[112:115], v[152:155], v[192:195], v[112:115]
	v_mfma_f32_16x16x32_bf16 v[104:107], v[144:147], v[200:203], v[104:107]
	v_mfma_f32_16x16x32_bf16 v[96:99], v[152:155], v[200:203], v[96:99]
	v_mfma_f32_16x16x32_bf16 v[88:91], v[144:147], v[212:215], v[88:91]
	v_mfma_f32_16x16x32_bf16 v[80:83], v[152:155], v[212:215], v[80:83]
	v_mfma_f32_16x16x32_bf16 v[72:75], v[144:147], v[220:223], v[72:75]
	v_mfma_f32_16x16x32_bf16 v[64:67], v[152:155], v[220:223], v[64:67]
	s_setprio 0
	s_barrier
	s_add_i32 s22, 0, 0x1c000
	v_add_u32_e32 v168, s22, v133
	s_add_u32 s20, s20, 0x80
	ds_read_b128 v[224:227], v168
	ds_read_b128 v[228:231], v168 offset:1024
	ds_read_b128 v[232:235], v168 offset:2048
	ds_read_b128 v[236:239], v168 offset:3072
	s_addc_u32 s21, s21, 0
	v_mov_b32_e32 v168, v129
	s_add_i32 s23, s75, s52
	s_mov_b32 m0, s23
	s_nop 0
	global_load_lds_dwordx4 v168, s[20:21]
	v_mov_b32_e32 v168, v131
	s_add_i32 m0, s23, 0x2000
	s_nop 0
	global_load_lds_dwordx4 v168, s[20:21]
	s_barrier
; #define PG8_STAGE(bufoff, gbase, voff) do { const char* _gb = (const char*)(gbase); asm volatile("" : "+s"(_gb)); _Pragma("unroll") for (int _i = 0; _i < 2; ++_i) { unsigned _vo = (voff)[_i]; asm volatile("" : "+v"(_vo)); \
;         __builtin_amdgcn_global_load_lds((const GAS unsigned*)(_gb + _vo), (LAS unsigned*)(lds + (bufoff) + ldsw + _i * 8192), 16, 0, 0); } } while (0)
; #define PG8_LDA(dst, b, h) do { _Pragma("unroll") for (int m = 0; m < 4; ++m) _Pragma("unroll") for (int k = 0; k < 2; ++k) dst[m][k] = *(const LAS bf16x8*)(lds + PG8_SA(b, h) + aoff + m * 2048 + k * 1024); } while (0)
; #define PG8_MMA(ai, bj, At, Bt) do { __builtin_amdgcn_s_setprio(1); _Pragma("unroll") for (int m = 0; m < 4; ++m) _Pragma("unroll") for (int n = 0; n < 2; ++n) _Pragma("unroll") for (int k = 0; k < 2; ++k) \
;         acc[ai][bj][m][n] = __builtin_amdgcn_mfma_f32_16x16x32_bf16(Bt[n][k], At[m][k], acc[ai][bj][m][n], 0, 0, 0); __builtin_amdgcn_s_setprio(0); } while (0)
; #define PG8_WAIT_V(n) asm volatile("s_waitcnt vmcnt(" #n ")" ::: "memory")
; #define PG8_WAIT_L(n) asm volatile("s_waitcnt lgkmcnt(" #n ")" ::: "memory")
; #define PG8_BAR __builtin_amdgcn_s_barrier()
; #define PG8_SCHED __builtin_amdgcn_sched_barrier(0)
; template <class Epi, class Ord>
; __device__ __forceinline__ void gemm_phase(LAS unsigned char* lds, const Gemm g, const Ord& S, const Epi& E) {
;     ...
;             const bool last = (t == nt - 2);
;             const char* a1 = cA + (size_t)(t + 1) * kstep;
;             const char* a2 = last ? nA : cA + (size_t)(t + 2) * kstep; const char* b2 = last ? nB : cB + (size_t)(t + 2) * kstep;
;             const char* a3 = a2 + kstep; const char* b3 = b2 + kstep;
;     ...
;             PG8_LDA(At, 1, 1); PG8_STAGE(PG8_SA(1, 0), a3, voffA);
;             PG8_BAR; PG8_WAIT_L(0); PG8_MMA(1, 0, At, B0); PG8_BAR; PG8_SCHED;
;             PG8_STAGE(PG8_SB(1, 1), b3 + hstep, voffB);
;             PG8_WAIT_V(6); PG8_BAR; PG8_MMA(1, 1, At, B1); PG8_BAR;
	s_waitcnt lgkmcnt(0)
	s_setprio 1
	s_waitcnt lgkmcnt(0)
	v_mfma_f32_16x16x32_bf16 v[124:127], v[224:227], v[156:159], v[124:127]
	v_mfma_f32_16x16x32_bf16 v[116:119], v[232:235], v[156:159], v[116:119]
	v_mfma_f32_16x16x32_bf16 v[108:111], v[224:227], v[196:199], v[108:111]
	v_mfma_f32_16x16x32_bf16 v[100:103], v[232:235], v[196:199], v[100:103]
	v_mfma_f32_16x16x32_bf16 v[92:95], v[224:227], v[204:207], v[92:95]
	v_mfma_f32_16x16x32_bf16 v[84:87], v[232:235], v[204:207], v[84:87]
	v_mfma_f32_16x16x32_bf16 v[76:79], v[224:227], v[216:219], v[76:79]
	v_mfma_f32_16x16x32_bf16 v[68:71], v[232:235], v[216:219], v[68:71]
	v_mfma_f32_16x16x32_bf16 v[124:127], v[228:231], v[192:195], v[124:127]
	v_mfma_f32_16x16x32_bf16 v[116:119], v[236:239], v[192:195], v[116:119]
	v_mfma_f32_16x16x32_bf16 v[108:111], v[228:231], v[200:203], v[108:111]
	v_mfma_f32_16x16x32_bf16 v[100:103], v[236:239], v[200:203], v[100:103]
	v_mfma_f32_16x16x32_bf16 v[92:95], v[228:231], v[212:215], v[92:95]
	v_mfma_f32_16x16x32_bf16 v[84:87], v[236:239], v[212:215], v[84:87]
	v_mfma_f32_16x16x32_bf16 v[76:79], v[228:231], v[220:223], v[76:79]
	v_mfma_f32_16x16x32_bf16 v[68:71], v[236:239], v[220:223], v[68:71]
	s_setprio 0
	v_mov_b32_e32 v168, v128
	s_mov_b32 m0, s65
	s_barrier
	ds_read_b128 v[156:159], v139 offset:49152
	ds_read_b128 v[192:195], v139 offset:50176
	ds_read_b128 v[196:199], v139 offset:51200
	ds_read_b128 v[200:203], v139 offset:52224
	ds_read_b128 v[204:207], v139 offset:53248
	ds_read_b128 v[212:215], v139 offset:54272
	ds_read_b128 v[216:219], v139 offset:55296
	ds_read_b128 v[220:223], v139 offset:56320
	s_nop 0
	global_load_lds_dwordx4 v168, s[12:13]
	v_mov_b32_e32 v168, v130
	s_mov_b32 m0, s66
	s_nop 0
	global_load_lds_dwordx4 v168, s[12:13]
	s_barrier
	s_waitcnt lgkmcnt(0)
	s_setprio 1
	s_waitcnt lgkmcnt(0)
	v_mfma_f32_16x16x32_bf16 v[56:59], v[140:143], v[156:159], v[56:59]
	v_mfma_f32_16x16x32_bf16 v[48:51], v[148:151], v[156:159], v[48:51]
	v_mfma_f32_16x16x32_bf16 v[40:43], v[140:143], v[196:199], v[40:43]
	v_mfma_f32_16x16x32_bf16 v[32:35], v[148:151], v[196:199], v[32:35]
	v_mfma_f32_16x16x32_bf16 v[24:27], v[140:143], v[204:207], v[24:27]
	v_mfma_f32_16x16x32_bf16 v[16:19], v[148:151], v[204:207], v[16:19]
	v_mfma_f32_16x16x32_bf16 v[8:11], v[140:143], v[216:219], v[8:11]
	v_mfma_f32_16x16x32_bf16 v[0:3], v[148:151], v[216:219], v[0:3]
	v_mfma_f32_16x16x32_bf16 v[56:59], v[144:147], v[192:195], v[56:59]
	v_mfma_f32_16x16x32_bf16 v[48:51], v[152:155], v[192:195], v[48:51]
	v_mfma_f32_16x16x32_bf16 v[40:43], v[144:147], v[200:203], v[40:43]
	v_mfma_f32_16x16x32_bf16 v[32:35], v[152:155], v[200:203], v[32:35]
	v_mfma_f32_16x16x32_bf16 v[24:27], v[144:147], v[212:215], v[24:27]
	v_mfma_f32_16x16x32_bf16 v[16:19], v[152:155], v[212:215], v[16:19]
	v_mfma_f32_16x16x32_bf16 v[8:11], v[144:147], v[220:223], v[8:11]
	v_mfma_f32_16x16x32_bf16 v[0:3], v[152:155], v[220:223], v[0:3]
	s_setprio 0
	s_barrier
	s_add_u32 s12, s24, 0x80
	s_addc_u32 s13, s25, 0
	v_mov_b32_e32 v140, v129
	s_add_i32 s20, s22, s52
	s_mov_b32 m0, s20
	s_nop 0
	global_load_lds_dwordx4 v140, s[12:13]
	v_mov_b32_e32 v140, v131
	s_add_i32 m0, s20, 0x2000
	s_nop 0
	global_load_lds_dwordx4 v140, s[12:13]
	s_waitcnt vmcnt(6)
	s_barrier
	s_setprio 1
	v_mfma_f32_16x16x32_bf16 v[60:63], v[224:227], v[156:159], v[60:63]
	v_mfma_f32_16x16x32_bf16 v[52:55], v[232:235], v[156:159], v[52:55]
	v_mfma_f32_16x16x32_bf16 v[44:47], v[224:227], v[196:199], v[44:47]
	v_mfma_f32_16x16x32_bf16 v[36:39], v[232:235], v[196:199], v[36:39]
	v_mfma_f32_16x16x32_bf16 v[28:31], v[224:227], v[204:207], v[28:31]
	v_mfma_f32_16x16x32_bf16 v[20:23], v[232:235], v[204:207], v[20:23]
	v_mfma_f32_16x16x32_bf16 v[12:15], v[224:227], v[216:219], v[12:15]
	v_mfma_f32_16x16x32_bf16 v[4:7], v[232:235], v[216:219], v[4:7]
	v_mfma_f32_16x16x32_bf16 v[60:63], v[228:231], v[192:195], v[60:63]
	v_mfma_f32_16x16x32_bf16 v[52:55], v[236:239], v[192:195], v[52:55]
	v_mfma_f32_16x16x32_bf16 v[44:47], v[228:231], v[200:203], v[44:47]
	v_mfma_f32_16x16x32_bf16 v[36:39], v[236:239], v[200:203], v[36:39]
	v_mfma_f32_16x16x32_bf16 v[28:31], v[228:231], v[212:215], v[28:31]
	v_mfma_f32_16x16x32_bf16 v[20:23], v[236:239], v[212:215], v[20:23]
	v_mfma_f32_16x16x32_bf16 v[12:15], v[228:231], v[220:223], v[12:15]
	v_mfma_f32_16x16x32_bf16 v[4:7], v[236:239], v[220:223], v[4:7]
	s_setprio 0
	s_add_u32 s44, s44, 0x100
	s_addc_u32 s45, s45, 0
	s_add_u32 s46, s46, 0x100
	s_addc_u32 s47, s47, 0
	s_mov_b32 s12, s74
	s_add_i32 s74, s12, 2
	s_cmp_eq_u32 s67, s12
	s_cselect_b32 s22, s38, s46
	s_cselect_b32 s23, s39, s47
	s_cselect_b32 s20, s42, s44
	s_cselect_b32 s21, s43, s45
	s_add_u32 s12, s22, 0x80
	s_addc_u32 s13, s23, 0
	s_add_i32 s75, 0, 0x10000
	v_add_u32_e32 v152, s75, v133
	s_sub_i32 s98, s74, 2
	s_cmp_ge_i32 s98, s64
	s_barrier
	s_cbranch_scc0 .LBB0_613
	s_branch .LBB0_603

; __global__ void __launch_bounds__(NTHREADS, 2) mega_fwd(Params P) {
;     extern __shared__ __attribute__((aligned(16))) unsigned char lds_raw[];
	.amdhsa_kernel _Z8mega_fwd6Params
		.amdhsa_group_segment_fixed_size 0
		.amdhsa_private_segment_fixed_size 0
		.amdhsa_kernarg_size 480
		.amdhsa_user_sgpr_count 2
		.amdhsa_user_sgpr_dispatch_ptr 0
		.amdhsa_user_sgpr_queue_ptr 0
		.amdhsa_user_sgpr_kernarg_segment_ptr 1
		.amdhsa_user_sgpr_dispatch_id 0
		.amdhsa_user_sgpr_kernarg_preload_length 0
		.amdhsa_user_sgpr_kernarg_preload_offset 0
		.amdhsa_user_sgpr_private_segment_size 0
		.amdhsa_uses_dynamic_stack 0
		.amdhsa_enable_private_segment 0
		.amdhsa_system_sgpr_workgroup_id_x 1
		.amdhsa_system_sgpr_workgroup_id_y 0
		.amdhsa_system_sgpr_workgroup_id_z 0
		.amdhsa_system_sgpr_workgroup_info 0
		.amdhsa_system_vgpr_workitem_id 2
		.amdhsa_next_free_vgpr 254
		.amdhsa_next_free_sgpr 100
		.amdhsa_accum_offset 256
		.amdhsa_reserve_vcc 1
		.amdhsa_float_round_mode_32 0
		.amdhsa_float_round_mode_16_64 0
		.amdhsa_float_denorm_mode_32 3
		.amdhsa_float_denorm_mode_16_64 3
		.amdhsa_dx10_clamp 1
		.amdhsa_ieee_mode 1
		.amdhsa_fp16_overflow 0
		.amdhsa_tg_split 0
		.amdhsa_exception_fp_ieee_invalid_op 0
		.amdhsa_exception_fp_denorm_src 0
		.amdhsa_exception_fp_ieee_div_zero 0
		.amdhsa_exception_fp_ieee_overflow 0
		.amdhsa_exception_fp_ieee_underflow 0
		.amdhsa_exception_fp_ieee_inexact 0
		.amdhsa_exception_int_div_zero 0
	.end_amdhsa_kernel
